# GEMM k-loops: counted lgkmcnt waits (each MFMA group waits only for the LDS reads it consumes); convert_T gain load hoisted
# speedup vs baseline: 1.0384x; 1.0045x over previous
; DI bf16_t bf1(float a) { return (bf16_t)(pk2(a, 0.f) & 0xffffu); }
; DI void convert_T(const float* __restrict__ W, int K, int N, bf16_t* __restrict__ Wt, bool permute, const float* __restrict__ gain, char* lds, int tid) {
;     ...
;         for (int i = 0; i < 8; ++i) {
;             const int idx = tid + NTH * i, nr = idx >> 6, kc = idx & 63; const int n = n0 + nr; int nd = n;
;             if (permute) { if (n < 2816) nd = (n >> 5) * 64 + (n & 31); else { const int j = n - 2816; nd = (j >> 5) * 64 + 32 + (j & 31); } }
;             Wt[(long)nd * K + k0 + kc] = bf1(tile[kc * 65 + nr] * (gain ? gain[k0 + kc] : 1.0f));
;         }
;         __syncthreads();
;     }
.LBB0_9:
	v_add_u32_e32 v8, s8, v18
	s_waitcnt lgkmcnt(0)
	v_mul_f32_e32 v9, v36, v35
	v_cvt_pk_bf16_f32 v35, v9, s0
	v_ashrrev_i32_e32 v9, 31, v8
	v_lshlrev_b64 v[8:9], 11, v[8:9]
	s_add_i32 s35, s35, s28
	s_add_i32 s34, s34, s33
	v_lshl_add_u64 v[8:9], v[10:11], 0, v[8:9]
	s_cmpk_lt_i32 s35, 0x200
	global_store_short v[8:9], v35, off
	s_barrier
	s_cbranch_scc0 .LBB0_26

; DI bf16_t bf1(float a) { return (bf16_t)(pk2(a, 0.f) & 0xffffu); }
; DI void convert_T(const float* __restrict__ W, int K, int N, bf16_t* __restrict__ Wt, bool permute, const float* __restrict__ gain, char* lds, int tid) {
;     ...
;         for (int i = 0; i < 8; ++i) {
;             const int idx = tid + NTH * i, nr = idx >> 6, kc = idx & 63; const int n = n0 + nr; int nd = n;
;             if (permute) { if (n < 2816) nd = (n >> 5) * 64 + (n & 31); else { const int j = n - 2816; nd = (j >> 5) * 64 + 32 + (j & 31); } }
;             Wt[(long)nd * K + k0 + kc] = bf1(tile[kc * 65 + nr] * (gain ? gain[k0 + kc] : 1.0f));
;         }
.LBB0_12:
	s_sub_i32 s36, 0, s9
	s_ashr_i32 s9, s8, 31
	s_waitcnt vmcnt(0) lgkmcnt(0)
	v_mov_b32_e32 v80, v37
	v_mul_f32_e32 v36, v36, v37
	v_lshl_add_u64 v[10:11], s[8:9], 1, v[6:7]
	s_add_i32 s8, s36, s34
	v_cvt_pk_bf16_f32 v37, v36, s0
	ds_read_b32 v36, v20
	v_add_u32_e32 v38, s8, v2
	v_ashrrev_i32_e32 v39, 31, v38
	v_lshlrev_b64 v[38:39], 11, v[38:39]
	v_lshl_add_u64 v[38:39], v[10:11], 0, v[38:39]
	s_and_b64 vcc, exec, s[6:7]
	global_store_short v[38:39], v37, off
	s_cbranch_vccnz .LBB0_14
	v_mov_b32_e32 v35, v80
.LBB0_14:
	v_add_u32_e32 v38, s8, v12
	v_ashrrev_i32_e32 v39, 31, v38
	s_waitcnt lgkmcnt(0)
	v_mul_f32_e32 v35, v36, v35
	v_lshlrev_b64 v[36:37], 11, v[38:39]
	v_lshl_add_u64 v[38:39], v[10:11], 0, v[36:37]
	ds_read_b32 v36, v21
	v_cvt_pk_bf16_f32 v35, v35, s0
	global_store_short v[38:39], v35, off
	v_mov_b32_e32 v35, 1.0
	s_and_b64 vcc, exec, s[6:7]
	v_mov_b32_e32 v37, 1.0
	s_cbranch_vccnz .LBB0_16
	v_mov_b32_e32 v37, v80
.LBB0_16:
	s_waitcnt lgkmcnt(0)
	v_mul_f32_e32 v36, v36, v37
	v_cvt_pk_bf16_f32 v37, v36, s0
	ds_read_b32 v36, v22
	v_add_u32_e32 v38, s8, v13
	v_ashrrev_i32_e32 v39, 31, v38
	v_lshlrev_b64 v[38:39], 11, v[38:39]
	v_lshl_add_u64 v[38:39], v[10:11], 0, v[38:39]
	s_and_b64 vcc, exec, s[6:7]
	global_store_short v[38:39], v37, off
	s_cbranch_vccnz .LBB0_18
	v_mov_b32_e32 v35, v80
.LBB0_18:
	v_add_u32_e32 v38, s8, v14
	v_ashrrev_i32_e32 v39, 31, v38
	s_waitcnt lgkmcnt(0)
	v_mul_f32_e32 v35, v36, v35
	v_lshlrev_b64 v[36:37], 11, v[38:39]
	v_lshl_add_u64 v[38:39], v[10:11], 0, v[36:37]
	ds_read_b32 v36, v23
	v_cvt_pk_bf16_f32 v35, v35, s0
	global_store_short v[38:39], v35, off
	v_mov_b32_e32 v35, 1.0
	s_and_b64 vcc, exec, s[6:7]
	v_mov_b32_e32 v37, 1.0
	s_cbranch_vccnz .LBB0_20
	v_mov_b32_e32 v37, v80
.LBB0_20:
	s_waitcnt lgkmcnt(0)
	v_mul_f32_e32 v36, v36, v37
	v_cvt_pk_bf16_f32 v37, v36, s0
	ds_read_b32 v36, v24
	v_add_u32_e32 v38, s8, v15
	v_ashrrev_i32_e32 v39, 31, v38
	v_lshlrev_b64 v[38:39], 11, v[38:39]
	v_lshl_add_u64 v[38:39], v[10:11], 0, v[38:39]
	s_and_b64 vcc, exec, s[6:7]
	global_store_short v[38:39], v37, off
	s_cbranch_vccnz .LBB0_22
	v_mov_b32_e32 v35, v80
.LBB0_22:
	v_add_u32_e32 v38, s8, v16
	v_ashrrev_i32_e32 v39, 31, v38
	s_waitcnt lgkmcnt(0)
	v_mul_f32_e32 v35, v36, v35
	v_lshlrev_b64 v[36:37], 11, v[38:39]
	v_lshl_add_u64 v[38:39], v[10:11], 0, v[36:37]
	ds_read_b32 v36, v25
	v_cvt_pk_bf16_f32 v35, v35, s0
	global_store_short v[38:39], v35, off
	v_mov_b32_e32 v35, 1.0
	s_and_b64 vcc, exec, s[6:7]
	v_mov_b32_e32 v37, 1.0
	s_cbranch_vccnz .LBB0_24
	v_mov_b32_e32 v37, v80
.LBB0_24:
	s_waitcnt lgkmcnt(0)
	v_mul_f32_e32 v36, v36, v37
	v_cvt_pk_bf16_f32 v37, v36, s0
	ds_read_b32 v36, v26
	v_add_u32_e32 v38, s8, v17
	v_ashrrev_i32_e32 v39, 31, v38
	v_lshlrev_b64 v[38:39], 11, v[38:39]
	v_lshl_add_u64 v[38:39], v[10:11], 0, v[38:39]
	s_and_b64 vcc, exec, s[6:7]
	global_store_short v[38:39], v37, off
	s_cbranch_vccnz .LBB0_9
	v_mov_b32_e32 v35, v80
	s_branch .LBB0_9

; DI bf16_t bf1(float a) { return (bf16_t)(pk2(a, 0.f) & 0xffffu); }
; DI void convert_T(const float* __restrict__ W, int K, int N, bf16_t* __restrict__ Wt, bool permute, const float* __restrict__ gain, char* lds, int tid) {
;     ...
;         for (int i = 0; i < 8; ++i) {
;             const int idx = tid + NTH * i, nr = idx >> 6, kc = idx & 63; const int n = n0 + nr; int nd = n;
;             if (permute) { if (n < 2816) nd = (n >> 5) * 64 + (n & 31); else { const int j = n - 2816; nd = (j >> 5) * 64 + 32 + (j & 31); } }
;             Wt[(long)nd * K + k0 + kc] = bf1(tile[kc * 65 + nr] * (gain ? gain[k0 + kc] : 1.0f));
;         }
;         __syncthreads();
;     }
.LBB0_39:
	s_or_b64 exec, exec, s[20:21]
	ds_read_b32 v13, v36
	s_and_b64 vcc, exec, s[6:7]
	s_cbranch_vccnz .LBB0_48
	v_mov_b32_e32 v10, v80
.LBB0_41:
	s_waitcnt lgkmcnt(0)
	v_mul_f32_e32 v10, v13, v10
	v_ashrrev_i32_e32 v13, 31, v12
	v_cvt_pk_bf16_f32 v61, v10, s0
	v_lshlrev_b64 v[10:11], 11, v[12:13]
	s_add_i32 s46, s46, s28
	s_add_i32 s45, s45, s36
	s_add_i32 s16, s16, s33
	v_lshl_add_u64 v[8:9], v[8:9], 0, v[10:11]
	s_cmpk_lt_i32 s46, 0x580
	global_store_short v[8:9], v61, off
	s_barrier
	s_cbranch_scc0 .LBB0_96

; DI bf16_t bf1(float a) { return (bf16_t)(pk2(a, 0.f) & 0xffffu); }
; DI void convert_T(const float* __restrict__ W, int K, int N, bf16_t* __restrict__ Wt, bool permute, const float* __restrict__ gain, char* lds, int tid) {
;     ...
;         for (int i = 0; i < 8; ++i) {
;             const int idx = tid + NTH * i, nr = idx >> 6, kc = idx & 63; const int n = n0 + nr; int nd = n;
;             if (permute) { if (n < 2816) nd = (n >> 5) * 64 + (n & 31); else { const int j = n - 2816; nd = (j >> 5) * 64 + 32 + (j & 31); } }
;             Wt[(long)nd * K + k0 + kc] = bf1(tile[kc * 65 + nr] * (gain ? gain[k0 + kc] : 1.0f));
;         }
.LBB0_50:
	s_waitcnt vmcnt(0) lgkmcnt(0)
	v_mov_b32_e32 v80, v61
	v_mul_f32_e32 v13, v13, v61
	s_ashr_i32 s23, s22, 31
	v_cvt_pk_bf16_f32 v61, v13, s0
	v_ashrrev_i32_e32 v13, 31, v12
	v_lshl_add_u64 v[8:9], s[22:23], 1, v[6:7]
	v_lshlrev_b64 v[12:13], 11, v[12:13]
	v_lshl_add_u64 v[12:13], v[8:9], 0, v[12:13]
	global_store_short v[12:13], v61, off
	v_add_u32_e32 v12, s20, v14
	v_cmp_lt_i32_e32 vcc, s38, v12
	v_add_u32_e32 v13, s21, v51
	s_and_saveexec_b64 s[22:23], vcc
	s_xor_b64 s[22:23], exec, s[22:23]
	s_cbranch_execz .LBB0_54
	v_add_u32_e32 v12, 0x7fffea00, v13
	v_and_or_b32 v12, v12, s39, v38
	s_andn2_saveexec_b64 s[22:23], s[22:23]
	s_cbranch_execnz .LBB0_55

; DI bf16_t bf1(float a) { return (bf16_t)(pk2(a, 0.f) & 0xffffu); }
; DI void convert_T(const float* __restrict__ W, int K, int N, bf16_t* __restrict__ Wt, bool permute, const float* __restrict__ gain, char* lds, int tid) {
;     ...
;             Wt[(long)nd * K + k0 + kc] = bf1(tile[kc * 65 + nr] * (gain ? gain[k0 + kc] : 1.0f));
.LBB0_53:
	v_mov_b32_e32 v61, v80
	s_branch .LBB0_57

; DI bf16_t bf1(float a) { return (bf16_t)(pk2(a, 0.f) & 0xffffu); }
; DI void convert_T(const float* __restrict__ W, int K, int N, bf16_t* __restrict__ Wt, bool permute, const float* __restrict__ gain, char* lds, int tid) {
;     ...
;             const int idx = tid + NTH * i, nr = idx >> 6, kc = idx & 63; const int n = n0 + nr; int nd = n;
;             if (permute) { if (n < 2816) nd = (n >> 5) * 64 + (n & 31); else { const int j = n - 2816; nd = (j >> 5) * 64 + 32 + (j & 31); } }
;             Wt[(long)nd * K + k0 + kc] = bf1(tile[kc * 65 + nr] * (gain ? gain[k0 + kc] : 1.0f));
.LBB0_57:
	s_waitcnt lgkmcnt(0)
	v_mul_f32_e32 v13, v13, v61
	v_cvt_pk_bf16_f32 v61, v13, s0
	v_ashrrev_i32_e32 v13, 31, v12
	v_lshlrev_b64 v[12:13], 11, v[12:13]
	v_lshl_add_u64 v[12:13], v[8:9], 0, v[12:13]
	global_store_short v[12:13], v61, off
	v_add_u32_e32 v12, s20, v15
	v_cmp_lt_i32_e32 vcc, s38, v12
	v_add_u32_e32 v13, s21, v50
	s_and_saveexec_b64 s[22:23], vcc
	s_xor_b64 s[22:23], exec, s[22:23]
	s_cbranch_execz .LBB0_61
	v_add_u32_e32 v12, 0x7fffea00, v13
	v_and_or_b32 v12, v12, s39, v39
	s_andn2_saveexec_b64 s[22:23], s[22:23]
	s_cbranch_execnz .LBB0_62

; DI bf16_t bf1(float a) { return (bf16_t)(pk2(a, 0.f) & 0xffffu); }
; DI void convert_T(const float* __restrict__ W, int K, int N, bf16_t* __restrict__ Wt, bool permute, const float* __restrict__ gain, char* lds, int tid) {
;     ...
;             const int idx = tid + NTH * i, nr = idx >> 6, kc = idx & 63; const int n = n0 + nr; int nd = n;
;             if (permute) { if (n < 2816) nd = (n >> 5) * 64 + (n & 31); else { const int j = n - 2816; nd = (j >> 5) * 64 + 32 + (j & 31); } }
;             Wt[(long)nd * K + k0 + kc] = bf1(tile[kc * 65 + nr] * (gain ? gain[k0 + kc] : 1.0f));
.LBB0_64:
	s_waitcnt lgkmcnt(0)
	v_mul_f32_e32 v13, v13, v61
	v_cvt_pk_bf16_f32 v61, v13, s0
	v_ashrrev_i32_e32 v13, 31, v12
	v_lshlrev_b64 v[12:13], 11, v[12:13]
	v_lshl_add_u64 v[12:13], v[8:9], 0, v[12:13]
	global_store_short v[12:13], v61, off
	v_add_u32_e32 v12, s20, v16
	v_cmp_lt_i32_e32 vcc, s38, v12
	v_add_u32_e32 v13, s21, v49
	s_and_saveexec_b64 s[22:23], vcc
	s_xor_b64 s[22:23], exec, s[22:23]
	s_cbranch_execz .LBB0_68
	v_add_u32_e32 v12, 0x7fffea00, v13
	v_and_or_b32 v12, v12, s39, v40
	s_andn2_saveexec_b64 s[22:23], s[22:23]
	s_cbranch_execnz .LBB0_69

; DI bf16_t bf1(float a) { return (bf16_t)(pk2(a, 0.f) & 0xffffu); }
; DI void convert_T(const float* __restrict__ W, int K, int N, bf16_t* __restrict__ Wt, bool permute, const float* __restrict__ gain, char* lds, int tid) {
;     ...
;             const int idx = tid + NTH * i, nr = idx >> 6, kc = idx & 63; const int n = n0 + nr; int nd = n;
;             if (permute) { if (n < 2816) nd = (n >> 5) * 64 + (n & 31); else { const int j = n - 2816; nd = (j >> 5) * 64 + 32 + (j & 31); } }
;             Wt[(long)nd * K + k0 + kc] = bf1(tile[kc * 65 + nr] * (gain ? gain[k0 + kc] : 1.0f));
.LBB0_71:
	s_waitcnt lgkmcnt(0)
	v_mul_f32_e32 v13, v13, v61
	v_cvt_pk_bf16_f32 v61, v13, s0
	v_ashrrev_i32_e32 v13, 31, v12
	v_lshlrev_b64 v[12:13], 11, v[12:13]
	v_lshl_add_u64 v[12:13], v[8:9], 0, v[12:13]
	global_store_short v[12:13], v61, off
	v_add_u32_e32 v12, s20, v17
	v_cmp_lt_i32_e32 vcc, s38, v12
	v_add_u32_e32 v13, s21, v48
	s_and_saveexec_b64 s[22:23], vcc
	s_xor_b64 s[22:23], exec, s[22:23]
	s_cbranch_execz .LBB0_75
	v_add_u32_e32 v12, 0x7fffea00, v13
	v_and_or_b32 v12, v12, s39, v41
	s_andn2_saveexec_b64 s[22:23], s[22:23]
	s_cbranch_execnz .LBB0_76

; DI bf16_t bf1(float a) { return (bf16_t)(pk2(a, 0.f) & 0xffffu); }
; DI void convert_T(const float* __restrict__ W, int K, int N, bf16_t* __restrict__ Wt, bool permute, const float* __restrict__ gain, char* lds, int tid) {
;     ...
;             const int idx = tid + NTH * i, nr = idx >> 6, kc = idx & 63; const int n = n0 + nr; int nd = n;
;             if (permute) { if (n < 2816) nd = (n >> 5) * 64 + (n & 31); else { const int j = n - 2816; nd = (j >> 5) * 64 + 32 + (j & 31); } }
;             Wt[(long)nd * K + k0 + kc] = bf1(tile[kc * 65 + nr] * (gain ? gain[k0 + kc] : 1.0f));
.LBB0_78:
	s_waitcnt lgkmcnt(0)
	v_mul_f32_e32 v13, v13, v61
	v_cvt_pk_bf16_f32 v61, v13, s0
	v_ashrrev_i32_e32 v13, 31, v12
	v_lshlrev_b64 v[12:13], 11, v[12:13]
	v_lshl_add_u64 v[12:13], v[8:9], 0, v[12:13]
	global_store_short v[12:13], v61, off
	v_add_u32_e32 v12, s20, v18
	v_cmp_lt_i32_e32 vcc, s38, v12
	v_add_u32_e32 v13, s21, v47
	s_and_saveexec_b64 s[22:23], vcc
	s_xor_b64 s[22:23], exec, s[22:23]
	s_cbranch_execz .LBB0_82
	v_add_u32_e32 v12, 0x7fffea00, v13
	v_and_or_b32 v12, v12, s39, v42
	s_andn2_saveexec_b64 s[22:23], s[22:23]
	s_cbranch_execnz .LBB0_83

; DI bf16_t bf1(float a) { return (bf16_t)(pk2(a, 0.f) & 0xffffu); }
; DI void convert_T(const float* __restrict__ W, int K, int N, bf16_t* __restrict__ Wt, bool permute, const float* __restrict__ gain, char* lds, int tid) {
;     ...
;             const int idx = tid + NTH * i, nr = idx >> 6, kc = idx & 63; const int n = n0 + nr; int nd = n;
;             if (permute) { if (n < 2816) nd = (n >> 5) * 64 + (n & 31); else { const int j = n - 2816; nd = (j >> 5) * 64 + 32 + (j & 31); } }
;             Wt[(long)nd * K + k0 + kc] = bf1(tile[kc * 65 + nr] * (gain ? gain[k0 + kc] : 1.0f));
.LBB0_85:
	s_waitcnt lgkmcnt(0)
	v_mul_f32_e32 v13, v13, v61
	v_cvt_pk_bf16_f32 v61, v13, s0
	v_ashrrev_i32_e32 v13, 31, v12
	v_lshlrev_b64 v[12:13], 11, v[12:13]
	v_lshl_add_u64 v[12:13], v[8:9], 0, v[12:13]
	global_store_short v[12:13], v61, off
	v_add_u32_e32 v12, s20, v19
	v_cmp_lt_i32_e32 vcc, s38, v12
	v_add_u32_e32 v13, s21, v46
	s_and_saveexec_b64 s[22:23], vcc
	s_xor_b64 s[22:23], exec, s[22:23]
	s_cbranch_execz .LBB0_89
	v_add_u32_e32 v12, 0x7fffea00, v13
	v_and_or_b32 v12, v12, s39, v43
	s_andn2_saveexec_b64 s[22:23], s[22:23]
	s_cbranch_execnz .LBB0_90

; DI bf16_t bf1(float a) { return (bf16_t)(pk2(a, 0.f) & 0xffffu); }
; DI void convert_T(const float* __restrict__ W, int K, int N, bf16_t* __restrict__ Wt, bool permute, const float* __restrict__ gain, char* lds, int tid) {
;     ...
;             const int idx = tid + NTH * i, nr = idx >> 6, kc = idx & 63; const int n = n0 + nr; int nd = n;
;             if (permute) { if (n < 2816) nd = (n >> 5) * 64 + (n & 31); else { const int j = n - 2816; nd = (j >> 5) * 64 + 32 + (j & 31); } }
;             Wt[(long)nd * K + k0 + kc] = bf1(tile[kc * 65 + nr] * (gain ? gain[k0 + kc] : 1.0f));
.LBB0_92:
	s_waitcnt lgkmcnt(0)
	v_mul_f32_e32 v13, v13, v61
	v_cvt_pk_bf16_f32 v61, v13, s0
	v_ashrrev_i32_e32 v13, 31, v12
	v_lshlrev_b64 v[12:13], 11, v[12:13]
	v_lshl_add_u64 v[12:13], v[8:9], 0, v[12:13]
	global_store_short v[12:13], v61, off
	v_add_u32_e32 v12, s20, v20
	v_cmp_lt_i32_e32 vcc, s38, v12
	v_add_u32_e32 v13, s21, v45
	s_and_saveexec_b64 s[20:21], vcc
	s_xor_b64 s[20:21], exec, s[20:21]
	s_cbranch_execz .LBB0_94
	v_add_u32_e32 v12, 0x7fffea00, v13
	v_and_or_b32 v12, v12, s39, v44
	s_andn2_saveexec_b64 s[20:21], s[20:21]
	s_cbranch_execz .LBB0_39
	s_branch .LBB0_95

; #define MFMA16(a, b, c) __builtin_amdgcn_mfma_f32_16x16x32_bf16((a), (b), (c), 0, 0, 0)
; DI bf16x8 ldfrag(const char* lds, int row, int chunk) { return *(const bf16x8*)(lds + swz(row, chunk)); }
; template <bool RSTD, bool SWAP>
; DI void gemm_tile(gacc_t& acc, const bf16_t* __restrict__ A, int lda, const bf16_t* __restrict__ Bt, int ldb, int K,
;                   char* lds, int tid, int wr, int wc, int lane, const float* ssq_row) {
;     ...
;     for (int kt = 0; kt < nk; ++kt) {
;         const char* cur = lds + (kt & 1) * 65536;
;         if (kt + 1 < nk) GEMM_ISSUE(kt + 1, (kt + 1) & 1);
;         bf16x8 bfr[2][4], afr[3];
; #pragma unroll
;         for (int n = 0; n < 4; ++n) bfr[0][n] = ldfrag(cur + 32768, wc * 64 + n * 16 + fr, fq);
;         afr[0] = ldfrag(cur, wr * 128 + fr, fq);
;         afr[1] = ldfrag(cur, wr * 128 + 16 + fr, fq);
; #pragma unroll
;         for (int idx = 0; idx < 16; ++idx) {
;             const int ks = idx >> 3, m = idx & 7;
;             if (idx < 14) afr[(idx + 2) % 3] = ldfrag(cur, wr * 128 + ((idx + 2) & 7) * 16 + fr, ((idx + 2) >> 3) * 4 + fq);
;             if (ks == 0 && m >= 2 && m < 6) bfr[1][m - 2] = ldfrag(cur + 32768, wc * 64 + (m - 2) * 16 + fr, 4 + fq);
; #pragma unroll
;             for (int n = 0; n < 4; ++n) acc[m][n] = SWAP ? MFMA16(bfr[ks][n], afr[idx % 3], acc[m][n]) : MFMA16(afr[idx % 3], bfr[ks][n], acc[m][n]);
.LBB0_141:
	s_add_i32 s30, s21, 0xffff0000
	s_and_b32 s31, s21, 0x10000
	v_lshl_add_u64 v[164:165], v[136:137], 0, s[6:7]
	s_and_b32 s34, s30, 0x10000
	s_add_i32 s35, s19, s31
	s_mov_b64 s[30:31], 0xc80080
	v_lshl_add_u64 v[172:173], v[164:165], 0, s[30:31]
	s_mov_b64 s[30:31], 0xca0080
	v_lshl_add_u64 v[176:177], v[164:165], 0, s[30:31]
	s_mov_b64 s[30:31], 0xcc0080
	v_lshl_add_u64 v[162:163], v[138:139], 0, s[6:7]
	v_lshl_add_u64 v[180:181], v[164:165], 0, s[30:31]
	s_mov_b64 s[30:31], 0xce0080
	v_lshl_add_u64 v[166:167], v[162:163], 0, s[94:95]
	v_lshl_add_u64 v[164:165], v[164:165], 0, s[30:31]
	s_add_i32 s31, s35, 0x8000
	s_mov_b32 m0, s35
	v_lshl_add_u64 v[174:175], v[162:163], 0, s[96:97]
	global_load_lds_dwordx4 v[166:167], off
	v_mfma_f32_16x16x32_bf16 v[60:63], v[210:213], v[236:239], v[60:63]
	s_mov_b32 m0, s31
	v_lshl_add_u64 v[178:179], v[162:163], 0, s[80:81]
	global_load_lds_dwordx4 v[172:173], off
	v_mfma_f32_16x16x32_bf16 v[56:59], v[214:217], v[236:239], v[56:59]
	s_add_i32 m0, s35, 0x2000
	v_lshl_add_u64 v[162:163], v[162:163], 0, s[82:83]
	global_load_lds_dwordx4 v[174:175], off
	v_mfma_f32_16x16x32_bf16 v[52:55], v[218:221], v[236:239], v[52:55]
	s_add_i32 m0, s35, 0xa000
	s_add_i32 s30, s34, 0
	global_load_lds_dwordx4 v[176:177], off
	v_mfma_f32_16x16x32_bf16 v[48:51], v[222:225], v[236:239], v[48:51]
	s_add_i32 m0, s35, 0x4000
	v_add_u32_e32 v146, s30, v143
	global_load_lds_dwordx4 v[178:179], off
	v_mfma_f32_16x16x32_bf16 v[44:47], v[210:213], v[240:243], v[44:47]
	s_add_i32 m0, s35, 0xc000
	v_add3_u32 v161, v146, v149, v150
	global_load_lds_dwordx4 v[180:181], off
	v_mfma_f32_16x16x32_bf16 v[40:43], v[214:217], v[240:243], v[40:43]
	s_add_i32 m0, s35, 0x6000
	v_add_u32_e32 v166, v146, v145
	global_load_lds_dwordx4 v[162:163], off
	v_mfma_f32_16x16x32_bf16 v[36:39], v[218:221], v[240:243], v[36:39]
	s_add_i32 m0, s35, 0xe000
	s_nop 0
	global_load_lds_dwordx4 v[164:165], off
	v_mfma_f32_16x16x32_bf16 v[32:35], v[222:225], v[240:243], v[32:35]
	ds_read_b128 v[162:165], v161 offset:32768
	ds_read_b128 v[186:189], v161 offset:34816
	ds_read_b128 v[194:197], v161 offset:36864
	ds_read_b128 v[198:201], v161 offset:38912
	ds_read_b128 v[190:193], v166
	ds_read_b128 v[202:205], v166 offset:2048
	v_add_u32_e32 v161, v146, v151
	ds_read_b128 v[206:209], v166 offset:4096
	v_mfma_f32_16x16x32_bf16 v[28:31], v[210:213], v[244:247], v[28:31]
	v_mfma_f32_16x16x32_bf16 v[24:27], v[214:217], v[244:247], v[24:27]
	v_mfma_f32_16x16x32_bf16 v[20:23], v[218:221], v[244:247], v[20:23]
	v_mfma_f32_16x16x32_bf16 v[16:19], v[222:225], v[244:247], v[16:19]
	v_mfma_f32_16x16x32_bf16 v[12:15], v[210:213], v[248:251], v[12:15]
	v_mfma_f32_16x16x32_bf16 v[8:11], v[214:217], v[248:251], v[8:11]
	v_mfma_f32_16x16x32_bf16 v[4:7], v[218:221], v[248:251], v[4:7]
	v_mfma_f32_16x16x32_bf16 v[0:3], v[222:225], v[248:251], v[0:3]
	s_waitcnt lgkmcnt(2)
	v_mfma_f32_16x16x32_bf16 v[124:127], v[162:165], v[190:193], v[124:127]
	v_add_u32_e32 v146, v146, v153
	v_mfma_f32_16x16x32_bf16 v[120:123], v[186:189], v[190:193], v[120:123]
	v_mfma_f32_16x16x32_bf16 v[116:119], v[194:197], v[190:193], v[116:119]
	v_mfma_f32_16x16x32_bf16 v[112:115], v[198:201], v[190:193], v[112:115]
	ds_read_b128 v[190:193], v161
	v_add_u32_e32 v161, s30, v148
	v_add_u32_e32 v167, v161, v152
	s_waitcnt lgkmcnt(2)
	v_mfma_f32_16x16x32_bf16 v[108:111], v[162:165], v[202:205], v[108:111]
	v_mfma_f32_16x16x32_bf16 v[104:107], v[186:189], v[202:205], v[104:107]
	v_mfma_f32_16x16x32_bf16 v[100:103], v[194:197], v[202:205], v[100:103]
	v_mfma_f32_16x16x32_bf16 v[96:99], v[198:201], v[202:205], v[96:99]
	ds_read_b128 v[202:205], v166 offset:8192
	ds_read_b128 v[210:213], v167 offset:32768
	s_waitcnt lgkmcnt(3)
	v_mfma_f32_16x16x32_bf16 v[92:95], v[162:165], v[206:209], v[92:95]
	v_mfma_f32_16x16x32_bf16 v[88:91], v[186:189], v[206:209], v[88:91]
	v_mfma_f32_16x16x32_bf16 v[84:87], v[194:197], v[206:209], v[84:87]
	v_mfma_f32_16x16x32_bf16 v[80:83], v[198:201], v[206:209], v[80:83]
	ds_read_b128 v[206:209], v166 offset:10240
	ds_read_b128 v[214:217], v167 offset:34816
	s_waitcnt lgkmcnt(4)
	v_mfma_f32_16x16x32_bf16 v[76:79], v[162:165], v[190:193], v[76:79]
	v_mfma_f32_16x16x32_bf16 v[72:75], v[186:189], v[190:193], v[72:75]
	v_mfma_f32_16x16x32_bf16 v[68:71], v[194:197], v[190:193], v[68:71]
	v_mfma_f32_16x16x32_bf16 v[64:67], v[198:201], v[190:193], v[64:67]
	ds_read_b128 v[190:193], v166 offset:12288
	v_add_u32_e32 v166, v161, v154
	ds_read_b128 v[218:221], v167 offset:36864
	s_waitcnt lgkmcnt(5)
	v_mfma_f32_16x16x32_bf16 v[60:63], v[162:165], v[202:205], v[60:63]
	v_mfma_f32_16x16x32_bf16 v[56:59], v[186:189], v[202:205], v[56:59]
	v_mfma_f32_16x16x32_bf16 v[52:55], v[194:197], v[202:205], v[52:55]
	v_mfma_f32_16x16x32_bf16 v[48:51], v[198:201], v[202:205], v[48:51]
	ds_read_b128 v[222:225], v166 offset:38912
	ds_read_b128 v[202:205], v146
	v_add_u32_e32 v146, v161, v145
	s_waitcnt lgkmcnt(5)
	v_mfma_f32_16x16x32_bf16 v[44:47], v[162:165], v[206:209], v[44:47]
	v_add_u32_e32 v166, v161, v151
	v_mfma_f32_16x16x32_bf16 v[40:43], v[186:189], v[206:209], v[40:43]
	v_mfma_f32_16x16x32_bf16 v[36:39], v[194:197], v[206:209], v[36:39]
	v_mfma_f32_16x16x32_bf16 v[32:35], v[198:201], v[206:209], v[32:35]
	ds_read_b128 v[206:209], v146
	s_waitcnt lgkmcnt(4)
	v_mfma_f32_16x16x32_bf16 v[28:31], v[162:165], v[190:193], v[28:31]
	v_mfma_f32_16x16x32_bf16 v[24:27], v[186:189], v[190:193], v[24:27]
	v_mfma_f32_16x16x32_bf16 v[20:23], v[194:197], v[190:193], v[20:23]
	v_mfma_f32_16x16x32_bf16 v[16:19], v[198:201], v[190:193], v[16:19]
	ds_read_b128 v[190:193], v146 offset:2048
	s_waitcnt lgkmcnt(2)
; #define MFMA16(a, b, c) __builtin_amdgcn_mfma_f32_16x16x32_bf16((a), (b), (c), 0, 0, 0)
; DI bf16x8 ldfrag(const char* lds, int row, int chunk) { return *(const bf16x8*)(lds + swz(row, chunk)); }
; #define GEMM_SG1() do { __builtin_amdgcn_sched_group_barrier(0x100, 1, 0); __builtin_amdgcn_sched_group_barrier(0x008, 4, 0); } while (0)
; #define GEMM_SG2() do { __builtin_amdgcn_sched_group_barrier(0x100, 2, 0); __builtin_amdgcn_sched_group_barrier(0x008, 4, 0); } while (0)
; template <bool RSTD, bool SWAP>
; DI void gemm_tile(gacc_t& acc, const bf16_t* __restrict__ A, int lda, const bf16_t* __restrict__ Bt, int ldb, int K,
;                   char* lds, int tid, int wr, int wc, int lane, const float* ssq_row) {
;     ...
;     for (int kt = 0; kt < nk; ++kt) {
;         const char* cur = lds + (kt & 1) * 65536;
;         if (kt + 1 < nk) GEMM_ISSUE(kt + 1, (kt + 1) & 1);
;         bf16x8 bfr[2][4], afr[3];
; #pragma unroll
;         for (int n = 0; n < 4; ++n) bfr[0][n] = ldfrag(cur + 32768, wc * 64 + n * 16 + fr, fq);
;         afr[0] = ldfrag(cur, wr * 128 + fr, fq);
;         afr[1] = ldfrag(cur, wr * 128 + 16 + fr, fq);
; #pragma unroll
;         for (int idx = 0; idx < 16; ++idx) {
;             const int ks = idx >> 3, m = idx & 7;
;             if (idx < 14) afr[(idx + 2) % 3] = ldfrag(cur, wr * 128 + ((idx + 2) & 7) * 16 + fr, ((idx + 2) >> 3) * 4 + fq);
;             if (ks == 0 && m >= 2 && m < 6) bfr[1][m - 2] = ldfrag(cur + 32768, wc * 64 + (m - 2) * 16 + fr, 4 + fq);
; #pragma unroll
;             for (int n = 0; n < 4; ++n) acc[m][n] = SWAP ? MFMA16(bfr[ks][n], afr[idx % 3], acc[m][n]) : MFMA16(afr[idx % 3], bfr[ks][n], acc[m][n]);
;         }
;         __builtin_amdgcn_sched_group_barrier(0x100, 6, 0);
;     ...
;         GEMM_SG1(); GEMM_SG1(); GEMM_SG2(); GEMM_SG2(); GEMM_SG2(); GEMM_SG2(); GEMM_SG1(); GEMM_SG1();
;         GEMM_SG1(); GEMM_SG1(); GEMM_SG1(); GEMM_SG1(); GEMM_SG1(); GEMM_SG1();
;         __builtin_amdgcn_sched_group_barrier(0x008, 8, 0);
;         __builtin_amdgcn_sched_barrier(0);
;         asm volatile("s_waitcnt vmcnt(0)" ::: "memory");
;         __syncthreads();
	v_mfma_f32_16x16x32_bf16 v[12:15], v[162:165], v[202:205], v[12:15]
	v_mfma_f32_16x16x32_bf16 v[8:11], v[186:189], v[202:205], v[8:11]
	v_mfma_f32_16x16x32_bf16 v[4:7], v[194:197], v[202:205], v[4:7]
	v_mfma_f32_16x16x32_bf16 v[0:3], v[198:201], v[202:205], v[0:3]
	ds_read_b128 v[162:165], v146 offset:4096
	s_waitcnt lgkmcnt(2)
	v_mfma_f32_16x16x32_bf16 v[124:127], v[210:213], v[206:209], v[124:127]
	v_mfma_f32_16x16x32_bf16 v[120:123], v[214:217], v[206:209], v[120:123]
	v_mfma_f32_16x16x32_bf16 v[116:119], v[218:221], v[206:209], v[116:119]
	v_mfma_f32_16x16x32_bf16 v[112:115], v[222:225], v[206:209], v[112:115]
	ds_read_b128 v[186:189], v166
	s_waitcnt lgkmcnt(2)
	v_mfma_f32_16x16x32_bf16 v[108:111], v[210:213], v[190:193], v[108:111]
	v_mfma_f32_16x16x32_bf16 v[104:107], v[214:217], v[190:193], v[104:107]
	v_mfma_f32_16x16x32_bf16 v[100:103], v[218:221], v[190:193], v[100:103]
	v_mfma_f32_16x16x32_bf16 v[96:99], v[222:225], v[190:193], v[96:99]
	ds_read_b128 v[236:239], v146 offset:8192
	s_waitcnt lgkmcnt(2)
	v_mfma_f32_16x16x32_bf16 v[92:95], v[210:213], v[162:165], v[92:95]
	v_mfma_f32_16x16x32_bf16 v[88:91], v[214:217], v[162:165], v[88:91]
	v_mfma_f32_16x16x32_bf16 v[84:87], v[218:221], v[162:165], v[84:87]
	v_mfma_f32_16x16x32_bf16 v[80:83], v[222:225], v[162:165], v[80:83]
	ds_read_b128 v[240:243], v146 offset:10240
	ds_read_b128 v[244:247], v146 offset:12288
	v_add_u32_e32 v146, v161, v153
	ds_read_b128 v[248:251], v146
	s_waitcnt lgkmcnt(4)
	v_mfma_f32_16x16x32_bf16 v[76:79], v[210:213], v[186:189], v[76:79]
	v_mfma_f32_16x16x32_bf16 v[72:75], v[214:217], v[186:189], v[72:75]
	v_mfma_f32_16x16x32_bf16 v[68:71], v[218:221], v[186:189], v[68:71]
	v_mfma_f32_16x16x32_bf16 v[64:67], v[222:225], v[186:189], v[64:67]
	s_waitcnt lgkmcnt(0)
	s_waitcnt vmcnt(0)
	s_add_u32 s6, s6, 0x80
	s_addc_u32 s7, s7, 0
	s_add_i32 s21, s21, 0x10000
	s_cmpk_lg_i32 s6, 0x780
	s_waitcnt vmcnt(0)
	s_barrier
	s_cbranch_scc1 .LBB0_141
	v_mfma_f32_16x16x32_bf16 v[60:63], v[210:213], v[236:239], v[60:63]
	v_mfma_f32_16x16x32_bf16 v[56:59], v[214:217], v[236:239], v[56:59]
	v_mfma_f32_16x16x32_bf16 v[52:55], v[218:221], v[236:239], v[52:55]
	v_mfma_f32_16x16x32_bf16 v[48:51], v[222:225], v[236:239], v[48:51]
	v_mfma_f32_16x16x32_bf16 v[44:47], v[210:213], v[240:243], v[44:47]
	v_mfma_f32_16x16x32_bf16 v[40:43], v[214:217], v[240:243], v[40:43]
	v_mfma_f32_16x16x32_bf16 v[36:39], v[218:221], v[240:243], v[36:39]
	v_mfma_f32_16x16x32_bf16 v[32:35], v[222:225], v[240:243], v[32:35]
	v_mfma_f32_16x16x32_bf16 v[28:31], v[210:213], v[244:247], v[28:31]
	v_mfma_f32_16x16x32_bf16 v[24:27], v[214:217], v[244:247], v[24:27]
	v_mfma_f32_16x16x32_bf16 v[20:23], v[218:221], v[244:247], v[20:23]
	v_mfma_f32_16x16x32_bf16 v[16:19], v[222:225], v[244:247], v[16:19]
	v_mfma_f32_16x16x32_bf16 v[12:15], v[210:213], v[248:251], v[12:15]
	v_mfma_f32_16x16x32_bf16 v[8:11], v[214:217], v[248:251], v[8:11]
	v_mfma_f32_16x16x32_bf16 v[4:7], v[218:221], v[248:251], v[4:7]
	v_mfma_f32_16x16x32_bf16 v[0:3], v[222:225], v[248:251], v[0:3]
	ds_read_b128 v[136:139], v160
	ds_read_b128 v[162:165], v160 offset:2048
	ds_read_b128 v[190:193], v160 offset:4096
	ds_read_b128 v[194:197], v160 offset:6144
	v_add_u32_e32 v146, v155, v145
	ds_read_b128 v[186:189], v146
	ds_read_b128 v[198:201], v146 offset:2048
	ds_read_b128 v[202:205], v146 offset:4096
	s_waitcnt lgkmcnt(2)
	v_mfma_f32_16x16x32_bf16 v[124:127], v[136:139], v[186:189], v[124:127]
	v_mfma_f32_16x16x32_bf16 v[206:209], v[162:165], v[186:189], v[120:123]
	v_mfma_f32_16x16x32_bf16 v[116:119], v[190:193], v[186:189], v[116:119]
	v_mfma_f32_16x16x32_bf16 v[186:189], v[194:197], v[186:189], v[112:115]
	s_nop 2
	v_add_u32_e32 v112, v155, v151
	ds_read_b128 v[112:115], v112
	s_waitcnt lgkmcnt(2)
	v_mfma_f32_16x16x32_bf16 v[108:111], v[136:139], v[198:201], v[108:111]
	v_mfma_f32_16x16x32_bf16 v[210:213], v[162:165], v[198:201], v[104:107]
	v_mfma_f32_16x16x32_bf16 v[100:103], v[190:193], v[198:201], v[100:103]
	s_nop 1
	v_add_u32_e32 v104, v156, v152
	v_mfma_f32_16x16x32_bf16 v[198:201], v[194:197], v[198:201], v[96:99]
	ds_read_b128 v[214:217], v104
	s_nop 1
	ds_read_b128 v[96:99], v146 offset:8192
	s_waitcnt lgkmcnt(3)
	v_mfma_f32_16x16x32_bf16 v[92:95], v[136:139], v[202:205], v[92:95]
	v_mfma_f32_16x16x32_bf16 v[218:221], v[162:165], v[202:205], v[88:91]
	v_mfma_f32_16x16x32_bf16 v[84:87], v[190:193], v[202:205], v[84:87]
	v_mfma_f32_16x16x32_bf16 v[202:205], v[194:197], v[202:205], v[80:83]
	ds_read_b128 v[222:225], v104 offset:2048
	s_nop 1
	ds_read_b128 v[80:83], v146 offset:10240
	s_waitcnt lgkmcnt(4)
	v_mfma_f32_16x16x32_bf16 v[76:79], v[136:139], v[112:115], v[76:79]
	v_mfma_f32_16x16x32_bf16 v[226:229], v[162:165], v[112:115], v[72:75]
	v_mfma_f32_16x16x32_bf16 v[68:71], v[190:193], v[112:115], v[68:71]
	v_mfma_f32_16x16x32_bf16 v[230:233], v[194:197], v[112:115], v[64:67]
	ds_read_b128 v[234:237], v104 offset:4096
	s_nop 1
	ds_read_b128 v[64:67], v146 offset:12288
	s_waitcnt lgkmcnt(4)
	v_mfma_f32_16x16x32_bf16 v[238:241], v[162:165], v[96:99], v[56:59]
	v_mfma_f32_16x16x32_bf16 v[60:63], v[136:139], v[96:99], v[60:63]
	s_nop 1
	v_add_u32_e32 v56, v156, v154
	v_mfma_f32_16x16x32_bf16 v[52:55], v[190:193], v[96:99], v[52:55]
	v_mfma_f32_16x16x32_bf16 v[242:245], v[194:197], v[96:99], v[48:51]
	ds_read_b128 v[246:249], v56 offset:6144
	s_nop 1
	v_add_u32_e32 v48, v155, v153
	ds_read_b128 v[48:51], v48
	s_waitcnt lgkmcnt(4)
	v_mfma_f32_16x16x32_bf16 v[250:253], v[162:165], v[80:83], v[40:43]
	v_mfma_f32_16x16x32_bf16 v[44:47], v[136:139], v[80:83], v[44:47]
	s_nop 1
	v_add_u32_e32 v40, v157, v145
	v_mfma_f32_16x16x32_bf16 v[36:39], v[190:193], v[80:83], v[36:39]
	v_mfma_f32_16x16x32_bf16 v[172:175], v[194:197], v[80:83], v[32:35]
	s_nop 2
	ds_read_b128 v[32:35], v40
	s_waitcnt lgkmcnt(3)
; #define MFMA16(a, b, c) __builtin_amdgcn_mfma_f32_16x16x32_bf16((a), (b), (c), 0, 0, 0)
; DI unsigned pk2(float a, float b) { f32x2 v = {a, b}; bf16x2_t r = __builtin_convertvector(v, bf16x2_t); return __builtin_bit_cast(unsigned, r); }
; DI bf16x8 ldfrag(const char* lds, int row, int chunk) { return *(const bf16x8*)(lds + swz(row, chunk)); }
; template <bool RSTD, bool SWAP>
; DI void gemm_tile(gacc_t& acc, const bf16_t* __restrict__ A, int lda, const bf16_t* __restrict__ Bt, int ldb, int K,
;                   char* lds, int tid, int wr, int wc, int lane, const float* ssq_row) {
;     ...
;         for (int idx = 0; idx < 16; ++idx) {
;             const int ks = idx >> 3, m = idx & 7;
;             if (idx < 14) afr[(idx + 2) % 3] = ldfrag(cur, wr * 128 + ((idx + 2) & 7) * 16 + fr, ((idx + 2) >> 3) * 4 + fq);
;             if (ks == 0 && m >= 2 && m < 6) bfr[1][m - 2] = ldfrag(cur + 32768, wc * 64 + (m - 2) * 16 + fr, 4 + fq);
; #pragma unroll
;             for (int n = 0; n < 4; ++n) acc[m][n] = SWAP ? MFMA16(bfr[ks][n], afr[idx % 3], acc[m][n]) : MFMA16(afr[idx % 3], bfr[ks][n], acc[m][n]);
;     DI void operator()(gacc_t& acc, int pm, int pn, char* lds, int tid, int wr, int wc, int lane) const {
;     ...
; #pragma unroll
;             for (int m = 0; m < 8; ++m) {
;                 const float r = rlt[m * 16];
; #pragma unroll
;                 for (int n = 0; n < 4; ++n) { u32x2 w; w.x = pk2(acc[m][n][0] * r, acc[m][n][1] * r); w.y = pk2(acc[m][n][2] * r, acc[m][n][3] * r); *(u32x2*)(lbase + m * 16 * 528 + n * 32) = w; }
;             }
	v_mfma_f32_16x16x32_bf16 v[28:31], v[136:139], v[64:67], v[28:31]
	v_mfma_f32_16x16x32_bf16 v[176:179], v[162:165], v[64:67], v[24:27]
	v_mfma_f32_16x16x32_bf16 v[20:23], v[190:193], v[64:67], v[20:23]
	v_mfma_f32_16x16x32_bf16 v[180:183], v[194:197], v[64:67], v[16:19]
	s_nop 2
	ds_read_b128 v[16:19], v40 offset:2048
	s_waitcnt lgkmcnt(2)
	v_mfma_f32_16x16x32_bf16 v[12:15], v[136:139], v[48:51], v[12:15]
	v_mfma_f32_16x16x32_bf16 v[136:139], v[162:165], v[48:51], v[8:11]
	s_nop 2
	v_add_u32_e32 v8, v157, v151
	v_mfma_f32_16x16x32_bf16 v[4:7], v[190:193], v[48:51], v[4:7]
	v_mfma_f32_16x16x32_bf16 v[162:165], v[194:197], v[48:51], v[0:3]
	s_nop 2
	ds_read_b128 v[0:3], v40 offset:4096
	s_waitcnt lgkmcnt(2)
	v_mfma_f32_16x16x32_bf16 v[120:123], v[214:217], v[32:35], v[124:127]
	v_mfma_f32_16x16x32_bf16 v[112:115], v[222:225], v[32:35], v[206:209]
	v_mfma_f32_16x16x32_bf16 v[124:127], v[234:237], v[32:35], v[116:119]
	v_mfma_f32_16x16x32_bf16 v[116:119], v[246:249], v[32:35], v[186:189]
	ds_read_b128 v[8:11], v8
	s_waitcnt lgkmcnt(2)
	v_mfma_f32_16x16x32_bf16 v[104:107], v[214:217], v[16:19], v[108:111]
	v_mfma_f32_16x16x32_bf16 v[96:99], v[222:225], v[16:19], v[210:213]
	v_mfma_f32_16x16x32_bf16 v[108:111], v[234:237], v[16:19], v[100:103]
	v_mfma_f32_16x16x32_bf16 v[100:103], v[246:249], v[16:19], v[198:201]
	ds_read_b128 v[16:19], v40 offset:8192
	s_waitcnt lgkmcnt(2)
	v_mfma_f32_16x16x32_bf16 v[88:91], v[214:217], v[0:3], v[92:95]
	v_mfma_f32_16x16x32_bf16 v[80:83], v[222:225], v[0:3], v[218:221]
	v_mfma_f32_16x16x32_bf16 v[92:95], v[234:237], v[0:3], v[84:87]
	v_mfma_f32_16x16x32_bf16 v[84:87], v[246:249], v[0:3], v[202:205]
	ds_read_b128 v[0:3], v40 offset:10240
	s_waitcnt lgkmcnt(2)
	v_mfma_f32_16x16x32_bf16 v[72:75], v[214:217], v[8:11], v[76:79]
	v_mfma_f32_16x16x32_bf16 v[64:67], v[222:225], v[8:11], v[226:229]
	v_mfma_f32_16x16x32_bf16 v[76:79], v[234:237], v[8:11], v[68:71]
	v_mfma_f32_16x16x32_bf16 v[68:71], v[246:249], v[8:11], v[230:233]
	ds_read_b128 v[8:11], v40 offset:12288
	s_waitcnt lgkmcnt(2)
	v_mfma_f32_16x16x32_bf16 v[56:59], v[214:217], v[16:19], v[60:63]
	v_mfma_f32_16x16x32_bf16 v[48:51], v[222:225], v[16:19], v[238:241]
	v_mfma_f32_16x16x32_bf16 v[60:63], v[234:237], v[16:19], v[52:55]
	v_mfma_f32_16x16x32_bf16 v[52:55], v[246:249], v[16:19], v[242:245]
	v_add_u32_e32 v16, v157, v153
	ds_read_b128 v[186:189], v16
	s_waitcnt lgkmcnt(2)
	v_mfma_f32_16x16x32_bf16 v[40:43], v[214:217], v[0:3], v[44:47]
	v_mfma_f32_16x16x32_bf16 v[32:35], v[222:225], v[0:3], v[250:253]
	v_mfma_f32_16x16x32_bf16 v[44:47], v[234:237], v[0:3], v[36:39]
	v_mfma_f32_16x16x32_bf16 v[36:39], v[246:249], v[0:3], v[172:175]
	s_waitcnt lgkmcnt(1)
	v_mfma_f32_16x16x32_bf16 v[24:27], v[214:217], v[8:11], v[28:31]
	v_mfma_f32_16x16x32_bf16 v[16:19], v[222:225], v[8:11], v[176:179]
	v_mfma_f32_16x16x32_bf16 v[28:31], v[234:237], v[8:11], v[20:23]
	v_mfma_f32_16x16x32_bf16 v[20:23], v[246:249], v[8:11], v[180:183]
	s_waitcnt lgkmcnt(0)
	v_mfma_f32_16x16x32_bf16 v[8:11], v[214:217], v[186:189], v[12:15]
	v_mfma_f32_16x16x32_bf16 v[0:3], v[222:225], v[186:189], v[136:139]
	v_mfma_f32_16x16x32_bf16 v[12:15], v[234:237], v[186:189], v[4:7]
	v_mfma_f32_16x16x32_bf16 v[4:7], v[246:249], v[186:189], v[162:165]
	s_nop 0
	v_mov_b32_e32 v138, v140
	v_mov_b32_e32 v136, v141
	s_cmp_lt_i32 s20, 64
	s_waitcnt vmcnt(0)
	s_barrier
	s_cselect_b64 s[6:7], -1, 0
	v_and_b32_e32 v137, 15, v136
	s_and_b64 s[20:21], s[6:7], exec
	s_movk_i32 s19, 0xf000
	v_ashrrev_i32_e32 v136, 2, v136
	s_cselect_b32 s19, s19, 0x7fffe000
	v_or_b32_e32 v139, v137, v144
	v_and_b32_e32 v136, -4, v136
	s_ashr_i32 s17, s17, 24
	v_mul_lo_u32 v139, v139, s3
	v_lshlrev_b32_e32 v146, 1, v136
	s_cmp_gt_i32 s17, 7
	v_add3_u32 v139, v158, v139, v146
	v_lshl_add_u32 v146, v137, 2, v159
	s_cselect_b64 s[20:21], -1, 0
	s_cmp_lt_i32 s17, 8
	s_mov_b64 s[30:31], -1
	s_cbranch_scc1 .LBB0_144
	ds_read_b32 v162, v146
	v_add_u32_e32 v161, 0x2000, v139
	s_mov_b64 s[30:31], 0
	s_waitcnt lgkmcnt(0)
	v_pk_mul_f32 v[164:165], v[120:121], v[162:163] op_sel_hi:[1,0]
	v_pk_mul_f32 v[166:167], v[122:123], v[162:163] op_sel_hi:[1,0]
	v_cvt_pk_bf16_f32 v164, v164, v165
	v_cvt_pk_bf16_f32 v165, v166, v167
	v_pk_mul_f32 v[166:167], v[112:113], v[162:163] op_sel_hi:[1,0]
	v_pk_mul_f32 v[172:173], v[114:115], v[162:163] op_sel_hi:[1,0]
	v_cvt_pk_bf16_f32 v166, v166, v167
	v_cvt_pk_bf16_f32 v167, v172, v173
	ds_write2_b64 v139, v[164:165], v[166:167] offset1:4
	v_pk_mul_f32 v[164:165], v[124:125], v[162:163] op_sel_hi:[1,0]
	v_pk_mul_f32 v[166:167], v[126:127], v[162:163] op_sel_hi:[1,0]
	v_cvt_pk_bf16_f32 v164, v164, v165
	v_cvt_pk_bf16_f32 v165, v166, v167
	v_pk_mul_f32 v[166:167], v[116:117], v[162:163] op_sel_hi:[1,0]
	v_pk_mul_f32 v[162:163], v[118:119], v[162:163] op_sel_hi:[1,0]
	v_cvt_pk_bf16_f32 v166, v166, v167
	v_cvt_pk_bf16_f32 v167, v162, v163
	ds_write2_b64 v139, v[164:165], v[166:167] offset0:8 offset1:12
	ds_read_b32 v162, v146 offset:64
	s_waitcnt lgkmcnt(0)
	v_pk_mul_f32 v[164:165], v[104:105], v[162:163] op_sel_hi:[1,0]
	v_pk_mul_f32 v[166:167], v[106:107], v[162:163] op_sel_hi:[1,0]
	v_cvt_pk_bf16_f32 v164, v164, v165
	v_cvt_pk_bf16_f32 v165, v166, v167
	v_pk_mul_f32 v[166:167], v[96:97], v[162:163] op_sel_hi:[1,0]
	v_pk_mul_f32 v[172:173], v[98:99], v[162:163] op_sel_hi:[1,0]
	v_cvt_pk_bf16_f32 v166, v166, v167
	v_cvt_pk_bf16_f32 v167, v172, v173
	ds_write2_b64 v161, v[164:165], v[166:167] offset0:32 offset1:36
	v_pk_mul_f32 v[164:165], v[108:109], v[162:163] op_sel_hi:[1,0]
	v_pk_mul_f32 v[166:167], v[110:111], v[162:163] op_sel_hi:[1,0]
	v_cvt_pk_bf16_f32 v164, v164, v165
	v_cvt_pk_bf16_f32 v165, v166, v167
	v_pk_mul_f32 v[166:167], v[100:101], v[162:163] op_sel_hi:[1,0]
	v_pk_mul_f32 v[162:163], v[102:103], v[162:163] op_sel_hi:[1,0]
	v_cvt_pk_bf16_f32 v166, v166, v167
	v_cvt_pk_bf16_f32 v167, v162, v163
	ds_write2_b64 v161, v[164:165], v[166:167] offset0:40 offset1:44
	ds_read_b32 v162, v146 offset:128
	v_add_u32_e32 v161, 0x4000, v139
	s_waitcnt lgkmcnt(0)
; DI unsigned pk2(float a, float b) { f32x2 v = {a, b}; bf16x2_t r = __builtin_convertvector(v, bf16x2_t); return __builtin_bit_cast(unsigned, r); }
;     DI void operator()(gacc_t& acc, int pm, int pn, char* lds, int tid, int wr, int wc, int lane) const {
;     ...
; #pragma unroll
;             for (int m = 0; m < 8; ++m) {
;                 const float r = rlt[m * 16];
; #pragma unroll
;                 for (int n = 0; n < 4; ++n) { u32x2 w; w.x = pk2(acc[m][n][0] * r, acc[m][n][1] * r); w.y = pk2(acc[m][n][2] * r, acc[m][n][3] * r); *(u32x2*)(lbase + m * 16 * 528 + n * 32) = w; }
;             }
	v_pk_mul_f32 v[164:165], v[88:89], v[162:163] op_sel_hi:[1,0]
	v_pk_mul_f32 v[166:167], v[90:91], v[162:163] op_sel_hi:[1,0]
	v_cvt_pk_bf16_f32 v164, v164, v165
	v_cvt_pk_bf16_f32 v165, v166, v167
	v_pk_mul_f32 v[166:167], v[80:81], v[162:163] op_sel_hi:[1,0]
	v_pk_mul_f32 v[172:173], v[82:83], v[162:163] op_sel_hi:[1,0]
	v_cvt_pk_bf16_f32 v166, v166, v167
	v_cvt_pk_bf16_f32 v167, v172, v173
	ds_write2_b64 v161, v[164:165], v[166:167] offset0:64 offset1:68
	v_pk_mul_f32 v[164:165], v[92:93], v[162:163] op_sel_hi:[1,0]
	v_pk_mul_f32 v[166:167], v[94:95], v[162:163] op_sel_hi:[1,0]
	v_cvt_pk_bf16_f32 v164, v164, v165
	v_cvt_pk_bf16_f32 v165, v166, v167
	v_pk_mul_f32 v[166:167], v[84:85], v[162:163] op_sel_hi:[1,0]
	v_pk_mul_f32 v[162:163], v[86:87], v[162:163] op_sel_hi:[1,0]
	v_cvt_pk_bf16_f32 v166, v166, v167
	v_cvt_pk_bf16_f32 v167, v162, v163
	ds_write2_b64 v161, v[164:165], v[166:167] offset0:72 offset1:76
	ds_read_b32 v162, v146 offset:192
	v_add_u32_e32 v161, 0x6000, v139
	s_waitcnt lgkmcnt(0)
	v_pk_mul_f32 v[164:165], v[72:73], v[162:163] op_sel_hi:[1,0]
	v_pk_mul_f32 v[166:167], v[74:75], v[162:163] op_sel_hi:[1,0]
	v_cvt_pk_bf16_f32 v164, v164, v165
	v_cvt_pk_bf16_f32 v165, v166, v167
	v_pk_mul_f32 v[166:167], v[64:65], v[162:163] op_sel_hi:[1,0]
	v_pk_mul_f32 v[172:173], v[66:67], v[162:163] op_sel_hi:[1,0]
	v_cvt_pk_bf16_f32 v166, v166, v167
	v_cvt_pk_bf16_f32 v167, v172, v173
	ds_write2_b64 v161, v[164:165], v[166:167] offset0:96 offset1:100
	v_pk_mul_f32 v[164:165], v[76:77], v[162:163] op_sel_hi:[1,0]
	v_pk_mul_f32 v[166:167], v[78:79], v[162:163] op_sel_hi:[1,0]
	v_cvt_pk_bf16_f32 v164, v164, v165
	v_cvt_pk_bf16_f32 v165, v166, v167
	v_pk_mul_f32 v[166:167], v[68:69], v[162:163] op_sel_hi:[1,0]
	v_pk_mul_f32 v[162:163], v[70:71], v[162:163] op_sel_hi:[1,0]
	v_cvt_pk_bf16_f32 v166, v166, v167
	v_cvt_pk_bf16_f32 v167, v162, v163
	ds_write2_b64 v161, v[164:165], v[166:167] offset0:104 offset1:108
	ds_read_b32 v162, v146 offset:256
	v_add_u32_e32 v161, 0x8000, v139
	s_waitcnt lgkmcnt(0)
	v_pk_mul_f32 v[164:165], v[56:57], v[162:163] op_sel_hi:[1,0]
	v_pk_mul_f32 v[166:167], v[58:59], v[162:163] op_sel_hi:[1,0]
	v_cvt_pk_bf16_f32 v164, v164, v165
	v_cvt_pk_bf16_f32 v165, v166, v167
	v_pk_mul_f32 v[166:167], v[48:49], v[162:163] op_sel_hi:[1,0]
	v_pk_mul_f32 v[172:173], v[50:51], v[162:163] op_sel_hi:[1,0]
	v_cvt_pk_bf16_f32 v166, v166, v167
	v_cvt_pk_bf16_f32 v167, v172, v173
	ds_write2_b64 v161, v[164:165], v[166:167] offset0:128 offset1:132
	v_pk_mul_f32 v[164:165], v[60:61], v[162:163] op_sel_hi:[1,0]
	v_pk_mul_f32 v[166:167], v[62:63], v[162:163] op_sel_hi:[1,0]
	v_cvt_pk_bf16_f32 v164, v164, v165
	v_cvt_pk_bf16_f32 v165, v166, v167
	v_pk_mul_f32 v[166:167], v[52:53], v[162:163] op_sel_hi:[1,0]
	v_pk_mul_f32 v[162:163], v[54:55], v[162:163] op_sel_hi:[1,0]
	v_cvt_pk_bf16_f32 v166, v166, v167
	v_cvt_pk_bf16_f32 v167, v162, v163
	ds_write2_b64 v161, v[164:165], v[166:167] offset0:136 offset1:140
	ds_read_b32 v162, v146 offset:320
	v_add_u32_e32 v161, 0xa000, v139
	s_waitcnt lgkmcnt(0)
	v_pk_mul_f32 v[164:165], v[40:41], v[162:163] op_sel_hi:[1,0]
	v_pk_mul_f32 v[166:167], v[42:43], v[162:163] op_sel_hi:[1,0]
	v_cvt_pk_bf16_f32 v164, v164, v165
	v_cvt_pk_bf16_f32 v165, v166, v167
	v_pk_mul_f32 v[166:167], v[32:33], v[162:163] op_sel_hi:[1,0]
	v_pk_mul_f32 v[172:173], v[34:35], v[162:163] op_sel_hi:[1,0]
	v_cvt_pk_bf16_f32 v166, v166, v167
	v_cvt_pk_bf16_f32 v167, v172, v173
	ds_write2_b64 v161, v[164:165], v[166:167] offset0:160 offset1:164
	v_pk_mul_f32 v[164:165], v[44:45], v[162:163] op_sel_hi:[1,0]
	v_pk_mul_f32 v[166:167], v[46:47], v[162:163] op_sel_hi:[1,0]
	v_cvt_pk_bf16_f32 v164, v164, v165
	v_cvt_pk_bf16_f32 v165, v166, v167
	v_pk_mul_f32 v[166:167], v[36:37], v[162:163] op_sel_hi:[1,0]
	v_pk_mul_f32 v[162:163], v[38:39], v[162:163] op_sel_hi:[1,0]
	v_cvt_pk_bf16_f32 v166, v166, v167
	v_cvt_pk_bf16_f32 v167, v162, v163
	ds_write2_b64 v161, v[164:165], v[166:167] offset0:168 offset1:172
	ds_read_b32 v162, v146 offset:384
	v_add_u32_e32 v161, 0xc000, v139
	s_waitcnt lgkmcnt(0)
	v_pk_mul_f32 v[164:165], v[24:25], v[162:163] op_sel_hi:[1,0]
	v_pk_mul_f32 v[166:167], v[26:27], v[162:163] op_sel_hi:[1,0]
	v_cvt_pk_bf16_f32 v164, v164, v165
	v_cvt_pk_bf16_f32 v165, v166, v167
	v_pk_mul_f32 v[166:167], v[16:17], v[162:163] op_sel_hi:[1,0]
	v_pk_mul_f32 v[172:173], v[18:19], v[162:163] op_sel_hi:[1,0]
	v_cvt_pk_bf16_f32 v166, v166, v167
	v_cvt_pk_bf16_f32 v167, v172, v173
	ds_write2_b64 v161, v[164:165], v[166:167] offset0:192 offset1:196
	v_pk_mul_f32 v[164:165], v[28:29], v[162:163] op_sel_hi:[1,0]
	v_pk_mul_f32 v[166:167], v[30:31], v[162:163] op_sel_hi:[1,0]
	v_cvt_pk_bf16_f32 v164, v164, v165
	v_cvt_pk_bf16_f32 v165, v166, v167
	v_pk_mul_f32 v[166:167], v[20:21], v[162:163] op_sel_hi:[1,0]
	v_pk_mul_f32 v[162:163], v[22:23], v[162:163] op_sel_hi:[1,0]
	v_cvt_pk_bf16_f32 v166, v166, v167
	v_cvt_pk_bf16_f32 v167, v162, v163
	ds_write2_b64 v161, v[164:165], v[166:167] offset0:200 offset1:204
	ds_read_b32 v162, v146 offset:448
	v_add_u32_e32 v161, 0xe000, v139
	s_waitcnt lgkmcnt(0)
	v_pk_mul_f32 v[164:165], v[8:9], v[162:163] op_sel_hi:[1,0]
	v_pk_mul_f32 v[166:167], v[10:11], v[162:163] op_sel_hi:[1,0]
	v_cvt_pk_bf16_f32 v164, v164, v165
	v_cvt_pk_bf16_f32 v165, v166, v167
	v_pk_mul_f32 v[166:167], v[0:1], v[162:163] op_sel_hi:[1,0]
	v_pk_mul_f32 v[172:173], v[2:3], v[162:163] op_sel_hi:[1,0]
	v_cvt_pk_bf16_f32 v166, v166, v167
	v_cvt_pk_bf16_f32 v167, v172, v173
	ds_write2_b64 v161, v[164:165], v[166:167] offset0:224 offset1:228
	v_pk_mul_f32 v[164:165], v[12:13], v[162:163] op_sel_hi:[1,0]
	v_pk_mul_f32 v[166:167], v[14:15], v[162:163] op_sel_hi:[1,0]
	v_cvt_pk_bf16_f32 v164, v164, v165
	v_cvt_pk_bf16_f32 v165, v166, v167
	v_pk_mul_f32 v[166:167], v[4:5], v[162:163] op_sel_hi:[1,0]
	v_pk_mul_f32 v[162:163], v[6:7], v[162:163] op_sel_hi:[1,0]
	v_cvt_pk_bf16_f32 v166, v166, v167
	v_cvt_pk_bf16_f32 v167, v162, v163
	ds_write2_b64 v161, v[164:165], v[166:167] offset0:232 offset1:236

; #define MFMA16(a, b, c) __builtin_amdgcn_mfma_f32_16x16x32_bf16((a), (b), (c), 0, 0, 0)
; DI bf16x8 ldfrag(const char* lds, int row, int chunk) { return *(const bf16x8*)(lds + swz(row, chunk)); }
; template <bool RSTD, bool SWAP>
; DI void gemm_tile(gacc_t& acc, const bf16_t* __restrict__ A, int lda, const bf16_t* __restrict__ Bt, int ldb, int K,
;                   char* lds, int tid, int wr, int wc, int lane, const float* ssq_row) {
;     ...
;     for (int kt = 0; kt < nk; ++kt) {
;         const char* cur = lds + (kt & 1) * 65536;
;         if (kt + 1 < nk) GEMM_ISSUE(kt + 1, (kt + 1) & 1);
;         bf16x8 bfr[2][4], afr[3];
; #pragma unroll
;         for (int n = 0; n < 4; ++n) bfr[0][n] = ldfrag(cur + 32768, wc * 64 + n * 16 + fr, fq);
;         afr[0] = ldfrag(cur, wr * 128 + fr, fq);
;         afr[1] = ldfrag(cur, wr * 128 + 16 + fr, fq);
; #pragma unroll
;         for (int idx = 0; idx < 16; ++idx) {
;             const int ks = idx >> 3, m = idx & 7;
;             if (idx < 14) afr[(idx + 2) % 3] = ldfrag(cur, wr * 128 + ((idx + 2) & 7) * 16 + fr, ((idx + 2) >> 3) * 4 + fq);
;             if (ks == 0 && m >= 2 && m < 6) bfr[1][m - 2] = ldfrag(cur + 32768, wc * 64 + (m - 2) * 16 + fr, 4 + fq);
; #pragma unroll
;             for (int n = 0; n < 4; ++n) acc[m][n] = SWAP ? MFMA16(bfr[ks][n], afr[idx % 3], acc[m][n]) : MFMA16(afr[idx % 3], bfr[ks][n], acc[m][n]);
;         }
.LBB0_281:
	v_lshl_add_u64 v[158:159], v[136:137], 0, s[4:5]
	s_mov_b64 s[20:21], 0x1880080
	v_lshl_add_u64 v[162:163], v[158:159], 0, s[20:21]
	s_mov_b64 s[20:21], 0x18a0080
	s_add_i32 s18, s17, 0xffff0000
	s_and_b32 s19, s17, 0x10000
	v_lshl_add_u64 v[166:167], v[158:159], 0, s[20:21]
	s_mov_b64 s[20:21], 0x18c0080
	s_and_b32 s23, s18, 0x10000
	s_add_i32 s18, s19, 0
	v_lshl_add_u64 v[174:175], v[158:159], 0, s[20:21]
	s_mov_b64 s[20:21], 0x18e0080
	v_lshl_add_u64 v[156:157], v[138:139], 0, s[4:5]
	v_lshl_add_u64 v[158:159], v[158:159], 0, s[20:21]
	s_add_i32 s20, s18, s16
	v_lshl_add_u64 v[160:161], v[156:157], 0, s[14:15]
	s_add_i32 s21, s20, 0x8000
	s_mov_b32 m0, s20
	v_lshl_add_u64 v[164:165], v[156:157], 0, s[72:73]
	global_load_lds_dwordx4 v[160:161], off
	v_mfma_f32_16x16x32_bf16 v[60:63], v[194:197], v[236:239], v[60:63]
	s_mov_b32 m0, s21
	v_lshl_add_u64 v[172:173], v[156:157], 0, s[76:77]
	global_load_lds_dwordx4 v[162:163], off
	v_mfma_f32_16x16x32_bf16 v[56:59], v[198:201], v[236:239], v[56:59]
	s_add_i32 m0, s20, 0x2000
	v_lshl_add_u64 v[156:157], v[156:157], 0, s[0:1]
	global_load_lds_dwordx4 v[164:165], off
	v_mfma_f32_16x16x32_bf16 v[52:55], v[202:205], v[236:239], v[52:55]
	s_add_i32 m0, s20, 0xa000
	s_add_i32 s19, s23, 0
	global_load_lds_dwordx4 v[166:167], off
	v_mfma_f32_16x16x32_bf16 v[48:51], v[206:209], v[236:239], v[48:51]
	s_add_i32 m0, s20, 0x4000
	v_add_u32_e32 v146, s19, v142
	global_load_lds_dwordx4 v[172:173], off
	v_mfma_f32_16x16x32_bf16 v[44:47], v[194:197], v[240:243], v[44:47]
	s_add_i32 m0, s20, 0xc000
	v_add3_u32 v155, v146, v148, v149
	global_load_lds_dwordx4 v[174:175], off
	v_mfma_f32_16x16x32_bf16 v[40:43], v[198:201], v[240:243], v[40:43]
	s_add_i32 m0, s20, 0x6000
	v_add_u32_e32 v252, v146, v144
	global_load_lds_dwordx4 v[156:157], off
	v_mfma_f32_16x16x32_bf16 v[36:39], v[202:205], v[240:243], v[36:39]
	s_add_i32 m0, s20, 0xe000
	s_nop 0
	global_load_lds_dwordx4 v[158:159], off
	v_mfma_f32_16x16x32_bf16 v[32:35], v[206:209], v[240:243], v[32:35]
	ds_read_b128 v[156:159], v155 offset:32768
	ds_read_b128 v[160:163], v155 offset:34816
	ds_read_b128 v[172:175], v155 offset:36864
	ds_read_b128 v[176:179], v155 offset:38912
	ds_read_b128 v[164:167], v252
	ds_read_b128 v[180:183], v252 offset:2048
	ds_read_b128 v[190:193], v252 offset:4096
	v_add_u32_e32 v155, v146, v150
	v_mfma_f32_16x16x32_bf16 v[28:31], v[194:197], v[244:247], v[28:31]
	v_mfma_f32_16x16x32_bf16 v[24:27], v[198:201], v[244:247], v[24:27]
	v_mfma_f32_16x16x32_bf16 v[20:23], v[202:205], v[244:247], v[20:23]
	v_mfma_f32_16x16x32_bf16 v[16:19], v[206:209], v[244:247], v[16:19]
	v_mfma_f32_16x16x32_bf16 v[12:15], v[194:197], v[248:251], v[12:15]
	v_mfma_f32_16x16x32_bf16 v[8:11], v[198:201], v[248:251], v[8:11]
	v_mfma_f32_16x16x32_bf16 v[4:7], v[202:205], v[248:251], v[4:7]
	v_mfma_f32_16x16x32_bf16 v[0:3], v[206:209], v[248:251], v[0:3]
	s_waitcnt lgkmcnt(2)
	v_mfma_f32_16x16x32_bf16 v[124:127], v[156:159], v[164:167], v[124:127]
	v_add_u32_e32 v146, v146, v152
	v_mfma_f32_16x16x32_bf16 v[120:123], v[160:163], v[164:167], v[120:123]
	v_mfma_f32_16x16x32_bf16 v[116:119], v[172:175], v[164:167], v[116:119]
	v_mfma_f32_16x16x32_bf16 v[112:115], v[176:179], v[164:167], v[112:115]
	ds_read_b128 v[164:167], v155
	v_add_u32_e32 v155, s19, v145
	v_add_u32_e32 v203, v155, v151
	s_waitcnt lgkmcnt(2)
	v_mfma_f32_16x16x32_bf16 v[108:111], v[156:159], v[180:183], v[108:111]
	v_add_u32_e32 v206, v155, v153
	v_mfma_f32_16x16x32_bf16 v[104:107], v[160:163], v[180:183], v[104:107]
	v_mfma_f32_16x16x32_bf16 v[100:103], v[172:175], v[180:183], v[100:103]
	v_mfma_f32_16x16x32_bf16 v[96:99], v[176:179], v[180:183], v[96:99]
	ds_read_b128 v[180:183], v252 offset:8192
	ds_read_b128 v[194:197], v203 offset:32768
	s_waitcnt lgkmcnt(3)
	v_mfma_f32_16x16x32_bf16 v[92:95], v[156:159], v[190:193], v[92:95]
	v_mfma_f32_16x16x32_bf16 v[88:91], v[160:163], v[190:193], v[88:91]
	v_mfma_f32_16x16x32_bf16 v[84:87], v[172:175], v[190:193], v[84:87]
	v_mfma_f32_16x16x32_bf16 v[80:83], v[176:179], v[190:193], v[80:83]
	ds_read_b128 v[190:193], v252 offset:10240
	ds_read_b128 v[198:201], v203 offset:34816
	s_waitcnt lgkmcnt(4)
	v_mfma_f32_16x16x32_bf16 v[76:79], v[156:159], v[164:167], v[76:79]
	v_mfma_f32_16x16x32_bf16 v[72:75], v[160:163], v[164:167], v[72:75]
	v_mfma_f32_16x16x32_bf16 v[68:71], v[172:175], v[164:167], v[68:71]
	v_mfma_f32_16x16x32_bf16 v[64:67], v[176:179], v[164:167], v[64:67]
	ds_read_b128 v[164:167], v252 offset:12288
	ds_read_b128 v[202:205], v203 offset:36864
	s_waitcnt lgkmcnt(5)
	v_mfma_f32_16x16x32_bf16 v[60:63], v[156:159], v[180:183], v[60:63]
	v_mfma_f32_16x16x32_bf16 v[56:59], v[160:163], v[180:183], v[56:59]
	v_mfma_f32_16x16x32_bf16 v[52:55], v[172:175], v[180:183], v[52:55]
	v_mfma_f32_16x16x32_bf16 v[48:51], v[176:179], v[180:183], v[48:51]
	ds_read_b128 v[206:209], v206 offset:38912
	ds_read_b128 v[180:183], v146
	v_add_u32_e32 v146, v155, v144
	s_waitcnt lgkmcnt(5)
	v_mfma_f32_16x16x32_bf16 v[44:47], v[156:159], v[190:193], v[44:47]
	v_mfma_f32_16x16x32_bf16 v[40:43], v[160:163], v[190:193], v[40:43]
	v_mfma_f32_16x16x32_bf16 v[36:39], v[172:175], v[190:193], v[36:39]
	v_mfma_f32_16x16x32_bf16 v[32:35], v[176:179], v[190:193], v[32:35]
	ds_read_b128 v[190:193], v146
	s_waitcnt lgkmcnt(4)
	v_mfma_f32_16x16x32_bf16 v[28:31], v[156:159], v[164:167], v[28:31]
	v_mfma_f32_16x16x32_bf16 v[24:27], v[160:163], v[164:167], v[24:27]
	v_mfma_f32_16x16x32_bf16 v[20:23], v[172:175], v[164:167], v[20:23]
	v_mfma_f32_16x16x32_bf16 v[16:19], v[176:179], v[164:167], v[16:19]
	ds_read_b128 v[164:167], v146 offset:2048
	s_waitcnt lgkmcnt(2)
; #define MFMA16(a, b, c) __builtin_amdgcn_mfma_f32_16x16x32_bf16((a), (b), (c), 0, 0, 0)
; DI bf16x8 ldfrag(const char* lds, int row, int chunk) { return *(const bf16x8*)(lds + swz(row, chunk)); }
; template <bool RSTD, bool SWAP>
; DI void gemm_tile(gacc_t& acc, const bf16_t* __restrict__ A, int lda, const bf16_t* __restrict__ Bt, int ldb, int K,
;                   char* lds, int tid, int wr, int wc, int lane, const float* ssq_row) {
;     ...
;     for (int kt = 0; kt < nk; ++kt) {
;         const char* cur = lds + (kt & 1) * 65536;
;         if (kt + 1 < nk) GEMM_ISSUE(kt + 1, (kt + 1) & 1);
;         bf16x8 bfr[2][4], afr[3];
; #pragma unroll
;         for (int n = 0; n < 4; ++n) bfr[0][n] = ldfrag(cur + 32768, wc * 64 + n * 16 + fr, fq);
;         afr[0] = ldfrag(cur, wr * 128 + fr, fq);
;         afr[1] = ldfrag(cur, wr * 128 + 16 + fr, fq);
; #pragma unroll
;         for (int idx = 0; idx < 16; ++idx) {
;             const int ks = idx >> 3, m = idx & 7;
;             if (idx < 14) afr[(idx + 2) % 3] = ldfrag(cur, wr * 128 + ((idx + 2) & 7) * 16 + fr, ((idx + 2) >> 3) * 4 + fq);
;             if (ks == 0 && m >= 2 && m < 6) bfr[1][m - 2] = ldfrag(cur + 32768, wc * 64 + (m - 2) * 16 + fr, 4 + fq);
; #pragma unroll
;             for (int n = 0; n < 4; ++n) acc[m][n] = SWAP ? MFMA16(bfr[ks][n], afr[idx % 3], acc[m][n]) : MFMA16(afr[idx % 3], bfr[ks][n], acc[m][n]);
;         }
	v_mfma_f32_16x16x32_bf16 v[8:11], v[160:163], v[180:183], v[8:11]
	v_add_u32_e32 v160, v155, v150
	v_mfma_f32_16x16x32_bf16 v[12:15], v[156:159], v[180:183], v[12:15]
	v_mfma_f32_16x16x32_bf16 v[4:7], v[172:175], v[180:183], v[4:7]
	v_mfma_f32_16x16x32_bf16 v[0:3], v[176:179], v[180:183], v[0:3]
	ds_read_b128 v[156:159], v146 offset:4096
	s_waitcnt lgkmcnt(2)
	v_mfma_f32_16x16x32_bf16 v[124:127], v[194:197], v[190:193], v[124:127]
	v_mfma_f32_16x16x32_bf16 v[120:123], v[198:201], v[190:193], v[120:123]
	v_mfma_f32_16x16x32_bf16 v[116:119], v[202:205], v[190:193], v[116:119]
	v_mfma_f32_16x16x32_bf16 v[112:115], v[206:209], v[190:193], v[112:115]
	ds_read_b128 v[160:163], v160
	s_waitcnt lgkmcnt(2)
	v_mfma_f32_16x16x32_bf16 v[108:111], v[194:197], v[164:167], v[108:111]
	v_mfma_f32_16x16x32_bf16 v[104:107], v[198:201], v[164:167], v[104:107]
	v_mfma_f32_16x16x32_bf16 v[100:103], v[202:205], v[164:167], v[100:103]
	v_mfma_f32_16x16x32_bf16 v[96:99], v[206:209], v[164:167], v[96:99]
	ds_read_b128 v[236:239], v146 offset:8192
	s_waitcnt lgkmcnt(2)
	v_mfma_f32_16x16x32_bf16 v[92:95], v[194:197], v[156:159], v[92:95]
	v_mfma_f32_16x16x32_bf16 v[88:91], v[198:201], v[156:159], v[88:91]
	v_mfma_f32_16x16x32_bf16 v[84:87], v[202:205], v[156:159], v[84:87]
	v_mfma_f32_16x16x32_bf16 v[80:83], v[206:209], v[156:159], v[80:83]
	ds_read_b128 v[240:243], v146 offset:10240
	ds_read_b128 v[244:247], v146 offset:12288
	v_add_u32_e32 v146, v155, v152
	ds_read_b128 v[248:251], v146
	s_waitcnt lgkmcnt(4)
	v_mfma_f32_16x16x32_bf16 v[76:79], v[194:197], v[160:163], v[76:79]
	v_mfma_f32_16x16x32_bf16 v[72:75], v[198:201], v[160:163], v[72:75]
	v_mfma_f32_16x16x32_bf16 v[68:71], v[202:205], v[160:163], v[68:71]
	v_mfma_f32_16x16x32_bf16 v[64:67], v[206:209], v[160:163], v[64:67]
	s_waitcnt lgkmcnt(0)
	s_waitcnt vmcnt(0)
	s_add_u32 s4, s4, 0x80
	s_addc_u32 s5, s5, 0
	s_add_i32 s17, s17, 0x10000
	s_cmpk_eq_i32 s4, 0x780
	s_waitcnt vmcnt(0)
	s_barrier
	s_cbranch_scc0 .LBB0_281
	v_mfma_f32_16x16x32_bf16 v[60:63], v[194:197], v[236:239], v[60:63]
	v_mfma_f32_16x16x32_bf16 v[56:59], v[198:201], v[236:239], v[56:59]
	v_mfma_f32_16x16x32_bf16 v[52:55], v[202:205], v[236:239], v[52:55]
	v_mfma_f32_16x16x32_bf16 v[48:51], v[206:209], v[236:239], v[48:51]
	v_mfma_f32_16x16x32_bf16 v[44:47], v[194:197], v[240:243], v[44:47]
	v_mfma_f32_16x16x32_bf16 v[40:43], v[198:201], v[240:243], v[40:43]
	v_mfma_f32_16x16x32_bf16 v[36:39], v[202:205], v[240:243], v[36:39]
	v_mfma_f32_16x16x32_bf16 v[32:35], v[206:209], v[240:243], v[32:35]
	v_mfma_f32_16x16x32_bf16 v[28:31], v[194:197], v[244:247], v[28:31]
	v_mfma_f32_16x16x32_bf16 v[24:27], v[198:201], v[244:247], v[24:27]
	v_mfma_f32_16x16x32_bf16 v[20:23], v[202:205], v[244:247], v[20:23]
	v_mfma_f32_16x16x32_bf16 v[16:19], v[206:209], v[244:247], v[16:19]
	v_mfma_f32_16x16x32_bf16 v[12:15], v[194:197], v[248:251], v[12:15]
	v_mfma_f32_16x16x32_bf16 v[8:11], v[198:201], v[248:251], v[8:11]
	v_mfma_f32_16x16x32_bf16 v[4:7], v[202:205], v[248:251], v[4:7]
	v_mfma_f32_16x16x32_bf16 v[0:3], v[206:209], v[248:251], v[0:3]
	v_add_u32_e32 v146, s18, v142
	v_add3_u32 v155, v146, v148, v149
	ds_read_b128 v[136:139], v155 offset:32768
	ds_read_b128 v[156:159], v155 offset:34816
	ds_read_b128 v[164:167], v155 offset:36864
	ds_read_b128 v[172:175], v155 offset:38912
	v_add_u32_e32 v198, v146, v144
	ds_read_b128 v[160:163], v198
	ds_read_b128 v[176:179], v198 offset:2048
	v_add_u32_e32 v155, v146, v150
	ds_read_b128 v[180:183], v198 offset:4096
	s_waitcnt lgkmcnt(2)
	v_mfma_f32_16x16x32_bf16 v[124:127], v[136:139], v[160:163], v[124:127]
	v_add_u32_e32 v146, v146, v152
	s_lshl_b64 s[16:17], s[8:9], 8
	v_mfma_f32_16x16x32_bf16 v[120:123], v[156:159], v[160:163], v[120:123]
	v_mfma_f32_16x16x32_bf16 v[116:119], v[164:167], v[160:163], v[116:119]
	v_mfma_f32_16x16x32_bf16 v[112:115], v[172:175], v[160:163], v[112:115]
	ds_read_b128 v[160:163], v155
	v_add_u32_e32 v155, s18, v145
	v_add_u32_e32 v199, v155, v151
	s_waitcnt lgkmcnt(2)
	v_mfma_f32_16x16x32_bf16 v[108:111], v[136:139], v[176:179], v[108:111]
	v_mfma_f32_16x16x32_bf16 v[104:107], v[156:159], v[176:179], v[104:107]
	v_mfma_f32_16x16x32_bf16 v[100:103], v[164:167], v[176:179], v[100:103]
	v_mfma_f32_16x16x32_bf16 v[96:99], v[172:175], v[176:179], v[96:99]
	ds_read_b128 v[176:179], v198 offset:8192
	ds_read_b128 v[190:193], v199 offset:32768
	s_waitcnt lgkmcnt(3)
	v_mfma_f32_16x16x32_bf16 v[92:95], v[136:139], v[180:183], v[92:95]
	v_mfma_f32_16x16x32_bf16 v[88:91], v[156:159], v[180:183], v[88:91]
	v_mfma_f32_16x16x32_bf16 v[84:87], v[164:167], v[180:183], v[84:87]
	v_mfma_f32_16x16x32_bf16 v[80:83], v[172:175], v[180:183], v[80:83]
	ds_read_b128 v[180:183], v198 offset:10240
	ds_read_b128 v[194:197], v199 offset:34816
	s_waitcnt lgkmcnt(4)
	v_mfma_f32_16x16x32_bf16 v[76:79], v[136:139], v[160:163], v[76:79]
	v_mfma_f32_16x16x32_bf16 v[72:75], v[156:159], v[160:163], v[72:75]
	v_mfma_f32_16x16x32_bf16 v[68:71], v[164:167], v[160:163], v[68:71]
	v_mfma_f32_16x16x32_bf16 v[64:67], v[172:175], v[160:163], v[64:67]
	ds_read_b128 v[160:163], v198 offset:12288
	ds_read_b128 v[198:201], v199 offset:36864
	s_waitcnt lgkmcnt(5)
	v_mfma_f32_16x16x32_bf16 v[60:63], v[136:139], v[176:179], v[60:63]
	v_mfma_f32_16x16x32_bf16 v[56:59], v[156:159], v[176:179], v[56:59]
	v_mfma_f32_16x16x32_bf16 v[52:55], v[164:167], v[176:179], v[52:55]
	v_mfma_f32_16x16x32_bf16 v[48:51], v[172:175], v[176:179], v[48:51]
	ds_read_b128 v[176:179], v146
	v_add_u32_e32 v146, v155, v153
	ds_read_b128 v[202:205], v146 offset:38912
	v_add_u32_e32 v146, v155, v144
	s_waitcnt lgkmcnt(5)
; #define MFMA16(a, b, c) __builtin_amdgcn_mfma_f32_16x16x32_bf16((a), (b), (c), 0, 0, 0)
; DI unsigned pk2(float a, float b) { f32x2 v = {a, b}; bf16x2_t r = __builtin_convertvector(v, bf16x2_t); return __builtin_bit_cast(unsigned, r); }
; DI bf16x8 ldfrag(const char* lds, int row, int chunk) { return *(const bf16x8*)(lds + swz(row, chunk)); }
; template <bool RSTD, bool SWAP>
; DI void gemm_tile(gacc_t& acc, const bf16_t* __restrict__ A, int lda, const bf16_t* __restrict__ Bt, int ldb, int K,
;                   char* lds, int tid, int wr, int wc, int lane, const float* ssq_row) {
;     ...
;         for (int idx = 0; idx < 16; ++idx) {
;             const int ks = idx >> 3, m = idx & 7;
;             if (idx < 14) afr[(idx + 2) % 3] = ldfrag(cur, wr * 128 + ((idx + 2) & 7) * 16 + fr, ((idx + 2) >> 3) * 4 + fq);
;             if (ks == 0 && m >= 2 && m < 6) bfr[1][m - 2] = ldfrag(cur + 32768, wc * 64 + (m - 2) * 16 + fr, 4 + fq);
; #pragma unroll
;             for (int n = 0; n < 4; ++n) acc[m][n] = SWAP ? MFMA16(bfr[ks][n], afr[idx % 3], acc[m][n]) : MFMA16(afr[idx % 3], bfr[ks][n], acc[m][n]);
;         }
;     DI void operator()(gacc_t& acc, int pm, int pn, char* lds, int tid, int wr, int wc, int lane) const {
;     ...
;         for (int m = 0; m < 8; ++m)
; #pragma unroll
;             for (int n = 0; n < 4; ++n) { u32x2 w; w.x = pk2(acc[m][n][0], acc[m][n][1]); w.y = pk2(acc[m][n][2], acc[m][n][3]); *(u32x2*)(lbase + m * 16 * 528 + n * 32) = w; }
	v_mfma_f32_16x16x32_bf16 v[44:47], v[136:139], v[180:183], v[44:47]
	v_mfma_f32_16x16x32_bf16 v[40:43], v[156:159], v[180:183], v[40:43]
	v_mfma_f32_16x16x32_bf16 v[36:39], v[164:167], v[180:183], v[36:39]
	v_mfma_f32_16x16x32_bf16 v[32:35], v[172:175], v[180:183], v[32:35]
	ds_read_b128 v[180:183], v146
	s_waitcnt lgkmcnt(4)
	v_mfma_f32_16x16x32_bf16 v[28:31], v[136:139], v[160:163], v[28:31]
	v_mfma_f32_16x16x32_bf16 v[24:27], v[156:159], v[160:163], v[24:27]
	v_mfma_f32_16x16x32_bf16 v[20:23], v[164:167], v[160:163], v[20:23]
	v_mfma_f32_16x16x32_bf16 v[16:19], v[172:175], v[160:163], v[16:19]
	ds_read_b128 v[160:163], v146 offset:2048
	s_waitcnt lgkmcnt(3)
	v_mfma_f32_16x16x32_bf16 v[8:11], v[156:159], v[176:179], v[8:11]
	v_add_u32_e32 v156, v155, v150
	v_mfma_f32_16x16x32_bf16 v[12:15], v[136:139], v[176:179], v[12:15]
	v_mfma_f32_16x16x32_bf16 v[4:7], v[164:167], v[176:179], v[4:7]
	v_mfma_f32_16x16x32_bf16 v[0:3], v[172:175], v[176:179], v[0:3]
	ds_read_b128 v[136:139], v146 offset:4096
	s_waitcnt lgkmcnt(2)
	v_mfma_f32_16x16x32_bf16 v[124:127], v[190:193], v[180:183], v[124:127]
	v_mfma_f32_16x16x32_bf16 v[120:123], v[194:197], v[180:183], v[120:123]
	v_mfma_f32_16x16x32_bf16 v[116:119], v[198:201], v[180:183], v[116:119]
	v_mfma_f32_16x16x32_bf16 v[112:115], v[202:205], v[180:183], v[112:115]
	ds_read_b128 v[156:159], v156
	s_waitcnt lgkmcnt(2)
	v_mfma_f32_16x16x32_bf16 v[108:111], v[190:193], v[160:163], v[108:111]
	v_mfma_f32_16x16x32_bf16 v[104:107], v[194:197], v[160:163], v[104:107]
	v_mfma_f32_16x16x32_bf16 v[100:103], v[198:201], v[160:163], v[100:103]
	v_mfma_f32_16x16x32_bf16 v[96:99], v[202:205], v[160:163], v[96:99]
	ds_read_b128 v[160:163], v146 offset:8192
	s_waitcnt lgkmcnt(2)
	v_mfma_f32_16x16x32_bf16 v[92:95], v[190:193], v[136:139], v[92:95]
	v_mfma_f32_16x16x32_bf16 v[88:91], v[194:197], v[136:139], v[88:91]
	v_mfma_f32_16x16x32_bf16 v[84:87], v[198:201], v[136:139], v[84:87]
	v_mfma_f32_16x16x32_bf16 v[80:83], v[202:205], v[136:139], v[80:83]
	ds_read_b128 v[136:139], v146 offset:10240
	s_waitcnt lgkmcnt(2)
	v_mfma_f32_16x16x32_bf16 v[76:79], v[190:193], v[156:159], v[76:79]
	v_mfma_f32_16x16x32_bf16 v[72:75], v[194:197], v[156:159], v[72:75]
	v_mfma_f32_16x16x32_bf16 v[68:71], v[198:201], v[156:159], v[68:71]
	v_mfma_f32_16x16x32_bf16 v[64:67], v[202:205], v[156:159], v[64:67]
	ds_read_b128 v[156:159], v146 offset:12288
	v_add_u32_e32 v146, v155, v152
	s_waitcnt lgkmcnt(2)
	v_mfma_f32_16x16x32_bf16 v[60:63], v[190:193], v[160:163], v[60:63]
	v_mfma_f32_16x16x32_bf16 v[56:59], v[194:197], v[160:163], v[56:59]
	v_mfma_f32_16x16x32_bf16 v[52:55], v[198:201], v[160:163], v[52:55]
	v_mfma_f32_16x16x32_bf16 v[48:51], v[202:205], v[160:163], v[48:51]
	ds_read_b128 v[160:163], v146
	s_waitcnt lgkmcnt(2)
	v_mfma_f32_16x16x32_bf16 v[44:47], v[190:193], v[136:139], v[44:47]
	v_mfma_f32_16x16x32_bf16 v[40:43], v[194:197], v[136:139], v[40:43]
	v_mfma_f32_16x16x32_bf16 v[36:39], v[198:201], v[136:139], v[36:39]
	v_mfma_f32_16x16x32_bf16 v[32:35], v[202:205], v[136:139], v[32:35]
	s_waitcnt lgkmcnt(1)
	v_mfma_f32_16x16x32_bf16 v[24:27], v[194:197], v[156:159], v[24:27]
	v_mfma_f32_16x16x32_bf16 v[20:23], v[198:201], v[156:159], v[20:23]
	v_mfma_f32_16x16x32_bf16 v[16:19], v[202:205], v[156:159], v[16:19]
	s_waitcnt lgkmcnt(0)
	v_mfma_f32_16x16x32_bf16 v[12:15], v[190:193], v[160:163], v[12:15]
	v_mfma_f32_16x16x32_bf16 v[8:11], v[194:197], v[160:163], v[8:11]
	v_mfma_f32_16x16x32_bf16 v[4:7], v[198:201], v[160:163], v[4:7]
	v_mfma_f32_16x16x32_bf16 v[0:3], v[202:205], v[160:163], v[0:3]
	v_mfma_f32_16x16x32_bf16 v[28:31], v[190:193], v[156:159], v[28:31]
	v_mov_b32_e32 v136, v141
	v_mov_b32_e32 v137, v140
	s_waitcnt vmcnt(0)
	s_barrier
	v_cvt_pk_bf16_f32 v124, v124, v125
	v_and_or_b32 v138, v136, 15, v143
	v_ashrrev_i32_e32 v139, 1, v136
	v_mul_lo_u32 v138, v138, s3
	v_and_b32_e32 v139, -8, v139
	v_add3_u32 v138, v154, v138, v139
	v_cvt_pk_bf16_f32 v125, v126, v127
	v_cvt_pk_bf16_f32 v120, v120, v121
	v_cvt_pk_bf16_f32 v121, v122, v123
	v_cvt_pk_bf16_f32 v116, v116, v117
	v_cvt_pk_bf16_f32 v117, v118, v119
	v_cvt_pk_bf16_f32 v112, v112, v113
	v_cvt_pk_bf16_f32 v113, v114, v115
	v_cvt_pk_bf16_f32 v108, v108, v109
	v_cvt_pk_bf16_f32 v109, v110, v111
	v_cvt_pk_bf16_f32 v104, v104, v105
	v_cvt_pk_bf16_f32 v105, v106, v107
	v_add_u32_e32 v106, 0x2000, v138
	v_cvt_pk_bf16_f32 v100, v100, v101
	v_cvt_pk_bf16_f32 v101, v102, v103
	v_cvt_pk_bf16_f32 v96, v96, v97
	v_cvt_pk_bf16_f32 v97, v98, v99
	v_cvt_pk_bf16_f32 v92, v92, v93
	v_cvt_pk_bf16_f32 v93, v94, v95
	v_cvt_pk_bf16_f32 v88, v88, v89
	v_cvt_pk_bf16_f32 v89, v90, v91
	v_add_u32_e32 v90, 0x4000, v138
	v_cvt_pk_bf16_f32 v84, v84, v85
	v_cvt_pk_bf16_f32 v85, v86, v87
	v_cvt_pk_bf16_f32 v80, v80, v81
	v_cvt_pk_bf16_f32 v81, v82, v83
	v_cvt_pk_bf16_f32 v76, v76, v77
	v_cvt_pk_bf16_f32 v77, v78, v79
	v_cvt_pk_bf16_f32 v72, v72, v73
	v_cvt_pk_bf16_f32 v73, v74, v75
	v_add_u32_e32 v74, 0x6000, v138
	v_cvt_pk_bf16_f32 v68, v68, v69
	v_cvt_pk_bf16_f32 v69, v70, v71
	v_cvt_pk_bf16_f32 v64, v64, v65
	v_cvt_pk_bf16_f32 v65, v66, v67
	v_cvt_pk_bf16_f32 v60, v60, v61
	v_cvt_pk_bf16_f32 v61, v62, v63
	v_cvt_pk_bf16_f32 v56, v56, v57
	v_cvt_pk_bf16_f32 v57, v58, v59
	v_add_u32_e32 v58, 0x8000, v138
	v_cvt_pk_bf16_f32 v52, v52, v53
	v_cvt_pk_bf16_f32 v53, v54, v55
	v_cvt_pk_bf16_f32 v48, v48, v49
	v_cvt_pk_bf16_f32 v49, v50, v51
	v_cvt_pk_bf16_f32 v44, v44, v45
	v_cvt_pk_bf16_f32 v45, v46, v47
	v_cvt_pk_bf16_f32 v40, v40, v41
; DI unsigned pk2(float a, float b) { f32x2 v = {a, b}; bf16x2_t r = __builtin_convertvector(v, bf16x2_t); return __builtin_bit_cast(unsigned, r); }
; DI float bflo(unsigned w) { return __uint_as_float(w << 16); }
; DI float bfhi(unsigned w) { return __uint_as_float(w & 0xffff0000u); }
;     DI void operator()(gacc_t& acc, int pm, int pn, char* lds, int tid, int wr, int wc, int lane) const {
;     ...
;             for (int n = 0; n < 4; ++n) { u32x2 w; w.x = pk2(acc[m][n][0], acc[m][n][1]); w.y = pk2(acc[m][n][2], acc[m][n][3]); *(u32x2*)(lbase + m * 16 * 528 + n * 32) = w; }
;         __builtin_amdgcn_sched_barrier(0);
;         __syncthreads();
;         __builtin_amdgcn_sched_barrier(0);
;         const int g = lane >> 5, j32 = lane & 31;
; #pragma unroll
;         for (int ib = 0; ib < 4; ++ib) {
;             __builtin_amdgcn_sched_barrier(0);
;             u32x4 xv[4];
; #pragma unroll
;             for (int u = 0; u < 4; ++u) {
;                 const long row = (long)pm * 256 + (ib * 4 + u) * 16 + wid * 2 + g;
;                 xv[u] = *(const u32x4*)(xold + row * 1024 + pn * 256 + j32 * 8);
;             }
; #pragma unroll
;             for (int u = 0; u < 4; ++u) {
;                 const int rloc = (ib * 4 + u) * 16 + wid * 2 + g;
;                 const long row = (long)pm * 256 + rloc;
;                 const u32x4 a = *(const u32x4*)(lds + rloc * 528 + j32 * 16);
;                 u32x4 w; float ss = 0.f;
; #pragma unroll
;                 for (int e = 0; e < 4; ++e) {
;                     w[e] = pk2(bflo(xv[u][e]) + bflo(a[e]), bfhi(xv[u][e]) + bfhi(a[e]));
;                     const float b0 = bflo(w[e]), b1 = bfhi(w[e]);
;                     ss += b0 * b0 + b1 * b1;
;                 }
;                 *(u32x4*)(xnew + row * 1024 + pn * 256 + j32 * 8) = w;
; #pragma unroll
;                 for (int o = 1; o < 32; o <<= 1) ss += __shfl_xor(ss, o);
;                 if (j32 == 0) ssq[row * 4 + pn] = ss;
	v_cvt_pk_bf16_f32 v41, v42, v43
	v_add_u32_e32 v42, 0xa000, v138
	v_cvt_pk_bf16_f32 v36, v36, v37
	v_cvt_pk_bf16_f32 v37, v38, v39
	v_cvt_pk_bf16_f32 v32, v32, v33
	v_cvt_pk_bf16_f32 v33, v34, v35
	v_cvt_pk_bf16_f32 v28, v28, v29
	v_cvt_pk_bf16_f32 v29, v30, v31
	v_cvt_pk_bf16_f32 v24, v24, v25
	v_cvt_pk_bf16_f32 v25, v26, v27
	v_add_u32_e32 v26, 0xc000, v138
	v_cvt_pk_bf16_f32 v20, v20, v21
	v_cvt_pk_bf16_f32 v21, v22, v23
	v_cvt_pk_bf16_f32 v16, v16, v17
	v_cvt_pk_bf16_f32 v17, v18, v19
	v_cvt_pk_bf16_f32 v12, v12, v13
	v_cvt_pk_bf16_f32 v13, v14, v15
	v_cvt_pk_bf16_f32 v8, v8, v9
	v_cvt_pk_bf16_f32 v9, v10, v11
	v_add_u32_e32 v10, 0xe000, v138
	v_cvt_pk_bf16_f32 v4, v4, v5
	v_cvt_pk_bf16_f32 v5, v6, v7
	v_cvt_pk_bf16_f32 v0, v0, v1
	v_cvt_pk_bf16_f32 v1, v2, v3
	ds_write2_b64 v138, v[124:125], v[120:121] offset1:4
	ds_write2_b64 v138, v[116:117], v[112:113] offset0:8 offset1:12
	ds_write2_b64 v106, v[108:109], v[104:105] offset0:32 offset1:36
	ds_write2_b64 v106, v[100:101], v[96:97] offset0:40 offset1:44
	ds_write2_b64 v90, v[92:93], v[88:89] offset0:64 offset1:68
	ds_write2_b64 v90, v[84:85], v[80:81] offset0:72 offset1:76
	ds_write2_b64 v74, v[76:77], v[72:73] offset0:96 offset1:100
	ds_write2_b64 v74, v[68:69], v[64:65] offset0:104 offset1:108
	ds_write2_b64 v58, v[60:61], v[56:57] offset0:128 offset1:132
	ds_write2_b64 v58, v[52:53], v[48:49] offset0:136 offset1:140
	ds_write2_b64 v42, v[44:45], v[40:41] offset0:160 offset1:164
	ds_write2_b64 v42, v[36:37], v[32:33] offset0:168 offset1:172
	ds_write2_b64 v26, v[28:29], v[24:25] offset0:192 offset1:196
	ds_write2_b64 v26, v[20:21], v[16:17] offset0:200 offset1:204
	ds_write2_b64 v10, v[12:13], v[8:9] offset0:224 offset1:228
	ds_write2_b64 v10, v[4:5], v[0:1] offset0:232 offset1:236
	s_waitcnt lgkmcnt(0)
	s_barrier
	v_ashrrev_i32_e32 v0, 5, v136
	v_ashrrev_i32_e32 v1, 5, v137
	v_and_b32_e32 v23, 31, v136
	v_and_b32_e32 v2, -2, v1
	v_ashrrev_i32_e32 v1, 31, v0
	v_ashrrev_i32_e32 v3, 31, v2
	v_lshl_add_u64 v[4:5], s[16:17], 0, v[0:1]
	s_lshl_b32 s18, s6, 8
	v_lshlrev_b32_e32 v146, 4, v23
	v_lshl_add_u64 v[4:5], v[4:5], 0, v[2:3]
	s_ashr_i32 s19, s18, 31
	v_add_u32_e32 v16, v2, v0
	v_add_u32_e32 v22, 0, v146
	v_cmp_eq_u32_e64 s[4:5], 0, v23
	v_cmp_eq_u32_e64 s[98:99], 16, v23
	s_lshl_b64 s[20:21], s[18:19], 1
	s_add_u32 s30, s10, s20
	s_addc_u32 s31, s11, s21
	v_lshl_add_u64 v[0:1], s[30:31], 0, v[146:147]
	v_lshlrev_b64 v[2:3], 11, v[4:5]
	v_lshl_add_u64 v[18:19], v[0:1], 0, v[2:3]
	flat_load_dwordx4 v[12:15], v[18:19]
	v_add_co_u32_e32 v0, vcc, s49, v18
	v_mul_lo_u32 v24, v16, s3
	s_nop 0
	v_addc_co_u32_e32 v1, vcc, 0, v19, vcc
	flat_load_dwordx4 v[8:11], v[0:1]
	v_add_co_u32_e32 v0, vcc, s48, v18
	v_add_u32_e32 v20, v22, v24
	s_nop 0
	v_addc_co_u32_e32 v1, vcc, 0, v19, vcc
	flat_load_dwordx4 v[4:7], v[0:1]
	v_add_co_u32_e32 v0, vcc, s47, v18
	ds_read_b128 v[26:29], v20
	s_nop 0
	v_addc_co_u32_e32 v1, vcc, 0, v19, vcc
	flat_load_dwordx4 v[0:3], v[0:1]
	v_ashrrev_i32_e32 v17, 31, v16
	s_waitcnt lgkmcnt(0)
	v_lshlrev_b32_e32 v30, 16, v26
	v_and_b32_e32 v31, 0xffff0000, v26
	v_lshlrev_b32_e32 v26, 16, v27
	v_and_b32_e32 v27, 0xffff0000, v27
	s_waitcnt vmcnt(0)
	v_lshlrev_b32_e32 v20, 16, v12
	v_and_b32_e32 v21, 0xffff0000, v12
	v_pk_add_f32 v[20:21], v[20:21], v[30:31]
	s_nop 0
	v_cvt_pk_bf16_f32 v12, v20, v21
	v_and_b32_e32 v21, 0xffff0000, v12
	v_lshlrev_b32_e32 v20, 16, v12
	v_mul_f32_e32 v25, v21, v21
	v_fmac_f32_e32 v25, v20, v20
	v_lshlrev_b32_e32 v20, 16, v13
	v_and_b32_e32 v21, 0xffff0000, v13
	v_pk_add_f32 v[20:21], v[20:21], v[26:27]
	v_lshlrev_b32_e32 v26, 16, v28
	v_cvt_pk_bf16_f32 v13, v20, v21
	v_and_b32_e32 v21, 0xffff0000, v13
	v_lshlrev_b32_e32 v20, 16, v13
	v_mul_f32_e32 v21, v21, v21
	v_fmac_f32_e32 v21, v20, v20
	v_add_f32_e32 v25, v25, v21
	v_lshlrev_b32_e32 v20, 16, v14
	v_and_b32_e32 v21, 0xffff0000, v14
	v_and_b32_e32 v27, 0xffff0000, v28
	v_pk_add_f32 v[20:21], v[20:21], v[26:27]
	v_lshlrev_b32_e32 v26, 16, v29
	v_cvt_pk_bf16_f32 v14, v20, v21
	v_and_b32_e32 v21, 0xffff0000, v14
	v_lshlrev_b32_e32 v20, 16, v14
	v_mul_f32_e32 v21, v21, v21
	v_fmac_f32_e32 v21, v20, v20
	v_add_f32_e32 v25, v21, v25
	v_lshlrev_b32_e32 v20, 16, v15
	v_and_b32_e32 v21, 0xffff0000, v15
	v_and_b32_e32 v27, 0xffff0000, v29
	v_pk_add_f32 v[20:21], v[20:21], v[26:27]
	s_nop 0
	v_cvt_pk_bf16_f32 v15, v20, v21
	v_and_b32_e32 v21, 0xffff0000, v15
	v_lshlrev_b32_e32 v20, 16, v15
	v_mul_f32_e32 v21, v21, v21
	v_fmac_f32_e32 v21, v20, v20
	v_add_f32_e32 v25, v21, v25
	v_lshl_add_u64 v[20:21], s[16:17], 0, v[16:17]
	v_lshlrev_b64 v[26:27], 11, v[20:21]
	v_lshl_add_u64 v[26:27], s[68:69], 0, v[26:27]
	v_lshl_add_u64 v[26:27], v[26:27], 0, s[20:21]
	v_lshl_add_u64 v[26:27], v[26:27], 0, v[146:147]
	flat_store_dwordx4 v[26:27], v[12:15]
	s_nop 1
	v_add_f32_dpp v86, v25, v25 quad_perm:[1,0,3,2] row_mask:0xf bank_mask:0xf
	s_nop 1
	v_add_f32_dpp v86, v86, v86 quad_perm:[2,3,0,1] row_mask:0xf bank_mask:0xf
	s_nop 1
	v_add_f32_dpp v86, v86, v86 row_half_mirror row_mask:0xf bank_mask:0xf
	s_nop 1
	v_add_f32_dpp v86, v86, v86 row_mirror row_mask:0xf bank_mask:0xf
	s_nop 1
	v_add_f32_dpp v86, v86, v86 row_bcast:15 row_mask:0xa bank_mask:0xf
	s_waitcnt lgkmcnt(0)
	s_waitcnt lgkmcnt(0)
	s_waitcnt lgkmcnt(0)
	s_waitcnt lgkmcnt(0)
	s_and_saveexec_b64 s[20:21], s[98:99]
	s_cbranch_execz .LBB0_284
	v_lshl_add_u64 v[14:15], v[20:21], 4, s[78:79]
	v_lshl_add_u64 v[14:15], s[6:7], 2, v[14:15]
	s_waitcnt lgkmcnt(0)
	v_mov_b32_e32 v12, v86
	flat_store_dword v[14:15], v12

; #define MFMA16(a, b, c) __builtin_amdgcn_mfma_f32_16x16x32_bf16((a), (b), (c), 0, 0, 0)
; DI bf16x8 ldfrag(const char* lds, int row, int chunk) { return *(const bf16x8*)(lds + swz(row, chunk)); }
; template <bool RSTD, bool SWAP>
; DI void gemm_tile(gacc_t& acc, const bf16_t* __restrict__ A, int lda, const bf16_t* __restrict__ Bt, int ldb, int K,
;                   char* lds, int tid, int wr, int wc, int lane, const float* ssq_row) {
;     ...
;     for (int kt = 0; kt < nk; ++kt) {
;         const char* cur = lds + (kt & 1) * 65536;
;         if (kt + 1 < nk) GEMM_ISSUE(kt + 1, (kt + 1) & 1);
;         bf16x8 bfr[2][4], afr[3];
; #pragma unroll
;         for (int n = 0; n < 4; ++n) bfr[0][n] = ldfrag(cur + 32768, wc * 64 + n * 16 + fr, fq);
;         afr[0] = ldfrag(cur, wr * 128 + fr, fq);
;         afr[1] = ldfrag(cur, wr * 128 + 16 + fr, fq);
; #pragma unroll
;         for (int idx = 0; idx < 16; ++idx) {
;             const int ks = idx >> 3, m = idx & 7;
;             if (idx < 14) afr[(idx + 2) % 3] = ldfrag(cur, wr * 128 + ((idx + 2) & 7) * 16 + fr, ((idx + 2) >> 3) * 4 + fq);
;             if (ks == 0 && m >= 2 && m < 6) bfr[1][m - 2] = ldfrag(cur + 32768, wc * 64 + (m - 2) * 16 + fr, 4 + fq);
; #pragma unroll
;             for (int n = 0; n < 4; ++n) acc[m][n] = SWAP ? MFMA16(bfr[ks][n], afr[idx % 3], acc[m][n]) : MFMA16(afr[idx % 3], bfr[ks][n], acc[m][n]);
;         }
.LBB0_373:
	s_and_b32 s20, s18, 0x10000
	v_lshl_add_u64 v[162:163], v[138:139], 0, s[6:7]
	s_add_i32 s20, s22, s20
	v_lshl_add_u64 v[164:165], v[136:137], 0, s[6:7]
	v_lshl_add_u64 v[166:167], v[162:163], 0, s[94:95]
	s_add_i32 s21, s20, 0x8000
	s_mov_b32 m0, s20
	v_lshl_add_u64 v[172:173], v[164:165], 0, s[14:15]
	global_load_lds_dwordx4 v[166:167], off
	v_mfma_f32_16x16x32_bf16 v[60:63], v[210:213], v[236:239], v[60:63]
	s_mov_b32 m0, s21
	v_lshl_add_u64 v[174:175], v[162:163], 0, s[96:97]
	global_load_lds_dwordx4 v[172:173], off
	v_mfma_f32_16x16x32_bf16 v[56:59], v[214:217], v[236:239], v[56:59]
	s_add_i32 m0, s20, 0x2000
	v_lshl_add_u64 v[176:177], v[164:165], 0, s[72:73]
	global_load_lds_dwordx4 v[174:175], off
	v_mfma_f32_16x16x32_bf16 v[52:55], v[218:221], v[236:239], v[52:55]
	s_add_i32 m0, s20, 0xa000
	v_lshl_add_u64 v[178:179], v[162:163], 0, s[80:81]
	global_load_lds_dwordx4 v[176:177], off
	v_mfma_f32_16x16x32_bf16 v[48:51], v[222:225], v[236:239], v[48:51]
	s_add_i32 m0, s20, 0x4000
	v_lshl_add_u64 v[180:181], v[164:165], 0, s[76:77]
	global_load_lds_dwordx4 v[178:179], off
	v_mfma_f32_16x16x32_bf16 v[44:47], v[210:213], v[240:243], v[44:47]
	s_add_i32 m0, s20, 0xc000
	v_lshl_add_u64 v[162:163], v[162:163], 0, s[82:83]
	global_load_lds_dwordx4 v[180:181], off
	v_mfma_f32_16x16x32_bf16 v[40:43], v[214:217], v[240:243], v[40:43]
	s_add_i32 m0, s20, 0x6000
	v_lshl_add_u64 v[164:165], v[164:165], 0, s[0:1]
	global_load_lds_dwordx4 v[162:163], off
	v_mfma_f32_16x16x32_bf16 v[36:39], v[218:221], v[240:243], v[36:39]
	s_add_i32 m0, s20, 0xe000
	s_add_i32 s19, s18, 0xffff0000
	global_load_lds_dwordx4 v[164:165], off
	v_mfma_f32_16x16x32_bf16 v[32:35], v[222:225], v[240:243], v[32:35]
	s_and_b32 s19, s19, 0x10000
	s_add_i32 s19, s19, 0
	v_add_u32_e32 v146, s19, v144
	v_add3_u32 v166, v146, v150, v151
	ds_read_b128 v[162:165], v166 offset:32768
	ds_read_b128 v[186:189], v166 offset:34816
	ds_read_b128 v[194:197], v166 offset:36864
	ds_read_b128 v[198:201], v166 offset:38912
	v_add_u32_e32 v167, v146, v148
	ds_read_b128 v[190:193], v167
	ds_read_b128 v[202:205], v167 offset:2048
	v_add_u32_e32 v166, v146, v152
	ds_read_b128 v[206:209], v167 offset:4096
	v_mfma_f32_16x16x32_bf16 v[28:31], v[210:213], v[244:247], v[28:31]
	v_mfma_f32_16x16x32_bf16 v[24:27], v[214:217], v[244:247], v[24:27]
	v_mfma_f32_16x16x32_bf16 v[20:23], v[218:221], v[244:247], v[20:23]
	v_mfma_f32_16x16x32_bf16 v[16:19], v[222:225], v[244:247], v[16:19]
	v_mfma_f32_16x16x32_bf16 v[12:15], v[210:213], v[248:251], v[12:15]
	v_mfma_f32_16x16x32_bf16 v[8:11], v[214:217], v[248:251], v[8:11]
	v_mfma_f32_16x16x32_bf16 v[4:7], v[218:221], v[248:251], v[4:7]
	v_mfma_f32_16x16x32_bf16 v[0:3], v[222:225], v[248:251], v[0:3]
	s_waitcnt lgkmcnt(2)
	v_mfma_f32_16x16x32_bf16 v[124:127], v[162:165], v[190:193], v[124:127]
	v_add_u32_e32 v146, v146, v154
	v_mfma_f32_16x16x32_bf16 v[120:123], v[186:189], v[190:193], v[120:123]
	v_mfma_f32_16x16x32_bf16 v[116:119], v[194:197], v[190:193], v[116:119]
	v_mfma_f32_16x16x32_bf16 v[112:115], v[198:201], v[190:193], v[112:115]
	ds_read_b128 v[190:193], v166
	v_add_u32_e32 v166, s19, v149
	v_add_u32_e32 v172, v166, v153
	s_waitcnt lgkmcnt(2)
	v_mfma_f32_16x16x32_bf16 v[108:111], v[162:165], v[202:205], v[108:111]
	v_mfma_f32_16x16x32_bf16 v[104:107], v[186:189], v[202:205], v[104:107]
	v_mfma_f32_16x16x32_bf16 v[100:103], v[194:197], v[202:205], v[100:103]
	v_mfma_f32_16x16x32_bf16 v[96:99], v[198:201], v[202:205], v[96:99]
	ds_read_b128 v[202:205], v167 offset:8192
	ds_read_b128 v[210:213], v172 offset:32768
	s_waitcnt lgkmcnt(3)
	v_mfma_f32_16x16x32_bf16 v[92:95], v[162:165], v[206:209], v[92:95]
	v_mfma_f32_16x16x32_bf16 v[88:91], v[186:189], v[206:209], v[88:91]
	v_mfma_f32_16x16x32_bf16 v[84:87], v[194:197], v[206:209], v[84:87]
	v_mfma_f32_16x16x32_bf16 v[80:83], v[198:201], v[206:209], v[80:83]
	ds_read_b128 v[206:209], v167 offset:10240
	ds_read_b128 v[214:217], v172 offset:34816
	s_waitcnt lgkmcnt(4)
	v_mfma_f32_16x16x32_bf16 v[76:79], v[162:165], v[190:193], v[76:79]
	v_mfma_f32_16x16x32_bf16 v[72:75], v[186:189], v[190:193], v[72:75]
	v_mfma_f32_16x16x32_bf16 v[68:71], v[194:197], v[190:193], v[68:71]
	v_mfma_f32_16x16x32_bf16 v[64:67], v[198:201], v[190:193], v[64:67]
	ds_read_b128 v[190:193], v167 offset:12288
	v_add_u32_e32 v167, v166, v155
	ds_read_b128 v[218:221], v172 offset:36864
	s_waitcnt lgkmcnt(5)
	v_mfma_f32_16x16x32_bf16 v[60:63], v[162:165], v[202:205], v[60:63]
	v_mfma_f32_16x16x32_bf16 v[56:59], v[186:189], v[202:205], v[56:59]
	v_mfma_f32_16x16x32_bf16 v[52:55], v[194:197], v[202:205], v[52:55]
	v_mfma_f32_16x16x32_bf16 v[48:51], v[198:201], v[202:205], v[48:51]
	ds_read_b128 v[222:225], v167 offset:38912
	ds_read_b128 v[202:205], v146
	v_add_u32_e32 v146, v166, v148
	s_waitcnt lgkmcnt(5)
	v_mfma_f32_16x16x32_bf16 v[44:47], v[162:165], v[206:209], v[44:47]
	v_add_u32_e32 v167, v166, v152
	v_mfma_f32_16x16x32_bf16 v[40:43], v[186:189], v[206:209], v[40:43]
	v_mfma_f32_16x16x32_bf16 v[36:39], v[194:197], v[206:209], v[36:39]
	v_mfma_f32_16x16x32_bf16 v[32:35], v[198:201], v[206:209], v[32:35]
	ds_read_b128 v[206:209], v146
	s_waitcnt lgkmcnt(4)
	v_mfma_f32_16x16x32_bf16 v[28:31], v[162:165], v[190:193], v[28:31]
	v_mfma_f32_16x16x32_bf16 v[24:27], v[186:189], v[190:193], v[24:27]
	v_mfma_f32_16x16x32_bf16 v[20:23], v[194:197], v[190:193], v[20:23]
	v_mfma_f32_16x16x32_bf16 v[16:19], v[198:201], v[190:193], v[16:19]
	ds_read_b128 v[190:193], v146 offset:2048
	s_waitcnt lgkmcnt(2)
; #define MFMA16(a, b, c) __builtin_amdgcn_mfma_f32_16x16x32_bf16((a), (b), (c), 0, 0, 0)
; DI bf16x8 ldfrag(const char* lds, int row, int chunk) { return *(const bf16x8*)(lds + swz(row, chunk)); }
; #define GEMM_SG1() do { __builtin_amdgcn_sched_group_barrier(0x100, 1, 0); __builtin_amdgcn_sched_group_barrier(0x008, 4, 0); } while (0)
; #define GEMM_SG2() do { __builtin_amdgcn_sched_group_barrier(0x100, 2, 0); __builtin_amdgcn_sched_group_barrier(0x008, 4, 0); } while (0)
; template <bool RSTD, bool SWAP>
; DI void gemm_tile(gacc_t& acc, const bf16_t* __restrict__ A, int lda, const bf16_t* __restrict__ Bt, int ldb, int K,
;                   char* lds, int tid, int wr, int wc, int lane, const float* ssq_row) {
;     ...
;     for (int kt = 0; kt < nk; ++kt) {
;         const char* cur = lds + (kt & 1) * 65536;
;         if (kt + 1 < nk) GEMM_ISSUE(kt + 1, (kt + 1) & 1);
;         bf16x8 bfr[2][4], afr[3];
; #pragma unroll
;         for (int n = 0; n < 4; ++n) bfr[0][n] = ldfrag(cur + 32768, wc * 64 + n * 16 + fr, fq);
;         afr[0] = ldfrag(cur, wr * 128 + fr, fq);
;         afr[1] = ldfrag(cur, wr * 128 + 16 + fr, fq);
; #pragma unroll
;         for (int idx = 0; idx < 16; ++idx) {
;             const int ks = idx >> 3, m = idx & 7;
;             if (idx < 14) afr[(idx + 2) % 3] = ldfrag(cur, wr * 128 + ((idx + 2) & 7) * 16 + fr, ((idx + 2) >> 3) * 4 + fq);
;             if (ks == 0 && m >= 2 && m < 6) bfr[1][m - 2] = ldfrag(cur + 32768, wc * 64 + (m - 2) * 16 + fr, 4 + fq);
; #pragma unroll
;             for (int n = 0; n < 4; ++n) acc[m][n] = SWAP ? MFMA16(bfr[ks][n], afr[idx % 3], acc[m][n]) : MFMA16(afr[idx % 3], bfr[ks][n], acc[m][n]);
;         }
;         __builtin_amdgcn_sched_group_barrier(0x100, 6, 0);
;     ...
;         GEMM_SG1(); GEMM_SG1(); GEMM_SG2(); GEMM_SG2(); GEMM_SG2(); GEMM_SG2(); GEMM_SG1(); GEMM_SG1();
;         GEMM_SG1(); GEMM_SG1(); GEMM_SG1(); GEMM_SG1(); GEMM_SG1(); GEMM_SG1();
;         __builtin_amdgcn_sched_group_barrier(0x008, 8, 0);
;         __builtin_amdgcn_sched_barrier(0);
;         asm volatile("s_waitcnt vmcnt(0)" ::: "memory");
;         __syncthreads();
	v_mfma_f32_16x16x32_bf16 v[12:15], v[162:165], v[202:205], v[12:15]
	v_mfma_f32_16x16x32_bf16 v[8:11], v[186:189], v[202:205], v[8:11]
	v_mfma_f32_16x16x32_bf16 v[4:7], v[194:197], v[202:205], v[4:7]
	v_mfma_f32_16x16x32_bf16 v[0:3], v[198:201], v[202:205], v[0:3]
	ds_read_b128 v[162:165], v146 offset:4096
	s_waitcnt lgkmcnt(2)
	v_mfma_f32_16x16x32_bf16 v[124:127], v[210:213], v[206:209], v[124:127]
	v_mfma_f32_16x16x32_bf16 v[120:123], v[214:217], v[206:209], v[120:123]
	v_mfma_f32_16x16x32_bf16 v[116:119], v[218:221], v[206:209], v[116:119]
	v_mfma_f32_16x16x32_bf16 v[112:115], v[222:225], v[206:209], v[112:115]
	ds_read_b128 v[186:189], v167
	s_waitcnt lgkmcnt(2)
	v_mfma_f32_16x16x32_bf16 v[108:111], v[210:213], v[190:193], v[108:111]
	v_mfma_f32_16x16x32_bf16 v[104:107], v[214:217], v[190:193], v[104:107]
	v_mfma_f32_16x16x32_bf16 v[100:103], v[218:221], v[190:193], v[100:103]
	v_mfma_f32_16x16x32_bf16 v[96:99], v[222:225], v[190:193], v[96:99]
	ds_read_b128 v[236:239], v146 offset:8192
	s_waitcnt lgkmcnt(2)
	v_mfma_f32_16x16x32_bf16 v[92:95], v[210:213], v[162:165], v[92:95]
	v_mfma_f32_16x16x32_bf16 v[88:91], v[214:217], v[162:165], v[88:91]
	v_mfma_f32_16x16x32_bf16 v[84:87], v[218:221], v[162:165], v[84:87]
	v_mfma_f32_16x16x32_bf16 v[80:83], v[222:225], v[162:165], v[80:83]
	ds_read_b128 v[240:243], v146 offset:10240
	ds_read_b128 v[244:247], v146 offset:12288
	v_add_u32_e32 v146, v166, v154
	ds_read_b128 v[248:251], v146
	s_waitcnt lgkmcnt(4)
	v_mfma_f32_16x16x32_bf16 v[76:79], v[210:213], v[186:189], v[76:79]
	v_mfma_f32_16x16x32_bf16 v[72:75], v[214:217], v[186:189], v[72:75]
	v_mfma_f32_16x16x32_bf16 v[68:71], v[218:221], v[186:189], v[68:71]
	v_mfma_f32_16x16x32_bf16 v[64:67], v[222:225], v[186:189], v[64:67]
	s_waitcnt lgkmcnt(0)
	s_waitcnt vmcnt(0)
	s_add_u32 s6, s6, 0x80
	s_addc_u32 s7, s7, 0
	s_add_i32 s18, s18, 0x10000
	s_cmpk_lg_i32 s6, 0x780
	s_waitcnt vmcnt(0)
	s_barrier
	s_cbranch_scc1 .LBB0_373
	v_mfma_f32_16x16x32_bf16 v[60:63], v[210:213], v[236:239], v[60:63]
	v_mfma_f32_16x16x32_bf16 v[56:59], v[214:217], v[236:239], v[56:59]
	v_mfma_f32_16x16x32_bf16 v[52:55], v[218:221], v[236:239], v[52:55]
	v_mfma_f32_16x16x32_bf16 v[48:51], v[222:225], v[236:239], v[48:51]
	v_mfma_f32_16x16x32_bf16 v[44:47], v[210:213], v[240:243], v[44:47]
	v_mfma_f32_16x16x32_bf16 v[40:43], v[214:217], v[240:243], v[40:43]
	v_mfma_f32_16x16x32_bf16 v[36:39], v[218:221], v[240:243], v[36:39]
	v_mfma_f32_16x16x32_bf16 v[32:35], v[222:225], v[240:243], v[32:35]
	v_mfma_f32_16x16x32_bf16 v[28:31], v[210:213], v[244:247], v[28:31]
	v_mfma_f32_16x16x32_bf16 v[24:27], v[214:217], v[244:247], v[24:27]
	v_mfma_f32_16x16x32_bf16 v[20:23], v[218:221], v[244:247], v[20:23]
	v_mfma_f32_16x16x32_bf16 v[16:19], v[222:225], v[244:247], v[16:19]
	v_mfma_f32_16x16x32_bf16 v[12:15], v[210:213], v[248:251], v[12:15]
	v_mfma_f32_16x16x32_bf16 v[8:11], v[214:217], v[248:251], v[8:11]
	v_mfma_f32_16x16x32_bf16 v[4:7], v[218:221], v[248:251], v[4:7]
	v_mfma_f32_16x16x32_bf16 v[0:3], v[222:225], v[248:251], v[0:3]
	ds_read_b128 v[136:139], v161
	ds_read_b128 v[162:165], v161 offset:2048
	ds_read_b128 v[190:193], v161 offset:4096
	ds_read_b128 v[194:197], v161 offset:6144
	v_add_u32_e32 v146, v156, v148
	ds_read_b128 v[186:189], v146
	ds_read_b128 v[198:201], v146 offset:2048
	v_add_u32_e32 v166, v156, v152
	ds_read_b128 v[202:205], v146 offset:4096
	s_waitcnt lgkmcnt(2)
	v_mfma_f32_16x16x32_bf16 v[124:127], v[136:139], v[186:189], v[124:127]
	s_sext_i32_i8 s6, s16
	v_mfma_f32_16x16x32_bf16 v[120:123], v[162:165], v[186:189], v[120:123]
	v_mfma_f32_16x16x32_bf16 v[116:119], v[190:193], v[186:189], v[116:119]
	v_mfma_f32_16x16x32_bf16 v[112:115], v[194:197], v[186:189], v[112:115]
	ds_read_b128 v[186:189], v166
	v_add_u32_e32 v166, v157, v153
	s_waitcnt lgkmcnt(2)
	v_mfma_f32_16x16x32_bf16 v[108:111], v[136:139], v[198:201], v[108:111]
	v_mfma_f32_16x16x32_bf16 v[104:107], v[162:165], v[198:201], v[104:107]
	v_mfma_f32_16x16x32_bf16 v[100:103], v[190:193], v[198:201], v[100:103]
	v_mfma_f32_16x16x32_bf16 v[96:99], v[194:197], v[198:201], v[96:99]
	ds_read_b128 v[198:201], v146 offset:8192
	ds_read_b128 v[206:209], v166
	s_waitcnt lgkmcnt(3)
	v_mfma_f32_16x16x32_bf16 v[92:95], v[136:139], v[202:205], v[92:95]
	v_mfma_f32_16x16x32_bf16 v[88:91], v[162:165], v[202:205], v[88:91]
	v_mfma_f32_16x16x32_bf16 v[84:87], v[190:193], v[202:205], v[84:87]
	v_mfma_f32_16x16x32_bf16 v[80:83], v[194:197], v[202:205], v[80:83]
	ds_read_b128 v[202:205], v146 offset:10240
	ds_read_b128 v[210:213], v166 offset:2048
	s_waitcnt lgkmcnt(4)
	v_mfma_f32_16x16x32_bf16 v[76:79], v[136:139], v[186:189], v[76:79]
	v_mfma_f32_16x16x32_bf16 v[72:75], v[162:165], v[186:189], v[72:75]
	v_mfma_f32_16x16x32_bf16 v[68:71], v[190:193], v[186:189], v[68:71]
	v_mfma_f32_16x16x32_bf16 v[64:67], v[194:197], v[186:189], v[64:67]
	ds_read_b128 v[186:189], v146 offset:12288
	v_add_u32_e32 v146, v156, v154
	ds_read_b128 v[214:217], v166 offset:4096
	s_waitcnt lgkmcnt(5)
	v_mfma_f32_16x16x32_bf16 v[60:63], v[136:139], v[198:201], v[60:63]
	v_mfma_f32_16x16x32_bf16 v[56:59], v[162:165], v[198:201], v[56:59]
	v_mfma_f32_16x16x32_bf16 v[52:55], v[190:193], v[198:201], v[52:55]
	v_mfma_f32_16x16x32_bf16 v[48:51], v[194:197], v[198:201], v[48:51]
	ds_read_b128 v[198:201], v146
	v_add_u32_e32 v146, v157, v155
	ds_read_b128 v[218:221], v146 offset:6144
	v_add_u32_e32 v146, v158, v148
	s_waitcnt lgkmcnt(5)
	v_mfma_f32_16x16x32_bf16 v[44:47], v[136:139], v[202:205], v[44:47]
	v_mfma_f32_16x16x32_bf16 v[40:43], v[162:165], v[202:205], v[40:43]
	v_mfma_f32_16x16x32_bf16 v[36:39], v[190:193], v[202:205], v[36:39]
	v_mfma_f32_16x16x32_bf16 v[32:35], v[194:197], v[202:205], v[32:35]
	ds_read_b128 v[202:205], v146
	s_waitcnt lgkmcnt(4)
; #define MFMA16(a, b, c) __builtin_amdgcn_mfma_f32_16x16x32_bf16((a), (b), (c), 0, 0, 0)
; DI bf16x8 ldfrag(const char* lds, int row, int chunk) { return *(const bf16x8*)(lds + swz(row, chunk)); }
; template <bool RSTD, bool SWAP>
; DI void gemm_tile(gacc_t& acc, const bf16_t* __restrict__ A, int lda, const bf16_t* __restrict__ Bt, int ldb, int K,
;                   char* lds, int tid, int wr, int wc, int lane, const float* ssq_row) {
;     ...
;         for (int idx = 0; idx < 16; ++idx) {
;             const int ks = idx >> 3, m = idx & 7;
;             if (idx < 14) afr[(idx + 2) % 3] = ldfrag(cur, wr * 128 + ((idx + 2) & 7) * 16 + fr, ((idx + 2) >> 3) * 4 + fq);
;             if (ks == 0 && m >= 2 && m < 6) bfr[1][m - 2] = ldfrag(cur + 32768, wc * 64 + (m - 2) * 16 + fr, 4 + fq);
; #pragma unroll
;             for (int n = 0; n < 4; ++n) acc[m][n] = SWAP ? MFMA16(bfr[ks][n], afr[idx % 3], acc[m][n]) : MFMA16(afr[idx % 3], bfr[ks][n], acc[m][n]);
;         }
;     DI void operator()(gacc_t& acc, int pm, int pn, char* lds, int tid, int wr, int wc, int lane) const {
;     ...
;         const int fr = lane & 15, fq = lane >> 4;
;         char* lbase = lds + (wr * 128 + fr) * 528 + (wc * 64 + 4 * fq) * 2;
;         const float* rl = (const float*)(lds + RSTD_OFF) + wr * 128 + fr;
; #pragma unroll
;         for (int m = 0; m < 8; ++m) {
;             const float r = rl[m * 16];
; #pragma unroll
;             for (int n = 0; n < 4; ++n) {
;                 float g[4];
; #pragma unroll
;                 for (int j = 0; j < 4; ++j) {
;                     const float x = acc[m][n][j] * r;
;                     const float u = 0.7978845608028654f * (x + 0.044715f * x * x * x);
;                     const float e = __builtin_amdgcn_exp2f(-2.885390081777927f * u);
;                     g[j] = x * __builtin_amdgcn_rcpf(1.0f + e);
;                 }
	v_mfma_f32_16x16x32_bf16 v[28:31], v[136:139], v[186:189], v[28:31]
	v_mfma_f32_16x16x32_bf16 v[24:27], v[162:165], v[186:189], v[24:27]
	v_mfma_f32_16x16x32_bf16 v[20:23], v[190:193], v[186:189], v[20:23]
	v_mfma_f32_16x16x32_bf16 v[16:19], v[194:197], v[186:189], v[16:19]
	ds_read_b128 v[186:189], v146 offset:2048
	s_waitcnt lgkmcnt(3)
	v_mfma_f32_16x16x32_bf16 v[12:15], v[136:139], v[198:201], v[12:15]
	v_mfma_f32_16x16x32_bf16 v[8:11], v[162:165], v[198:201], v[8:11]
	v_mfma_f32_16x16x32_bf16 v[4:7], v[190:193], v[198:201], v[4:7]
	v_mfma_f32_16x16x32_bf16 v[0:3], v[194:197], v[198:201], v[0:3]
	ds_read_b128 v[136:139], v146 offset:4096
	s_waitcnt lgkmcnt(2)
	v_mfma_f32_16x16x32_bf16 v[162:165], v[206:209], v[202:205], v[124:127]
	s_nop 2
	v_add_u32_e32 v124, v158, v152
	v_mfma_f32_16x16x32_bf16 v[120:123], v[210:213], v[202:205], v[120:123]
	v_mfma_f32_16x16x32_bf16 v[116:119], v[214:217], v[202:205], v[116:119]
	v_mfma_f32_16x16x32_bf16 v[112:115], v[218:221], v[202:205], v[112:115]
	ds_read_b128 v[124:127], v124
	s_waitcnt lgkmcnt(2)
	v_mfma_f32_16x16x32_bf16 v[108:111], v[206:209], v[186:189], v[108:111]
	v_mfma_f32_16x16x32_bf16 v[104:107], v[210:213], v[186:189], v[104:107]
	v_mfma_f32_16x16x32_bf16 v[100:103], v[214:217], v[186:189], v[100:103]
	v_mfma_f32_16x16x32_bf16 v[96:99], v[218:221], v[186:189], v[96:99]
	ds_read_b128 v[186:189], v146 offset:8192
	s_waitcnt lgkmcnt(2)
	v_mfma_f32_16x16x32_bf16 v[92:95], v[206:209], v[136:139], v[92:95]
	v_mfma_f32_16x16x32_bf16 v[88:91], v[210:213], v[136:139], v[88:91]
	v_mfma_f32_16x16x32_bf16 v[84:87], v[214:217], v[136:139], v[84:87]
	v_mfma_f32_16x16x32_bf16 v[80:83], v[218:221], v[136:139], v[80:83]
	ds_read_b128 v[136:139], v146 offset:10240
	s_waitcnt lgkmcnt(2)
	v_mfma_f32_16x16x32_bf16 v[76:79], v[206:209], v[124:127], v[76:79]
	v_mfma_f32_16x16x32_bf16 v[72:75], v[210:213], v[124:127], v[72:75]
	v_mfma_f32_16x16x32_bf16 v[68:71], v[214:217], v[124:127], v[68:71]
	v_mfma_f32_16x16x32_bf16 v[64:67], v[218:221], v[124:127], v[64:67]
	ds_read_b128 v[124:127], v146 offset:12288
	v_add_u32_e32 v146, v158, v154
	s_waitcnt lgkmcnt(2)
	v_mfma_f32_16x16x32_bf16 v[60:63], v[206:209], v[186:189], v[60:63]
	v_mfma_f32_16x16x32_bf16 v[56:59], v[210:213], v[186:189], v[56:59]
	v_mfma_f32_16x16x32_bf16 v[52:55], v[214:217], v[186:189], v[52:55]
	v_mfma_f32_16x16x32_bf16 v[48:51], v[218:221], v[186:189], v[48:51]
	ds_read_b128 v[186:189], v146
	s_waitcnt lgkmcnt(2)
	v_mfma_f32_16x16x32_bf16 v[44:47], v[206:209], v[136:139], v[44:47]
	v_mfma_f32_16x16x32_bf16 v[40:43], v[210:213], v[136:139], v[40:43]
	v_mfma_f32_16x16x32_bf16 v[36:39], v[214:217], v[136:139], v[36:39]
	v_mfma_f32_16x16x32_bf16 v[32:35], v[218:221], v[136:139], v[32:35]
	s_waitcnt lgkmcnt(1)
	v_mfma_f32_16x16x32_bf16 v[28:31], v[206:209], v[124:127], v[28:31]
	v_mfma_f32_16x16x32_bf16 v[24:27], v[210:213], v[124:127], v[24:27]
	v_mfma_f32_16x16x32_bf16 v[20:23], v[214:217], v[124:127], v[20:23]
	v_mfma_f32_16x16x32_bf16 v[16:19], v[218:221], v[124:127], v[16:19]
	s_waitcnt lgkmcnt(0)
	v_mfma_f32_16x16x32_bf16 v[12:15], v[206:209], v[186:189], v[12:15]
	v_mfma_f32_16x16x32_bf16 v[8:11], v[210:213], v[186:189], v[8:11]
	v_mfma_f32_16x16x32_bf16 v[4:7], v[214:217], v[186:189], v[4:7]
	v_mfma_f32_16x16x32_bf16 v[0:3], v[218:221], v[186:189], v[0:3]
	v_mov_b32_e32 v124, v141
	v_mov_b32_e32 v125, v140
	s_waitcnt vmcnt(0)
	s_barrier
	s_nop 0
	v_and_b32_e32 v127, 15, v124
	v_or_b32_e32 v126, v127, v145
	v_ashrrev_i32_e32 v124, 1, v124
	v_mul_lo_u32 v126, v126, s3
	v_and_b32_e32 v124, -8, v124
	v_lshl_add_u32 v127, v127, 2, v160
	v_add3_u32 v126, v159, v126, v124
	ds_read_b32 v124, v127
	s_waitcnt lgkmcnt(0)
	v_pk_mul_f32 v[136:137], v[162:163], v[124:125] op_sel_hi:[1,0]
	s_nop 0
	v_mul_f32_e32 v138, 0x3d372713, v136
	v_mul_f32_e32 v139, 0x3d372713, v137
	v_mul_f32_e32 v138, v136, v138
	v_mul_f32_e32 v139, v137, v139
	v_fma_f32 v138, v136, v138, v136
	v_fma_f32 v139, v137, v139, v137
	v_mul_f32_e32 v138, 0x3f4c422a, v138
	v_mul_f32_e32 v139, 0x3f4c422a, v139
	v_mul_f32_e32 v138, 0xc038aa3b, v138
	v_mul_f32_e32 v139, 0xc038aa3b, v139
	v_exp_f32_e32 v138, v138
	v_exp_f32_e32 v139, v139
	v_pk_mul_f32 v[120:121], v[120:121], v[124:125] op_sel_hi:[1,0]
	v_pk_mul_f32 v[122:123], v[122:123], v[124:125] op_sel_hi:[1,0]
	v_add_f32_e32 v138, 1.0, v138
	v_add_f32_e32 v139, 1.0, v139
	v_rcp_f32_e32 v138, v138
	v_rcp_f32_e32 v139, v139
	v_pk_mul_f32 v[116:117], v[116:117], v[124:125] op_sel_hi:[1,0]
	v_pk_mul_f32 v[118:119], v[118:119], v[124:125] op_sel_hi:[1,0]
	v_pk_mul_f32 v[112:113], v[112:113], v[124:125] op_sel_hi:[1,0]
	v_pk_mul_f32 v[136:137], v[136:137], v[138:139]
	v_pk_mul_f32 v[138:139], v[164:165], v[124:125] op_sel_hi:[1,0]
	v_cvt_pk_bf16_f32 v136, v136, v137
	v_mul_f32_e32 v146, 0x3d372713, v138
	v_mul_f32_e32 v146, v138, v146
	v_fma_f32 v146, v138, v146, v138
	v_mul_f32_e32 v146, 0x3f4c422a, v146
	v_mul_f32_e32 v146, 0xc038aa3b, v146
	v_exp_f32_e32 v146, v146
	v_pk_mul_f32 v[114:115], v[114:115], v[124:125] op_sel_hi:[1,0]
	v_add_f32_e32 v146, 1.0, v146
	v_rcp_f32_e32 v162, v146
	v_mul_f32_e32 v146, 0x3d372713, v139
	v_mul_f32_e32 v146, v139, v146
	v_fma_f32 v146, v139, v146, v139
	v_mul_f32_e32 v146, 0x3f4c422a, v146
	v_mul_f32_e32 v146, 0xc038aa3b, v146
	v_exp_f32_e32 v146, v146
	s_nop 0
	v_add_f32_e32 v146, 1.0, v146
	v_rcp_f32_e32 v163, v146
	s_nop 0
	v_pk_mul_f32 v[138:139], v[138:139], v[162:163]
	s_nop 0
	v_cvt_pk_bf16_f32 v137, v138, v139
	v_mul_f32_e32 v138, 0x3d372713, v120
	v_mul_f32_e32 v139, 0x3d372713, v121
	v_mul_f32_e32 v138, v120, v138
	v_mul_f32_e32 v139, v121, v139
	v_fma_f32 v138, v120, v138, v120
; DI unsigned pk2(float a, float b) { f32x2 v = {a, b}; bf16x2_t r = __builtin_convertvector(v, bf16x2_t); return __builtin_bit_cast(unsigned, r); }
;     DI void operator()(gacc_t& acc, int pm, int pn, char* lds, int tid, int wr, int wc, int lane) const {
;     ...
;         for (int m = 0; m < 8; ++m) {
;             const float r = rl[m * 16];
; #pragma unroll
;             for (int n = 0; n < 4; ++n) {
;                 float g[4];
; #pragma unroll
;                 for (int j = 0; j < 4; ++j) {
;                     const float x = acc[m][n][j] * r;
;                     const float u = 0.7978845608028654f * (x + 0.044715f * x * x * x);
;                     const float e = __builtin_amdgcn_exp2f(-2.885390081777927f * u);
;                     g[j] = x * __builtin_amdgcn_rcpf(1.0f + e);
;                 }
;                 u32x2 w; w.x = pk2(g[0], g[1]); w.y = pk2(g[2], g[3]);
;                 *(u32x2*)(lbase + m * 16 * 528 + n * 32) = w;
;             }
	v_fma_f32 v139, v121, v139, v121
	v_mul_f32_e32 v138, 0x3f4c422a, v138
	v_mul_f32_e32 v139, 0x3f4c422a, v139
	v_mul_f32_e32 v138, 0xc038aa3b, v138
	v_mul_f32_e32 v139, 0xc038aa3b, v139
	v_exp_f32_e32 v138, v138
	v_exp_f32_e32 v139, v139
	v_add_f32_e32 v138, 1.0, v138
	v_add_f32_e32 v139, 1.0, v139
	v_rcp_f32_e32 v138, v138
	v_rcp_f32_e32 v139, v139
	s_nop 0
	v_pk_mul_f32 v[120:121], v[120:121], v[138:139]
	v_mul_f32_e32 v138, 0x3d372713, v122
	v_mul_f32_e32 v139, 0x3d372713, v123
	v_mul_f32_e32 v138, v122, v138
	v_mul_f32_e32 v139, v123, v139
	v_fma_f32 v138, v122, v138, v122
	v_fma_f32 v139, v123, v139, v123
	v_mul_f32_e32 v138, 0x3f4c422a, v138
	v_mul_f32_e32 v139, 0x3f4c422a, v139
	v_mul_f32_e32 v138, 0xc038aa3b, v138
	v_mul_f32_e32 v139, 0xc038aa3b, v139
	v_exp_f32_e32 v138, v138
	v_exp_f32_e32 v139, v139
	v_cvt_pk_bf16_f32 v120, v120, v121
	v_add_f32_e32 v138, 1.0, v138
	v_add_f32_e32 v139, 1.0, v139
	v_rcp_f32_e32 v138, v138
	v_rcp_f32_e32 v139, v139
	s_nop 0
	v_pk_mul_f32 v[122:123], v[122:123], v[138:139]
	s_nop 0
	v_cvt_pk_bf16_f32 v121, v122, v123
	ds_write2_b64 v126, v[136:137], v[120:121] offset1:4
	v_mul_f32_e32 v120, 0x3d372713, v116
	v_mul_f32_e32 v121, 0x3d372713, v117
	v_mul_f32_e32 v120, v116, v120
	v_mul_f32_e32 v121, v117, v121
	v_fma_f32 v120, v116, v120, v116
	v_fma_f32 v121, v117, v121, v117
	v_mul_f32_e32 v120, 0x3f4c422a, v120
	v_mul_f32_e32 v121, 0x3f4c422a, v121
	v_mul_f32_e32 v120, 0xc038aa3b, v120
	v_mul_f32_e32 v121, 0xc038aa3b, v121
	v_exp_f32_e32 v120, v120
	v_exp_f32_e32 v121, v121
	v_add_f32_e32 v120, 1.0, v120
	v_add_f32_e32 v121, 1.0, v121
	v_rcp_f32_e32 v120, v120
	v_rcp_f32_e32 v121, v121
	s_nop 0
	v_pk_mul_f32 v[116:117], v[116:117], v[120:121]
	v_mul_f32_e32 v120, 0x3d372713, v118
	v_mul_f32_e32 v121, 0x3d372713, v119
	v_mul_f32_e32 v120, v118, v120
	v_mul_f32_e32 v121, v119, v121
	v_fma_f32 v120, v118, v120, v118
	v_fma_f32 v121, v119, v121, v119
	v_mul_f32_e32 v120, 0x3f4c422a, v120
	v_mul_f32_e32 v121, 0x3f4c422a, v121
	v_mul_f32_e32 v120, 0xc038aa3b, v120
	v_mul_f32_e32 v121, 0xc038aa3b, v121
	v_exp_f32_e32 v120, v120
	v_exp_f32_e32 v121, v121
	v_cvt_pk_bf16_f32 v116, v116, v117
	v_add_f32_e32 v120, 1.0, v120
	v_add_f32_e32 v121, 1.0, v121
	v_rcp_f32_e32 v120, v120
	v_rcp_f32_e32 v121, v121
	s_nop 0
	v_pk_mul_f32 v[118:119], v[118:119], v[120:121]
	s_nop 0
	v_cvt_pk_bf16_f32 v117, v118, v119
	v_mul_f32_e32 v118, 0x3d372713, v112
	v_mul_f32_e32 v119, 0x3d372713, v113
	v_mul_f32_e32 v118, v112, v118
	v_mul_f32_e32 v119, v113, v119
	v_fma_f32 v118, v112, v118, v112
	v_fma_f32 v119, v113, v119, v113
	v_mul_f32_e32 v118, 0x3f4c422a, v118
	v_mul_f32_e32 v119, 0x3f4c422a, v119
	v_mul_f32_e32 v118, 0xc038aa3b, v118
	v_mul_f32_e32 v119, 0xc038aa3b, v119
	v_exp_f32_e32 v118, v118
	v_exp_f32_e32 v119, v119
	v_add_f32_e32 v118, 1.0, v118
	v_add_f32_e32 v119, 1.0, v119
	v_rcp_f32_e32 v118, v118
	v_rcp_f32_e32 v119, v119
	s_nop 0
	v_pk_mul_f32 v[112:113], v[112:113], v[118:119]
	v_mul_f32_e32 v118, 0x3d372713, v114
	v_mul_f32_e32 v119, 0x3d372713, v115
	v_mul_f32_e32 v118, v114, v118
	v_mul_f32_e32 v119, v115, v119
	v_fma_f32 v118, v114, v118, v114
	v_fma_f32 v119, v115, v119, v115
	v_mul_f32_e32 v118, 0x3f4c422a, v118
	v_mul_f32_e32 v119, 0x3f4c422a, v119
	v_mul_f32_e32 v118, 0xc038aa3b, v118
	v_mul_f32_e32 v119, 0xc038aa3b, v119
	v_exp_f32_e32 v118, v118
	v_exp_f32_e32 v119, v119
	v_cvt_pk_bf16_f32 v112, v112, v113
	v_add_f32_e32 v118, 1.0, v118
	v_add_f32_e32 v119, 1.0, v119
	v_rcp_f32_e32 v118, v118
	v_rcp_f32_e32 v119, v119
	s_nop 0
	v_pk_mul_f32 v[114:115], v[114:115], v[118:119]
	s_nop 0
	v_cvt_pk_bf16_f32 v113, v114, v115
	ds_write2_b64 v126, v[116:117], v[112:113] offset0:8 offset1:12
	ds_read_b32 v112, v127 offset:64
	s_waitcnt lgkmcnt(0)
	v_pk_mul_f32 v[108:109], v[108:109], v[112:113] op_sel_hi:[1,0]
	s_nop 0
	v_mul_f32_e32 v113, 0x3d372713, v108
	v_mul_f32_e32 v113, v108, v113
	v_fma_f32 v113, v108, v113, v108
	v_mul_f32_e32 v113, 0x3f4c422a, v113
	v_mul_f32_e32 v113, 0xc038aa3b, v113
	v_exp_f32_e32 v113, v113
	s_nop 0
	v_add_f32_e32 v113, 1.0, v113
	v_rcp_f32_e32 v114, v113
	v_mul_f32_e32 v113, 0x3d372713, v109
	v_mul_f32_e32 v113, v109, v113
	v_fma_f32 v113, v109, v113, v109
	v_mul_f32_e32 v113, 0x3f4c422a, v113
	v_mul_f32_e32 v113, 0xc038aa3b, v113
	v_exp_f32_e32 v113, v113
	s_nop 0
	v_add_f32_e32 v113, 1.0, v113
	v_pk_mul_f32 v[110:111], v[110:111], v[112:113] op_sel_hi:[1,0]
	v_rcp_f32_e32 v115, v113
	v_mul_f32_e32 v113, 0x3d372713, v110
	v_mul_f32_e32 v113, v110, v113
	v_fma_f32 v113, v110, v113, v110
	v_mul_f32_e32 v113, 0x3f4c422a, v113
	v_mul_f32_e32 v113, 0xc038aa3b, v113
	v_exp_f32_e32 v113, v113
	v_pk_mul_f32 v[108:109], v[108:109], v[114:115]
	v_add_f32_e32 v113, 1.0, v113
	v_rcp_f32_e32 v114, v113
	v_mul_f32_e32 v113, 0x3d372713, v111
	v_mul_f32_e32 v113, v111, v113
	v_fma_f32 v113, v111, v113, v111
	v_mul_f32_e32 v113, 0x3f4c422a, v113
	v_mul_f32_e32 v113, 0xc038aa3b, v113
	v_exp_f32_e32 v113, v113
	v_cvt_pk_bf16_f32 v108, v108, v109
	v_add_f32_e32 v113, 1.0, v113
	v_rcp_f32_e32 v115, v113
	v_pk_mul_f32 v[104:105], v[104:105], v[112:113] op_sel_hi:[1,0]
	v_pk_mul_f32 v[106:107], v[106:107], v[112:113] op_sel_hi:[1,0]
	v_pk_mul_f32 v[100:101], v[100:101], v[112:113] op_sel_hi:[1,0]
	v_pk_mul_f32 v[110:111], v[110:111], v[114:115]
	v_pk_mul_f32 v[102:103], v[102:103], v[112:113] op_sel_hi:[1,0]
	v_cvt_pk_bf16_f32 v109, v110, v111
	v_mul_f32_e32 v110, 0x3d372713, v104
	v_mul_f32_e32 v111, 0x3d372713, v105
	v_mul_f32_e32 v110, v104, v110
	v_mul_f32_e32 v111, v105, v111
	v_fma_f32 v110, v104, v110, v104
	v_fma_f32 v111, v105, v111, v105
	v_mul_f32_e32 v110, 0x3f4c422a, v110
; DI unsigned pk2(float a, float b) { f32x2 v = {a, b}; bf16x2_t r = __builtin_convertvector(v, bf16x2_t); return __builtin_bit_cast(unsigned, r); }
;     DI void operator()(gacc_t& acc, int pm, int pn, char* lds, int tid, int wr, int wc, int lane) const {
;     ...
;         for (int m = 0; m < 8; ++m) {
;             const float r = rl[m * 16];
; #pragma unroll
;             for (int n = 0; n < 4; ++n) {
;                 float g[4];
; #pragma unroll
;                 for (int j = 0; j < 4; ++j) {
;                     const float x = acc[m][n][j] * r;
;                     const float u = 0.7978845608028654f * (x + 0.044715f * x * x * x);
;                     const float e = __builtin_amdgcn_exp2f(-2.885390081777927f * u);
;                     g[j] = x * __builtin_amdgcn_rcpf(1.0f + e);
;                 }
;                 u32x2 w; w.x = pk2(g[0], g[1]); w.y = pk2(g[2], g[3]);
;                 *(u32x2*)(lbase + m * 16 * 528 + n * 32) = w;
;             }
	v_mul_f32_e32 v111, 0x3f4c422a, v111
	v_mul_f32_e32 v110, 0xc038aa3b, v110
	v_mul_f32_e32 v111, 0xc038aa3b, v111
	v_exp_f32_e32 v110, v110
	v_exp_f32_e32 v111, v111
	v_pk_mul_f32 v[96:97], v[96:97], v[112:113] op_sel_hi:[1,0]
	v_pk_mul_f32 v[98:99], v[98:99], v[112:113] op_sel_hi:[1,0]
	v_add_f32_e32 v110, 1.0, v110
	v_add_f32_e32 v111, 1.0, v111
	v_rcp_f32_e32 v110, v110
	v_rcp_f32_e32 v111, v111
	s_nop 0
	v_pk_mul_f32 v[104:105], v[104:105], v[110:111]
	v_mul_f32_e32 v110, 0x3d372713, v106
	v_mul_f32_e32 v111, 0x3d372713, v107
	v_mul_f32_e32 v110, v106, v110
	v_mul_f32_e32 v111, v107, v111
	v_fma_f32 v110, v106, v110, v106
	v_fma_f32 v111, v107, v111, v107
	v_mul_f32_e32 v110, 0x3f4c422a, v110
	v_mul_f32_e32 v111, 0x3f4c422a, v111
	v_mul_f32_e32 v110, 0xc038aa3b, v110
	v_mul_f32_e32 v111, 0xc038aa3b, v111
	v_exp_f32_e32 v110, v110
	v_exp_f32_e32 v111, v111
	v_cvt_pk_bf16_f32 v104, v104, v105
	v_add_f32_e32 v110, 1.0, v110
	v_add_f32_e32 v111, 1.0, v111
	v_rcp_f32_e32 v110, v110
	v_rcp_f32_e32 v111, v111
	s_nop 0
	v_pk_mul_f32 v[106:107], v[106:107], v[110:111]
	s_nop 0
	v_cvt_pk_bf16_f32 v105, v106, v107
	v_add_u32_e32 v106, 0x2000, v126
	ds_write2_b64 v106, v[108:109], v[104:105] offset0:32 offset1:36
	v_mul_f32_e32 v104, 0x3d372713, v100
	v_mul_f32_e32 v105, 0x3d372713, v101
	v_mul_f32_e32 v104, v100, v104
	v_mul_f32_e32 v105, v101, v105
	v_fma_f32 v104, v100, v104, v100
	v_fma_f32 v105, v101, v105, v101
	v_mul_f32_e32 v104, 0x3f4c422a, v104
	v_mul_f32_e32 v105, 0x3f4c422a, v105
	v_mul_f32_e32 v104, 0xc038aa3b, v104
	v_mul_f32_e32 v105, 0xc038aa3b, v105
	v_exp_f32_e32 v104, v104
	v_exp_f32_e32 v105, v105
	v_add_f32_e32 v104, 1.0, v104
	v_add_f32_e32 v105, 1.0, v105
	v_rcp_f32_e32 v104, v104
	v_rcp_f32_e32 v105, v105
	s_nop 0
	v_pk_mul_f32 v[100:101], v[100:101], v[104:105]
	v_mul_f32_e32 v104, 0x3d372713, v102
	v_mul_f32_e32 v105, 0x3d372713, v103
	v_mul_f32_e32 v104, v102, v104
	v_mul_f32_e32 v105, v103, v105
	v_fma_f32 v104, v102, v104, v102
	v_fma_f32 v105, v103, v105, v103
	v_mul_f32_e32 v104, 0x3f4c422a, v104
	v_mul_f32_e32 v105, 0x3f4c422a, v105
	v_mul_f32_e32 v104, 0xc038aa3b, v104
	v_mul_f32_e32 v105, 0xc038aa3b, v105
	v_exp_f32_e32 v104, v104
	v_exp_f32_e32 v105, v105
	v_cvt_pk_bf16_f32 v100, v100, v101
	v_add_f32_e32 v104, 1.0, v104
	v_add_f32_e32 v105, 1.0, v105
	v_rcp_f32_e32 v104, v104
	v_rcp_f32_e32 v105, v105
	s_nop 0
	v_pk_mul_f32 v[102:103], v[102:103], v[104:105]
	s_nop 0
	v_cvt_pk_bf16_f32 v101, v102, v103
	v_mul_f32_e32 v102, 0x3d372713, v96
	v_mul_f32_e32 v103, 0x3d372713, v97
	v_mul_f32_e32 v102, v96, v102
	v_mul_f32_e32 v103, v97, v103
	v_fma_f32 v102, v96, v102, v96
	v_fma_f32 v103, v97, v103, v97
	v_mul_f32_e32 v102, 0x3f4c422a, v102
	v_mul_f32_e32 v103, 0x3f4c422a, v103
	v_mul_f32_e32 v102, 0xc038aa3b, v102
	v_mul_f32_e32 v103, 0xc038aa3b, v103
	v_exp_f32_e32 v102, v102
	v_exp_f32_e32 v103, v103
	v_add_f32_e32 v102, 1.0, v102
	v_add_f32_e32 v103, 1.0, v103
	v_rcp_f32_e32 v102, v102
	v_rcp_f32_e32 v103, v103
	s_nop 0
	v_pk_mul_f32 v[96:97], v[96:97], v[102:103]
	v_mul_f32_e32 v102, 0x3d372713, v98
	v_mul_f32_e32 v103, 0x3d372713, v99
	v_mul_f32_e32 v102, v98, v102
	v_mul_f32_e32 v103, v99, v103
	v_fma_f32 v102, v98, v102, v98
	v_fma_f32 v103, v99, v103, v99
	v_mul_f32_e32 v102, 0x3f4c422a, v102
	v_mul_f32_e32 v103, 0x3f4c422a, v103
	v_mul_f32_e32 v102, 0xc038aa3b, v102
	v_mul_f32_e32 v103, 0xc038aa3b, v103
	v_exp_f32_e32 v102, v102
	v_exp_f32_e32 v103, v103
	v_cvt_pk_bf16_f32 v96, v96, v97
	v_add_f32_e32 v102, 1.0, v102
	v_add_f32_e32 v103, 1.0, v103
	v_rcp_f32_e32 v102, v102
	v_rcp_f32_e32 v103, v103
	s_nop 0
	v_pk_mul_f32 v[98:99], v[98:99], v[102:103]
	s_nop 0
	v_cvt_pk_bf16_f32 v97, v98, v99
	ds_write2_b64 v106, v[100:101], v[96:97] offset0:40 offset1:44
	ds_read_b32 v96, v127 offset:128
	s_waitcnt lgkmcnt(0)
	v_pk_mul_f32 v[92:93], v[92:93], v[96:97] op_sel_hi:[1,0]
	s_nop 0
	v_mul_f32_e32 v97, 0x3d372713, v92
	v_mul_f32_e32 v97, v92, v97
	v_fma_f32 v97, v92, v97, v92
	v_mul_f32_e32 v97, 0x3f4c422a, v97
	v_mul_f32_e32 v97, 0xc038aa3b, v97
	v_exp_f32_e32 v97, v97
	s_nop 0
	v_add_f32_e32 v97, 1.0, v97
	v_rcp_f32_e32 v98, v97
	v_mul_f32_e32 v97, 0x3d372713, v93
	v_mul_f32_e32 v97, v93, v97
	v_fma_f32 v97, v93, v97, v93
	v_mul_f32_e32 v97, 0x3f4c422a, v97
	v_mul_f32_e32 v97, 0xc038aa3b, v97
	v_exp_f32_e32 v97, v97
	s_nop 0
	v_add_f32_e32 v97, 1.0, v97
	v_pk_mul_f32 v[94:95], v[94:95], v[96:97] op_sel_hi:[1,0]
	v_rcp_f32_e32 v99, v97
	v_mul_f32_e32 v97, 0x3d372713, v94
	v_mul_f32_e32 v97, v94, v97
	v_fma_f32 v97, v94, v97, v94
	v_mul_f32_e32 v97, 0x3f4c422a, v97
	v_mul_f32_e32 v97, 0xc038aa3b, v97
	v_exp_f32_e32 v97, v97
	v_pk_mul_f32 v[92:93], v[92:93], v[98:99]
	v_add_f32_e32 v97, 1.0, v97
	v_rcp_f32_e32 v98, v97
	v_mul_f32_e32 v97, 0x3d372713, v95
	v_mul_f32_e32 v97, v95, v97
	v_fma_f32 v97, v95, v97, v95
	v_mul_f32_e32 v97, 0x3f4c422a, v97
	v_mul_f32_e32 v97, 0xc038aa3b, v97
	v_exp_f32_e32 v97, v97
	v_cvt_pk_bf16_f32 v92, v92, v93
	v_add_f32_e32 v97, 1.0, v97
	v_rcp_f32_e32 v99, v97
	v_pk_mul_f32 v[88:89], v[88:89], v[96:97] op_sel_hi:[1,0]
	v_pk_mul_f32 v[90:91], v[90:91], v[96:97] op_sel_hi:[1,0]
	v_pk_mul_f32 v[84:85], v[84:85], v[96:97] op_sel_hi:[1,0]
	v_pk_mul_f32 v[94:95], v[94:95], v[98:99]
	v_pk_mul_f32 v[86:87], v[86:87], v[96:97] op_sel_hi:[1,0]
	v_cvt_pk_bf16_f32 v93, v94, v95
	v_mul_f32_e32 v94, 0x3d372713, v88
	v_mul_f32_e32 v95, 0x3d372713, v89
	v_mul_f32_e32 v94, v88, v94
	v_mul_f32_e32 v95, v89, v95
	v_fma_f32 v94, v88, v94, v88
	v_fma_f32 v95, v89, v95, v89
	v_mul_f32_e32 v94, 0x3f4c422a, v94
	v_mul_f32_e32 v95, 0x3f4c422a, v95
	v_mul_f32_e32 v94, 0xc038aa3b, v94
	v_mul_f32_e32 v95, 0xc038aa3b, v95
; DI unsigned pk2(float a, float b) { f32x2 v = {a, b}; bf16x2_t r = __builtin_convertvector(v, bf16x2_t); return __builtin_bit_cast(unsigned, r); }
;     DI void operator()(gacc_t& acc, int pm, int pn, char* lds, int tid, int wr, int wc, int lane) const {
;     ...
;         for (int m = 0; m < 8; ++m) {
;             const float r = rl[m * 16];
; #pragma unroll
;             for (int n = 0; n < 4; ++n) {
;                 float g[4];
; #pragma unroll
;                 for (int j = 0; j < 4; ++j) {
;                     const float x = acc[m][n][j] * r;
;                     const float u = 0.7978845608028654f * (x + 0.044715f * x * x * x);
;                     const float e = __builtin_amdgcn_exp2f(-2.885390081777927f * u);
;                     g[j] = x * __builtin_amdgcn_rcpf(1.0f + e);
;                 }
;                 u32x2 w; w.x = pk2(g[0], g[1]); w.y = pk2(g[2], g[3]);
;                 *(u32x2*)(lbase + m * 16 * 528 + n * 32) = w;
;             }
	v_exp_f32_e32 v94, v94
	v_exp_f32_e32 v95, v95
	v_pk_mul_f32 v[80:81], v[80:81], v[96:97] op_sel_hi:[1,0]
	v_pk_mul_f32 v[82:83], v[82:83], v[96:97] op_sel_hi:[1,0]
	v_add_f32_e32 v94, 1.0, v94
	v_add_f32_e32 v95, 1.0, v95
	v_rcp_f32_e32 v94, v94
	v_rcp_f32_e32 v95, v95
	s_nop 0
	v_pk_mul_f32 v[88:89], v[88:89], v[94:95]
	v_mul_f32_e32 v94, 0x3d372713, v90
	v_mul_f32_e32 v95, 0x3d372713, v91
	v_mul_f32_e32 v94, v90, v94
	v_mul_f32_e32 v95, v91, v95
	v_fma_f32 v94, v90, v94, v90
	v_fma_f32 v95, v91, v95, v91
	v_mul_f32_e32 v94, 0x3f4c422a, v94
	v_mul_f32_e32 v95, 0x3f4c422a, v95
	v_mul_f32_e32 v94, 0xc038aa3b, v94
	v_mul_f32_e32 v95, 0xc038aa3b, v95
	v_exp_f32_e32 v94, v94
	v_exp_f32_e32 v95, v95
	v_cvt_pk_bf16_f32 v88, v88, v89
	v_add_f32_e32 v94, 1.0, v94
	v_add_f32_e32 v95, 1.0, v95
	v_rcp_f32_e32 v94, v94
	v_rcp_f32_e32 v95, v95
	s_nop 0
	v_pk_mul_f32 v[90:91], v[90:91], v[94:95]
	s_nop 0
	v_cvt_pk_bf16_f32 v89, v90, v91
	v_add_u32_e32 v90, 0x4000, v126
	ds_write2_b64 v90, v[92:93], v[88:89] offset0:64 offset1:68
	v_mul_f32_e32 v88, 0x3d372713, v84
	v_mul_f32_e32 v89, 0x3d372713, v85
	v_mul_f32_e32 v88, v84, v88
	v_mul_f32_e32 v89, v85, v89
	v_fma_f32 v88, v84, v88, v84
	v_fma_f32 v89, v85, v89, v85
	v_mul_f32_e32 v88, 0x3f4c422a, v88
	v_mul_f32_e32 v89, 0x3f4c422a, v89
	v_mul_f32_e32 v88, 0xc038aa3b, v88
	v_mul_f32_e32 v89, 0xc038aa3b, v89
	v_exp_f32_e32 v88, v88
	v_exp_f32_e32 v89, v89
	v_add_f32_e32 v88, 1.0, v88
	v_add_f32_e32 v89, 1.0, v89
	v_rcp_f32_e32 v88, v88
	v_rcp_f32_e32 v89, v89
	s_nop 0
	v_pk_mul_f32 v[84:85], v[84:85], v[88:89]
	v_mul_f32_e32 v88, 0x3d372713, v86
	v_mul_f32_e32 v89, 0x3d372713, v87
	v_mul_f32_e32 v88, v86, v88
	v_mul_f32_e32 v89, v87, v89
	v_fma_f32 v88, v86, v88, v86
	v_fma_f32 v89, v87, v89, v87
	v_mul_f32_e32 v88, 0x3f4c422a, v88
	v_mul_f32_e32 v89, 0x3f4c422a, v89
	v_mul_f32_e32 v88, 0xc038aa3b, v88
	v_mul_f32_e32 v89, 0xc038aa3b, v89
	v_exp_f32_e32 v88, v88
	v_exp_f32_e32 v89, v89
	v_cvt_pk_bf16_f32 v84, v84, v85
	v_add_f32_e32 v88, 1.0, v88
	v_add_f32_e32 v89, 1.0, v89
	v_rcp_f32_e32 v88, v88
	v_rcp_f32_e32 v89, v89
	s_nop 0
	v_pk_mul_f32 v[86:87], v[86:87], v[88:89]
	s_nop 0
	v_cvt_pk_bf16_f32 v85, v86, v87
	v_mul_f32_e32 v86, 0x3d372713, v80
	v_mul_f32_e32 v87, 0x3d372713, v81
	v_mul_f32_e32 v86, v80, v86
	v_mul_f32_e32 v87, v81, v87
	v_fma_f32 v86, v80, v86, v80
	v_fma_f32 v87, v81, v87, v81
	v_mul_f32_e32 v86, 0x3f4c422a, v86
	v_mul_f32_e32 v87, 0x3f4c422a, v87
	v_mul_f32_e32 v86, 0xc038aa3b, v86
	v_mul_f32_e32 v87, 0xc038aa3b, v87
	v_exp_f32_e32 v86, v86
	v_exp_f32_e32 v87, v87
	v_add_f32_e32 v86, 1.0, v86
	v_add_f32_e32 v87, 1.0, v87
	v_rcp_f32_e32 v86, v86
	v_rcp_f32_e32 v87, v87
	s_nop 0
	v_pk_mul_f32 v[80:81], v[80:81], v[86:87]
	v_mul_f32_e32 v86, 0x3d372713, v82
	v_mul_f32_e32 v87, 0x3d372713, v83
	v_mul_f32_e32 v86, v82, v86
	v_mul_f32_e32 v87, v83, v87
	v_fma_f32 v86, v82, v86, v82
	v_fma_f32 v87, v83, v87, v83
	v_mul_f32_e32 v86, 0x3f4c422a, v86
	v_mul_f32_e32 v87, 0x3f4c422a, v87
	v_mul_f32_e32 v86, 0xc038aa3b, v86
	v_mul_f32_e32 v87, 0xc038aa3b, v87
	v_exp_f32_e32 v86, v86
	v_exp_f32_e32 v87, v87
	v_cvt_pk_bf16_f32 v80, v80, v81
	v_add_f32_e32 v86, 1.0, v86
	v_add_f32_e32 v87, 1.0, v87
	v_rcp_f32_e32 v86, v86
	v_rcp_f32_e32 v87, v87
	s_nop 0
	v_pk_mul_f32 v[82:83], v[82:83], v[86:87]
	s_nop 0
	v_cvt_pk_bf16_f32 v81, v82, v83
	ds_write2_b64 v90, v[84:85], v[80:81] offset0:72 offset1:76
	ds_read_b32 v80, v127 offset:192
	s_waitcnt lgkmcnt(0)
	v_pk_mul_f32 v[76:77], v[76:77], v[80:81] op_sel_hi:[1,0]
	s_nop 0
	v_mul_f32_e32 v81, 0x3d372713, v76
	v_mul_f32_e32 v81, v76, v81
	v_fma_f32 v81, v76, v81, v76
	v_mul_f32_e32 v81, 0x3f4c422a, v81
	v_mul_f32_e32 v81, 0xc038aa3b, v81
	v_exp_f32_e32 v81, v81
	s_nop 0
	v_add_f32_e32 v81, 1.0, v81
	v_rcp_f32_e32 v82, v81
	v_mul_f32_e32 v81, 0x3d372713, v77
	v_mul_f32_e32 v81, v77, v81
	v_fma_f32 v81, v77, v81, v77
	v_mul_f32_e32 v81, 0x3f4c422a, v81
	v_mul_f32_e32 v81, 0xc038aa3b, v81
	v_exp_f32_e32 v81, v81
	s_nop 0
	v_add_f32_e32 v81, 1.0, v81
	v_pk_mul_f32 v[78:79], v[78:79], v[80:81] op_sel_hi:[1,0]
	v_rcp_f32_e32 v83, v81
	v_mul_f32_e32 v81, 0x3d372713, v78
	v_mul_f32_e32 v81, v78, v81
	v_fma_f32 v81, v78, v81, v78
	v_mul_f32_e32 v81, 0x3f4c422a, v81
	v_mul_f32_e32 v81, 0xc038aa3b, v81
	v_exp_f32_e32 v81, v81
	v_pk_mul_f32 v[76:77], v[76:77], v[82:83]
	v_add_f32_e32 v81, 1.0, v81
	v_rcp_f32_e32 v82, v81
	v_mul_f32_e32 v81, 0x3d372713, v79
	v_mul_f32_e32 v81, v79, v81
	v_fma_f32 v81, v79, v81, v79
	v_mul_f32_e32 v81, 0x3f4c422a, v81
	v_mul_f32_e32 v81, 0xc038aa3b, v81
	v_exp_f32_e32 v81, v81
	v_cvt_pk_bf16_f32 v76, v76, v77
	v_add_f32_e32 v81, 1.0, v81
	v_rcp_f32_e32 v83, v81
	v_pk_mul_f32 v[72:73], v[72:73], v[80:81] op_sel_hi:[1,0]
	v_pk_mul_f32 v[74:75], v[74:75], v[80:81] op_sel_hi:[1,0]
	v_pk_mul_f32 v[68:69], v[68:69], v[80:81] op_sel_hi:[1,0]
	v_pk_mul_f32 v[78:79], v[78:79], v[82:83]
	v_pk_mul_f32 v[70:71], v[70:71], v[80:81] op_sel_hi:[1,0]
	v_cvt_pk_bf16_f32 v77, v78, v79
	v_mul_f32_e32 v78, 0x3d372713, v72
	v_mul_f32_e32 v79, 0x3d372713, v73
	v_mul_f32_e32 v78, v72, v78
	v_mul_f32_e32 v79, v73, v79
	v_fma_f32 v78, v72, v78, v72
	v_fma_f32 v79, v73, v79, v73
	v_mul_f32_e32 v78, 0x3f4c422a, v78
	v_mul_f32_e32 v79, 0x3f4c422a, v79
	v_mul_f32_e32 v78, 0xc038aa3b, v78
	v_mul_f32_e32 v79, 0xc038aa3b, v79
	v_exp_f32_e32 v78, v78
	v_exp_f32_e32 v79, v79
	v_pk_mul_f32 v[64:65], v[64:65], v[80:81] op_sel_hi:[1,0]
	v_pk_mul_f32 v[66:67], v[66:67], v[80:81] op_sel_hi:[1,0]
	v_add_f32_e32 v78, 1.0, v78
	v_add_f32_e32 v79, 1.0, v79
	v_rcp_f32_e32 v78, v78
	v_rcp_f32_e32 v79, v79
	s_nop 0
	v_pk_mul_f32 v[72:73], v[72:73], v[78:79]
; DI unsigned pk2(float a, float b) { f32x2 v = {a, b}; bf16x2_t r = __builtin_convertvector(v, bf16x2_t); return __builtin_bit_cast(unsigned, r); }
;     DI void operator()(gacc_t& acc, int pm, int pn, char* lds, int tid, int wr, int wc, int lane) const {
;     ...
;         for (int m = 0; m < 8; ++m) {
;             const float r = rl[m * 16];
; #pragma unroll
;             for (int n = 0; n < 4; ++n) {
;                 float g[4];
; #pragma unroll
;                 for (int j = 0; j < 4; ++j) {
;                     const float x = acc[m][n][j] * r;
;                     const float u = 0.7978845608028654f * (x + 0.044715f * x * x * x);
;                     const float e = __builtin_amdgcn_exp2f(-2.885390081777927f * u);
;                     g[j] = x * __builtin_amdgcn_rcpf(1.0f + e);
;                 }
;                 u32x2 w; w.x = pk2(g[0], g[1]); w.y = pk2(g[2], g[3]);
;                 *(u32x2*)(lbase + m * 16 * 528 + n * 32) = w;
;             }
	v_mul_f32_e32 v78, 0x3d372713, v74
	v_mul_f32_e32 v79, 0x3d372713, v75
	v_mul_f32_e32 v78, v74, v78
	v_mul_f32_e32 v79, v75, v79
	v_fma_f32 v78, v74, v78, v74
	v_fma_f32 v79, v75, v79, v75
	v_mul_f32_e32 v78, 0x3f4c422a, v78
	v_mul_f32_e32 v79, 0x3f4c422a, v79
	v_mul_f32_e32 v78, 0xc038aa3b, v78
	v_mul_f32_e32 v79, 0xc038aa3b, v79
	v_exp_f32_e32 v78, v78
	v_exp_f32_e32 v79, v79
	v_cvt_pk_bf16_f32 v72, v72, v73
	v_add_f32_e32 v78, 1.0, v78
	v_add_f32_e32 v79, 1.0, v79
	v_rcp_f32_e32 v78, v78
	v_rcp_f32_e32 v79, v79
	s_nop 0
	v_pk_mul_f32 v[74:75], v[74:75], v[78:79]
	s_nop 0
	v_cvt_pk_bf16_f32 v73, v74, v75
	v_add_u32_e32 v74, 0x6000, v126
	ds_write2_b64 v74, v[76:77], v[72:73] offset0:96 offset1:100
	v_mul_f32_e32 v72, 0x3d372713, v68
	v_mul_f32_e32 v73, 0x3d372713, v69
	v_mul_f32_e32 v72, v68, v72
	v_mul_f32_e32 v73, v69, v73
	v_fma_f32 v72, v68, v72, v68
	v_fma_f32 v73, v69, v73, v69
	v_mul_f32_e32 v72, 0x3f4c422a, v72
	v_mul_f32_e32 v73, 0x3f4c422a, v73
	v_mul_f32_e32 v72, 0xc038aa3b, v72
	v_mul_f32_e32 v73, 0xc038aa3b, v73
	v_exp_f32_e32 v72, v72
	v_exp_f32_e32 v73, v73
	v_add_f32_e32 v72, 1.0, v72
	v_add_f32_e32 v73, 1.0, v73
	v_rcp_f32_e32 v72, v72
	v_rcp_f32_e32 v73, v73
	s_nop 0
	v_pk_mul_f32 v[68:69], v[68:69], v[72:73]
	v_mul_f32_e32 v72, 0x3d372713, v70
	v_mul_f32_e32 v73, 0x3d372713, v71
	v_mul_f32_e32 v72, v70, v72
	v_mul_f32_e32 v73, v71, v73
	v_fma_f32 v72, v70, v72, v70
	v_fma_f32 v73, v71, v73, v71
	v_mul_f32_e32 v72, 0x3f4c422a, v72
	v_mul_f32_e32 v73, 0x3f4c422a, v73
	v_mul_f32_e32 v72, 0xc038aa3b, v72
	v_mul_f32_e32 v73, 0xc038aa3b, v73
	v_exp_f32_e32 v72, v72
	v_exp_f32_e32 v73, v73
	v_cvt_pk_bf16_f32 v68, v68, v69
	v_add_f32_e32 v72, 1.0, v72
	v_add_f32_e32 v73, 1.0, v73
	v_rcp_f32_e32 v72, v72
	v_rcp_f32_e32 v73, v73
	s_nop 0
	v_pk_mul_f32 v[70:71], v[70:71], v[72:73]
	s_nop 0
	v_cvt_pk_bf16_f32 v69, v70, v71
	v_mul_f32_e32 v70, 0x3d372713, v64
	v_mul_f32_e32 v71, 0x3d372713, v65
	v_mul_f32_e32 v70, v64, v70
	v_mul_f32_e32 v71, v65, v71
	v_fma_f32 v70, v64, v70, v64
	v_fma_f32 v71, v65, v71, v65
	v_mul_f32_e32 v70, 0x3f4c422a, v70
	v_mul_f32_e32 v71, 0x3f4c422a, v71
	v_mul_f32_e32 v70, 0xc038aa3b, v70
	v_mul_f32_e32 v71, 0xc038aa3b, v71
	v_exp_f32_e32 v70, v70
	v_exp_f32_e32 v71, v71
	v_add_f32_e32 v70, 1.0, v70
	v_add_f32_e32 v71, 1.0, v71
	v_rcp_f32_e32 v70, v70
	v_rcp_f32_e32 v71, v71
	s_nop 0
	v_pk_mul_f32 v[64:65], v[64:65], v[70:71]
	v_mul_f32_e32 v70, 0x3d372713, v66
	v_mul_f32_e32 v71, 0x3d372713, v67
	v_mul_f32_e32 v70, v66, v70
	v_mul_f32_e32 v71, v67, v71
	v_fma_f32 v70, v66, v70, v66
	v_fma_f32 v71, v67, v71, v67
	v_mul_f32_e32 v70, 0x3f4c422a, v70
	v_mul_f32_e32 v71, 0x3f4c422a, v71
	v_mul_f32_e32 v70, 0xc038aa3b, v70
	v_mul_f32_e32 v71, 0xc038aa3b, v71
	v_exp_f32_e32 v70, v70
	v_exp_f32_e32 v71, v71
	v_cvt_pk_bf16_f32 v64, v64, v65
	v_add_f32_e32 v70, 1.0, v70
	v_add_f32_e32 v71, 1.0, v71
	v_rcp_f32_e32 v70, v70
	v_rcp_f32_e32 v71, v71
	s_nop 0
	v_pk_mul_f32 v[66:67], v[66:67], v[70:71]
	s_nop 0
	v_cvt_pk_bf16_f32 v65, v66, v67
	ds_write2_b64 v74, v[68:69], v[64:65] offset0:104 offset1:108
	ds_read_b32 v64, v127 offset:256
	s_waitcnt lgkmcnt(0)
	v_pk_mul_f32 v[60:61], v[60:61], v[64:65] op_sel_hi:[1,0]
	s_nop 0
	v_mul_f32_e32 v65, 0x3d372713, v60
	v_mul_f32_e32 v65, v60, v65
	v_fma_f32 v65, v60, v65, v60
	v_mul_f32_e32 v65, 0x3f4c422a, v65
	v_mul_f32_e32 v65, 0xc038aa3b, v65
	v_exp_f32_e32 v65, v65
	s_nop 0
	v_add_f32_e32 v65, 1.0, v65
	v_rcp_f32_e32 v66, v65
	v_mul_f32_e32 v65, 0x3d372713, v61
	v_mul_f32_e32 v65, v61, v65
	v_fma_f32 v65, v61, v65, v61
	v_mul_f32_e32 v65, 0x3f4c422a, v65
	v_mul_f32_e32 v65, 0xc038aa3b, v65
	v_exp_f32_e32 v65, v65
	s_nop 0
	v_add_f32_e32 v65, 1.0, v65
	v_pk_mul_f32 v[62:63], v[62:63], v[64:65] op_sel_hi:[1,0]
	v_rcp_f32_e32 v67, v65
	v_mul_f32_e32 v65, 0x3d372713, v62
	v_mul_f32_e32 v65, v62, v65
	v_fma_f32 v65, v62, v65, v62
	v_mul_f32_e32 v65, 0x3f4c422a, v65
	v_mul_f32_e32 v65, 0xc038aa3b, v65
	v_exp_f32_e32 v65, v65
	v_pk_mul_f32 v[60:61], v[60:61], v[66:67]
	v_add_f32_e32 v65, 1.0, v65
	v_rcp_f32_e32 v66, v65
	v_mul_f32_e32 v65, 0x3d372713, v63
	v_mul_f32_e32 v65, v63, v65
	v_fma_f32 v65, v63, v65, v63
	v_mul_f32_e32 v65, 0x3f4c422a, v65
	v_mul_f32_e32 v65, 0xc038aa3b, v65
	v_exp_f32_e32 v65, v65
	v_cvt_pk_bf16_f32 v60, v60, v61
	v_add_f32_e32 v65, 1.0, v65
	v_rcp_f32_e32 v67, v65
	v_pk_mul_f32 v[56:57], v[56:57], v[64:65] op_sel_hi:[1,0]
	v_pk_mul_f32 v[58:59], v[58:59], v[64:65] op_sel_hi:[1,0]
	v_pk_mul_f32 v[52:53], v[52:53], v[64:65] op_sel_hi:[1,0]
	v_pk_mul_f32 v[62:63], v[62:63], v[66:67]
	v_pk_mul_f32 v[54:55], v[54:55], v[64:65] op_sel_hi:[1,0]
	v_cvt_pk_bf16_f32 v61, v62, v63
	v_mul_f32_e32 v62, 0x3d372713, v56
	v_mul_f32_e32 v63, 0x3d372713, v57
	v_mul_f32_e32 v62, v56, v62
	v_mul_f32_e32 v63, v57, v63
	v_fma_f32 v62, v56, v62, v56
	v_fma_f32 v63, v57, v63, v57
	v_mul_f32_e32 v62, 0x3f4c422a, v62
	v_mul_f32_e32 v63, 0x3f4c422a, v63
	v_mul_f32_e32 v62, 0xc038aa3b, v62
	v_mul_f32_e32 v63, 0xc038aa3b, v63
	v_exp_f32_e32 v62, v62
	v_exp_f32_e32 v63, v63
	v_pk_mul_f32 v[48:49], v[48:49], v[64:65] op_sel_hi:[1,0]
	v_pk_mul_f32 v[50:51], v[50:51], v[64:65] op_sel_hi:[1,0]
	v_add_f32_e32 v62, 1.0, v62
	v_add_f32_e32 v63, 1.0, v63
	v_rcp_f32_e32 v62, v62
	v_rcp_f32_e32 v63, v63
	s_nop 0
	v_pk_mul_f32 v[56:57], v[56:57], v[62:63]
	v_mul_f32_e32 v62, 0x3d372713, v58
	v_mul_f32_e32 v63, 0x3d372713, v59
	v_mul_f32_e32 v62, v58, v62
	v_mul_f32_e32 v63, v59, v63
	v_fma_f32 v62, v58, v62, v58
	v_fma_f32 v63, v59, v63, v59
	v_mul_f32_e32 v62, 0x3f4c422a, v62
	v_mul_f32_e32 v63, 0x3f4c422a, v63
	v_mul_f32_e32 v62, 0xc038aa3b, v62
	v_mul_f32_e32 v63, 0xc038aa3b, v63
; DI unsigned pk2(float a, float b) { f32x2 v = {a, b}; bf16x2_t r = __builtin_convertvector(v, bf16x2_t); return __builtin_bit_cast(unsigned, r); }
;     DI void operator()(gacc_t& acc, int pm, int pn, char* lds, int tid, int wr, int wc, int lane) const {
;     ...
;         for (int m = 0; m < 8; ++m) {
;             const float r = rl[m * 16];
; #pragma unroll
;             for (int n = 0; n < 4; ++n) {
;                 float g[4];
; #pragma unroll
;                 for (int j = 0; j < 4; ++j) {
;                     const float x = acc[m][n][j] * r;
;                     const float u = 0.7978845608028654f * (x + 0.044715f * x * x * x);
;                     const float e = __builtin_amdgcn_exp2f(-2.885390081777927f * u);
;                     g[j] = x * __builtin_amdgcn_rcpf(1.0f + e);
;                 }
;                 u32x2 w; w.x = pk2(g[0], g[1]); w.y = pk2(g[2], g[3]);
;                 *(u32x2*)(lbase + m * 16 * 528 + n * 32) = w;
;             }
	v_exp_f32_e32 v62, v62
	v_exp_f32_e32 v63, v63
	v_cvt_pk_bf16_f32 v56, v56, v57
	v_add_f32_e32 v62, 1.0, v62
	v_add_f32_e32 v63, 1.0, v63
	v_rcp_f32_e32 v62, v62
	v_rcp_f32_e32 v63, v63
	s_nop 0
	v_pk_mul_f32 v[58:59], v[58:59], v[62:63]
	s_nop 0
	v_cvt_pk_bf16_f32 v57, v58, v59
	v_add_u32_e32 v58, 0x8000, v126
	ds_write2_b64 v58, v[60:61], v[56:57] offset0:128 offset1:132
	v_mul_f32_e32 v56, 0x3d372713, v52
	v_mul_f32_e32 v57, 0x3d372713, v53
	v_mul_f32_e32 v56, v52, v56
	v_mul_f32_e32 v57, v53, v57
	v_fma_f32 v56, v52, v56, v52
	v_fma_f32 v57, v53, v57, v53
	v_mul_f32_e32 v56, 0x3f4c422a, v56
	v_mul_f32_e32 v57, 0x3f4c422a, v57
	v_mul_f32_e32 v56, 0xc038aa3b, v56
	v_mul_f32_e32 v57, 0xc038aa3b, v57
	v_exp_f32_e32 v56, v56
	v_exp_f32_e32 v57, v57
	v_add_f32_e32 v56, 1.0, v56
	v_add_f32_e32 v57, 1.0, v57
	v_rcp_f32_e32 v56, v56
	v_rcp_f32_e32 v57, v57
	s_nop 0
	v_pk_mul_f32 v[52:53], v[52:53], v[56:57]
	v_mul_f32_e32 v56, 0x3d372713, v54
	v_mul_f32_e32 v57, 0x3d372713, v55
	v_mul_f32_e32 v56, v54, v56
	v_mul_f32_e32 v57, v55, v57
	v_fma_f32 v56, v54, v56, v54
	v_fma_f32 v57, v55, v57, v55
	v_mul_f32_e32 v56, 0x3f4c422a, v56
	v_mul_f32_e32 v57, 0x3f4c422a, v57
	v_mul_f32_e32 v56, 0xc038aa3b, v56
	v_mul_f32_e32 v57, 0xc038aa3b, v57
	v_exp_f32_e32 v56, v56
	v_exp_f32_e32 v57, v57
	v_cvt_pk_bf16_f32 v52, v52, v53
	v_add_f32_e32 v56, 1.0, v56
	v_add_f32_e32 v57, 1.0, v57
	v_rcp_f32_e32 v56, v56
	v_rcp_f32_e32 v57, v57
	s_nop 0
	v_pk_mul_f32 v[54:55], v[54:55], v[56:57]
	s_nop 0
	v_cvt_pk_bf16_f32 v53, v54, v55
	v_mul_f32_e32 v54, 0x3d372713, v48
	v_mul_f32_e32 v55, 0x3d372713, v49
	v_mul_f32_e32 v54, v48, v54
	v_mul_f32_e32 v55, v49, v55
	v_fma_f32 v54, v48, v54, v48
	v_fma_f32 v55, v49, v55, v49
	v_mul_f32_e32 v54, 0x3f4c422a, v54
	v_mul_f32_e32 v55, 0x3f4c422a, v55
	v_mul_f32_e32 v54, 0xc038aa3b, v54
	v_mul_f32_e32 v55, 0xc038aa3b, v55
	v_exp_f32_e32 v54, v54
	v_exp_f32_e32 v55, v55
	v_add_f32_e32 v54, 1.0, v54
	v_add_f32_e32 v55, 1.0, v55
	v_rcp_f32_e32 v54, v54
	v_rcp_f32_e32 v55, v55
	s_nop 0
	v_pk_mul_f32 v[48:49], v[48:49], v[54:55]
	v_mul_f32_e32 v54, 0x3d372713, v50
	v_mul_f32_e32 v55, 0x3d372713, v51
	v_mul_f32_e32 v54, v50, v54
	v_mul_f32_e32 v55, v51, v55
	v_fma_f32 v54, v50, v54, v50
	v_fma_f32 v55, v51, v55, v51
	v_mul_f32_e32 v54, 0x3f4c422a, v54
	v_mul_f32_e32 v55, 0x3f4c422a, v55
	v_mul_f32_e32 v54, 0xc038aa3b, v54
	v_mul_f32_e32 v55, 0xc038aa3b, v55
	v_exp_f32_e32 v54, v54
	v_exp_f32_e32 v55, v55
	v_cvt_pk_bf16_f32 v48, v48, v49
	v_add_f32_e32 v54, 1.0, v54
	v_add_f32_e32 v55, 1.0, v55
	v_rcp_f32_e32 v54, v54
	v_rcp_f32_e32 v55, v55
	s_nop 0
	v_pk_mul_f32 v[50:51], v[50:51], v[54:55]
	s_nop 0
	v_cvt_pk_bf16_f32 v49, v50, v51
	ds_write2_b64 v58, v[52:53], v[48:49] offset0:136 offset1:140
	ds_read_b32 v48, v127 offset:320
	s_waitcnt lgkmcnt(0)
	v_pk_mul_f32 v[44:45], v[44:45], v[48:49] op_sel_hi:[1,0]
	s_nop 0
	v_mul_f32_e32 v49, 0x3d372713, v44
	v_mul_f32_e32 v49, v44, v49
	v_fma_f32 v49, v44, v49, v44
	v_mul_f32_e32 v49, 0x3f4c422a, v49
	v_mul_f32_e32 v49, 0xc038aa3b, v49
	v_exp_f32_e32 v49, v49
	s_nop 0
	v_add_f32_e32 v49, 1.0, v49
	v_rcp_f32_e32 v50, v49
	v_mul_f32_e32 v49, 0x3d372713, v45
	v_mul_f32_e32 v49, v45, v49
	v_fma_f32 v49, v45, v49, v45
	v_mul_f32_e32 v49, 0x3f4c422a, v49
	v_mul_f32_e32 v49, 0xc038aa3b, v49
	v_exp_f32_e32 v49, v49
	s_nop 0
	v_add_f32_e32 v49, 1.0, v49
	v_pk_mul_f32 v[46:47], v[46:47], v[48:49] op_sel_hi:[1,0]
	v_rcp_f32_e32 v51, v49
	v_mul_f32_e32 v49, 0x3d372713, v46
	v_mul_f32_e32 v49, v46, v49
	v_fma_f32 v49, v46, v49, v46
	v_mul_f32_e32 v49, 0x3f4c422a, v49
	v_mul_f32_e32 v49, 0xc038aa3b, v49
	v_exp_f32_e32 v49, v49
	v_pk_mul_f32 v[44:45], v[44:45], v[50:51]
	v_add_f32_e32 v49, 1.0, v49
	v_rcp_f32_e32 v50, v49
	v_mul_f32_e32 v49, 0x3d372713, v47
	v_mul_f32_e32 v49, v47, v49
	v_fma_f32 v49, v47, v49, v47
	v_mul_f32_e32 v49, 0x3f4c422a, v49
	v_mul_f32_e32 v49, 0xc038aa3b, v49
	v_exp_f32_e32 v49, v49
	v_cvt_pk_bf16_f32 v44, v44, v45
	v_add_f32_e32 v49, 1.0, v49
	v_rcp_f32_e32 v51, v49
	v_pk_mul_f32 v[40:41], v[40:41], v[48:49] op_sel_hi:[1,0]
	v_pk_mul_f32 v[42:43], v[42:43], v[48:49] op_sel_hi:[1,0]
	v_pk_mul_f32 v[36:37], v[36:37], v[48:49] op_sel_hi:[1,0]
	v_pk_mul_f32 v[46:47], v[46:47], v[50:51]
	v_pk_mul_f32 v[38:39], v[38:39], v[48:49] op_sel_hi:[1,0]
	v_cvt_pk_bf16_f32 v45, v46, v47
	v_mul_f32_e32 v46, 0x3d372713, v40
	v_mul_f32_e32 v47, 0x3d372713, v41
	v_mul_f32_e32 v46, v40, v46
	v_mul_f32_e32 v47, v41, v47
	v_fma_f32 v46, v40, v46, v40
	v_fma_f32 v47, v41, v47, v41
	v_mul_f32_e32 v46, 0x3f4c422a, v46
	v_mul_f32_e32 v47, 0x3f4c422a, v47
	v_mul_f32_e32 v46, 0xc038aa3b, v46
	v_mul_f32_e32 v47, 0xc038aa3b, v47
	v_exp_f32_e32 v46, v46
	v_exp_f32_e32 v47, v47
	v_pk_mul_f32 v[32:33], v[32:33], v[48:49] op_sel_hi:[1,0]
	v_pk_mul_f32 v[34:35], v[34:35], v[48:49] op_sel_hi:[1,0]
	v_add_f32_e32 v46, 1.0, v46
	v_add_f32_e32 v47, 1.0, v47
	v_rcp_f32_e32 v46, v46
	v_rcp_f32_e32 v47, v47
	s_nop 0
	v_pk_mul_f32 v[40:41], v[40:41], v[46:47]
	v_mul_f32_e32 v46, 0x3d372713, v42
	v_mul_f32_e32 v47, 0x3d372713, v43
	v_mul_f32_e32 v46, v42, v46
	v_mul_f32_e32 v47, v43, v47
	v_fma_f32 v46, v42, v46, v42
	v_fma_f32 v47, v43, v47, v43
	v_mul_f32_e32 v46, 0x3f4c422a, v46
	v_mul_f32_e32 v47, 0x3f4c422a, v47
	v_mul_f32_e32 v46, 0xc038aa3b, v46
	v_mul_f32_e32 v47, 0xc038aa3b, v47
	v_exp_f32_e32 v46, v46
	v_exp_f32_e32 v47, v47
	v_cvt_pk_bf16_f32 v40, v40, v41
	v_add_f32_e32 v46, 1.0, v46
	v_add_f32_e32 v47, 1.0, v47
	v_rcp_f32_e32 v46, v46
	v_rcp_f32_e32 v47, v47
	s_nop 0
	v_pk_mul_f32 v[42:43], v[42:43], v[46:47]
	s_nop 0
	v_cvt_pk_bf16_f32 v41, v42, v43
	v_add_u32_e32 v42, 0xa000, v126
; DI unsigned pk2(float a, float b) { f32x2 v = {a, b}; bf16x2_t r = __builtin_convertvector(v, bf16x2_t); return __builtin_bit_cast(unsigned, r); }
;     DI void operator()(gacc_t& acc, int pm, int pn, char* lds, int tid, int wr, int wc, int lane) const {
;     ...
;         for (int m = 0; m < 8; ++m) {
;             const float r = rl[m * 16];
; #pragma unroll
;             for (int n = 0; n < 4; ++n) {
;                 float g[4];
; #pragma unroll
;                 for (int j = 0; j < 4; ++j) {
;                     const float x = acc[m][n][j] * r;
;                     const float u = 0.7978845608028654f * (x + 0.044715f * x * x * x);
;                     const float e = __builtin_amdgcn_exp2f(-2.885390081777927f * u);
;                     g[j] = x * __builtin_amdgcn_rcpf(1.0f + e);
;                 }
;                 u32x2 w; w.x = pk2(g[0], g[1]); w.y = pk2(g[2], g[3]);
;                 *(u32x2*)(lbase + m * 16 * 528 + n * 32) = w;
;             }
	ds_write2_b64 v42, v[44:45], v[40:41] offset0:160 offset1:164
	v_mul_f32_e32 v40, 0x3d372713, v36
	v_mul_f32_e32 v41, 0x3d372713, v37
	v_mul_f32_e32 v40, v36, v40
	v_mul_f32_e32 v41, v37, v41
	v_fma_f32 v40, v36, v40, v36
	v_fma_f32 v41, v37, v41, v37
	v_mul_f32_e32 v40, 0x3f4c422a, v40
	v_mul_f32_e32 v41, 0x3f4c422a, v41
	v_mul_f32_e32 v40, 0xc038aa3b, v40
	v_mul_f32_e32 v41, 0xc038aa3b, v41
	v_exp_f32_e32 v40, v40
	v_exp_f32_e32 v41, v41
	v_add_f32_e32 v40, 1.0, v40
	v_add_f32_e32 v41, 1.0, v41
	v_rcp_f32_e32 v40, v40
	v_rcp_f32_e32 v41, v41
	s_nop 0
	v_pk_mul_f32 v[36:37], v[36:37], v[40:41]
	v_mul_f32_e32 v40, 0x3d372713, v38
	v_mul_f32_e32 v41, 0x3d372713, v39
	v_mul_f32_e32 v40, v38, v40
	v_mul_f32_e32 v41, v39, v41
	v_fma_f32 v40, v38, v40, v38
	v_fma_f32 v41, v39, v41, v39
	v_mul_f32_e32 v40, 0x3f4c422a, v40
	v_mul_f32_e32 v41, 0x3f4c422a, v41
	v_mul_f32_e32 v40, 0xc038aa3b, v40
	v_mul_f32_e32 v41, 0xc038aa3b, v41
	v_exp_f32_e32 v40, v40
	v_exp_f32_e32 v41, v41
	v_cvt_pk_bf16_f32 v36, v36, v37
	v_add_f32_e32 v40, 1.0, v40
	v_add_f32_e32 v41, 1.0, v41
	v_rcp_f32_e32 v40, v40
	v_rcp_f32_e32 v41, v41
	s_nop 0
	v_pk_mul_f32 v[38:39], v[38:39], v[40:41]
	s_nop 0
	v_cvt_pk_bf16_f32 v37, v38, v39
	v_mul_f32_e32 v38, 0x3d372713, v32
	v_mul_f32_e32 v39, 0x3d372713, v33
	v_mul_f32_e32 v38, v32, v38
	v_mul_f32_e32 v39, v33, v39
	v_fma_f32 v38, v32, v38, v32
	v_fma_f32 v39, v33, v39, v33
	v_mul_f32_e32 v38, 0x3f4c422a, v38
	v_mul_f32_e32 v39, 0x3f4c422a, v39
	v_mul_f32_e32 v38, 0xc038aa3b, v38
	v_mul_f32_e32 v39, 0xc038aa3b, v39
	v_exp_f32_e32 v38, v38
	v_exp_f32_e32 v39, v39
	v_add_f32_e32 v38, 1.0, v38
	v_add_f32_e32 v39, 1.0, v39
	v_rcp_f32_e32 v38, v38
	v_rcp_f32_e32 v39, v39
	s_nop 0
	v_pk_mul_f32 v[32:33], v[32:33], v[38:39]
	v_mul_f32_e32 v38, 0x3d372713, v34
	v_mul_f32_e32 v39, 0x3d372713, v35
	v_mul_f32_e32 v38, v34, v38
	v_mul_f32_e32 v39, v35, v39
	v_fma_f32 v38, v34, v38, v34
	v_fma_f32 v39, v35, v39, v35
	v_mul_f32_e32 v38, 0x3f4c422a, v38
	v_mul_f32_e32 v39, 0x3f4c422a, v39
	v_mul_f32_e32 v38, 0xc038aa3b, v38
	v_mul_f32_e32 v39, 0xc038aa3b, v39
	v_exp_f32_e32 v38, v38
	v_exp_f32_e32 v39, v39
	v_cvt_pk_bf16_f32 v32, v32, v33
	v_add_f32_e32 v38, 1.0, v38
	v_add_f32_e32 v39, 1.0, v39
	v_rcp_f32_e32 v38, v38
	v_rcp_f32_e32 v39, v39
	s_nop 0
	v_pk_mul_f32 v[34:35], v[34:35], v[38:39]
	s_nop 0
	v_cvt_pk_bf16_f32 v33, v34, v35
	ds_write2_b64 v42, v[36:37], v[32:33] offset0:168 offset1:172
	ds_read_b32 v32, v127 offset:384
	s_waitcnt lgkmcnt(0)
	v_pk_mul_f32 v[28:29], v[28:29], v[32:33] op_sel_hi:[1,0]
	s_nop 0
	v_mul_f32_e32 v33, 0x3d372713, v28
	v_mul_f32_e32 v33, v28, v33
	v_fma_f32 v33, v28, v33, v28
	v_mul_f32_e32 v33, 0x3f4c422a, v33
	v_mul_f32_e32 v33, 0xc038aa3b, v33
	v_exp_f32_e32 v33, v33
	s_nop 0
	v_add_f32_e32 v33, 1.0, v33
	v_rcp_f32_e32 v34, v33
	v_mul_f32_e32 v33, 0x3d372713, v29
	v_mul_f32_e32 v33, v29, v33
	v_fma_f32 v33, v29, v33, v29
	v_mul_f32_e32 v33, 0x3f4c422a, v33
	v_mul_f32_e32 v33, 0xc038aa3b, v33
	v_exp_f32_e32 v33, v33
	s_nop 0
	v_add_f32_e32 v33, 1.0, v33
	v_pk_mul_f32 v[30:31], v[30:31], v[32:33] op_sel_hi:[1,0]
	v_rcp_f32_e32 v35, v33
	v_mul_f32_e32 v33, 0x3d372713, v30
	v_mul_f32_e32 v33, v30, v33
	v_fma_f32 v33, v30, v33, v30
	v_mul_f32_e32 v33, 0x3f4c422a, v33
	v_mul_f32_e32 v33, 0xc038aa3b, v33
	v_exp_f32_e32 v33, v33
	v_pk_mul_f32 v[28:29], v[28:29], v[34:35]
	v_add_f32_e32 v33, 1.0, v33
	v_rcp_f32_e32 v34, v33
	v_mul_f32_e32 v33, 0x3d372713, v31
	v_mul_f32_e32 v33, v31, v33
	v_fma_f32 v33, v31, v33, v31
	v_mul_f32_e32 v33, 0x3f4c422a, v33
	v_mul_f32_e32 v33, 0xc038aa3b, v33
	v_exp_f32_e32 v33, v33
	v_cvt_pk_bf16_f32 v28, v28, v29
	v_add_f32_e32 v33, 1.0, v33
	v_rcp_f32_e32 v35, v33
	v_pk_mul_f32 v[24:25], v[24:25], v[32:33] op_sel_hi:[1,0]
	v_pk_mul_f32 v[26:27], v[26:27], v[32:33] op_sel_hi:[1,0]
	v_pk_mul_f32 v[20:21], v[20:21], v[32:33] op_sel_hi:[1,0]
	v_pk_mul_f32 v[30:31], v[30:31], v[34:35]
	v_pk_mul_f32 v[22:23], v[22:23], v[32:33] op_sel_hi:[1,0]
	v_cvt_pk_bf16_f32 v29, v30, v31
	v_mul_f32_e32 v30, 0x3d372713, v24
	v_mul_f32_e32 v31, 0x3d372713, v25
	v_mul_f32_e32 v30, v24, v30
	v_mul_f32_e32 v31, v25, v31
	v_fma_f32 v30, v24, v30, v24
	v_fma_f32 v31, v25, v31, v25
	v_mul_f32_e32 v30, 0x3f4c422a, v30
	v_mul_f32_e32 v31, 0x3f4c422a, v31
	v_mul_f32_e32 v30, 0xc038aa3b, v30
	v_mul_f32_e32 v31, 0xc038aa3b, v31
	v_exp_f32_e32 v30, v30
	v_exp_f32_e32 v31, v31
	v_pk_mul_f32 v[16:17], v[16:17], v[32:33] op_sel_hi:[1,0]
	v_pk_mul_f32 v[18:19], v[18:19], v[32:33] op_sel_hi:[1,0]
	v_add_f32_e32 v30, 1.0, v30
	v_add_f32_e32 v31, 1.0, v31
	v_rcp_f32_e32 v30, v30
	v_rcp_f32_e32 v31, v31
	s_nop 0
	v_pk_mul_f32 v[24:25], v[24:25], v[30:31]
	v_mul_f32_e32 v30, 0x3d372713, v26
	v_mul_f32_e32 v31, 0x3d372713, v27
	v_mul_f32_e32 v30, v26, v30
	v_mul_f32_e32 v31, v27, v31
	v_fma_f32 v30, v26, v30, v26
	v_fma_f32 v31, v27, v31, v27
	v_mul_f32_e32 v30, 0x3f4c422a, v30
	v_mul_f32_e32 v31, 0x3f4c422a, v31
	v_mul_f32_e32 v30, 0xc038aa3b, v30
	v_mul_f32_e32 v31, 0xc038aa3b, v31
	v_exp_f32_e32 v30, v30
	v_exp_f32_e32 v31, v31
	v_cvt_pk_bf16_f32 v24, v24, v25
	v_add_f32_e32 v30, 1.0, v30
	v_add_f32_e32 v31, 1.0, v31
	v_rcp_f32_e32 v30, v30
	v_rcp_f32_e32 v31, v31
	s_nop 0
	v_pk_mul_f32 v[26:27], v[26:27], v[30:31]
	s_nop 0
	v_cvt_pk_bf16_f32 v25, v26, v27
	v_add_u32_e32 v26, 0xc000, v126
	ds_write2_b64 v26, v[28:29], v[24:25] offset0:192 offset1:196
	v_mul_f32_e32 v24, 0x3d372713, v20
	v_mul_f32_e32 v25, 0x3d372713, v21
	v_mul_f32_e32 v24, v20, v24
	v_mul_f32_e32 v25, v21, v25
	v_fma_f32 v24, v20, v24, v20
	v_fma_f32 v25, v21, v25, v21
	v_mul_f32_e32 v24, 0x3f4c422a, v24
	v_mul_f32_e32 v25, 0x3f4c422a, v25
; DI unsigned pk2(float a, float b) { f32x2 v = {a, b}; bf16x2_t r = __builtin_convertvector(v, bf16x2_t); return __builtin_bit_cast(unsigned, r); }
;     DI void operator()(gacc_t& acc, int pm, int pn, char* lds, int tid, int wr, int wc, int lane) const {
;     ...
;         for (int m = 0; m < 8; ++m) {
;             const float r = rl[m * 16];
; #pragma unroll
;             for (int n = 0; n < 4; ++n) {
;                 float g[4];
; #pragma unroll
;                 for (int j = 0; j < 4; ++j) {
;                     const float x = acc[m][n][j] * r;
;                     const float u = 0.7978845608028654f * (x + 0.044715f * x * x * x);
;                     const float e = __builtin_amdgcn_exp2f(-2.885390081777927f * u);
;                     g[j] = x * __builtin_amdgcn_rcpf(1.0f + e);
;                 }
;                 u32x2 w; w.x = pk2(g[0], g[1]); w.y = pk2(g[2], g[3]);
;                 *(u32x2*)(lbase + m * 16 * 528 + n * 32) = w;
;             }
	v_mul_f32_e32 v24, 0xc038aa3b, v24
	v_mul_f32_e32 v25, 0xc038aa3b, v25
	v_exp_f32_e32 v24, v24
	v_exp_f32_e32 v25, v25
	v_add_f32_e32 v24, 1.0, v24
	v_add_f32_e32 v25, 1.0, v25
	v_rcp_f32_e32 v24, v24
	v_rcp_f32_e32 v25, v25
	s_nop 0
	v_pk_mul_f32 v[20:21], v[20:21], v[24:25]
	v_mul_f32_e32 v24, 0x3d372713, v22
	v_mul_f32_e32 v25, 0x3d372713, v23
	v_mul_f32_e32 v24, v22, v24
	v_mul_f32_e32 v25, v23, v25
	v_fma_f32 v24, v22, v24, v22
	v_fma_f32 v25, v23, v25, v23
	v_mul_f32_e32 v24, 0x3f4c422a, v24
	v_mul_f32_e32 v25, 0x3f4c422a, v25
	v_mul_f32_e32 v24, 0xc038aa3b, v24
	v_mul_f32_e32 v25, 0xc038aa3b, v25
	v_exp_f32_e32 v24, v24
	v_exp_f32_e32 v25, v25
	v_cvt_pk_bf16_f32 v20, v20, v21
	v_add_f32_e32 v24, 1.0, v24
	v_add_f32_e32 v25, 1.0, v25
	v_rcp_f32_e32 v24, v24
	v_rcp_f32_e32 v25, v25
	s_nop 0
	v_pk_mul_f32 v[22:23], v[22:23], v[24:25]
	s_nop 0
	v_cvt_pk_bf16_f32 v21, v22, v23
	v_mul_f32_e32 v22, 0x3d372713, v16
	v_mul_f32_e32 v23, 0x3d372713, v17
	v_mul_f32_e32 v22, v16, v22
	v_mul_f32_e32 v23, v17, v23
	v_fma_f32 v22, v16, v22, v16
	v_fma_f32 v23, v17, v23, v17
	v_mul_f32_e32 v22, 0x3f4c422a, v22
	v_mul_f32_e32 v23, 0x3f4c422a, v23
	v_mul_f32_e32 v22, 0xc038aa3b, v22
	v_mul_f32_e32 v23, 0xc038aa3b, v23
	v_exp_f32_e32 v22, v22
	v_exp_f32_e32 v23, v23
	v_add_f32_e32 v22, 1.0, v22
	v_add_f32_e32 v23, 1.0, v23
	v_rcp_f32_e32 v22, v22
	v_rcp_f32_e32 v23, v23
	s_nop 0
	v_pk_mul_f32 v[16:17], v[16:17], v[22:23]
	v_mul_f32_e32 v22, 0x3d372713, v18
	v_mul_f32_e32 v23, 0x3d372713, v19
	v_mul_f32_e32 v22, v18, v22
	v_mul_f32_e32 v23, v19, v23
	v_fma_f32 v22, v18, v22, v18
	v_fma_f32 v23, v19, v23, v19
	v_mul_f32_e32 v22, 0x3f4c422a, v22
	v_mul_f32_e32 v23, 0x3f4c422a, v23
	v_mul_f32_e32 v22, 0xc038aa3b, v22
	v_mul_f32_e32 v23, 0xc038aa3b, v23
	v_exp_f32_e32 v22, v22
	v_exp_f32_e32 v23, v23
	v_cvt_pk_bf16_f32 v16, v16, v17
	v_add_f32_e32 v22, 1.0, v22
	v_add_f32_e32 v23, 1.0, v23
	v_rcp_f32_e32 v22, v22
	v_rcp_f32_e32 v23, v23
	s_nop 0
	v_pk_mul_f32 v[18:19], v[18:19], v[22:23]
	s_nop 0
	v_cvt_pk_bf16_f32 v17, v18, v19
	ds_write2_b64 v26, v[20:21], v[16:17] offset0:200 offset1:204
	ds_read_b32 v16, v127 offset:448
	s_waitcnt lgkmcnt(0)
	v_pk_mul_f32 v[12:13], v[12:13], v[16:17] op_sel_hi:[1,0]
	s_nop 0
	v_mul_f32_e32 v17, 0x3d372713, v12
	v_mul_f32_e32 v17, v12, v17
	v_fma_f32 v17, v12, v17, v12
	v_mul_f32_e32 v17, 0x3f4c422a, v17
	v_mul_f32_e32 v17, 0xc038aa3b, v17
	v_exp_f32_e32 v17, v17
	s_nop 0
	v_add_f32_e32 v17, 1.0, v17
	v_rcp_f32_e32 v18, v17
	v_mul_f32_e32 v17, 0x3d372713, v13
	v_mul_f32_e32 v17, v13, v17
	v_fma_f32 v17, v13, v17, v13
	v_mul_f32_e32 v17, 0x3f4c422a, v17
	v_mul_f32_e32 v17, 0xc038aa3b, v17
	v_exp_f32_e32 v17, v17
	s_nop 0
	v_add_f32_e32 v17, 1.0, v17
	v_pk_mul_f32 v[14:15], v[14:15], v[16:17] op_sel_hi:[1,0]
	v_rcp_f32_e32 v19, v17
	v_mul_f32_e32 v17, 0x3d372713, v14
	v_mul_f32_e32 v17, v14, v17
	v_fma_f32 v17, v14, v17, v14
	v_mul_f32_e32 v17, 0x3f4c422a, v17
	v_mul_f32_e32 v17, 0xc038aa3b, v17
	v_exp_f32_e32 v17, v17
	v_pk_mul_f32 v[12:13], v[12:13], v[18:19]
	v_add_f32_e32 v17, 1.0, v17
	v_rcp_f32_e32 v18, v17
	v_mul_f32_e32 v17, 0x3d372713, v15
	v_mul_f32_e32 v17, v15, v17
	v_fma_f32 v17, v15, v17, v15
	v_mul_f32_e32 v17, 0x3f4c422a, v17
	v_mul_f32_e32 v17, 0xc038aa3b, v17
	v_exp_f32_e32 v17, v17
	v_cvt_pk_bf16_f32 v12, v12, v13
	v_add_f32_e32 v17, 1.0, v17
	v_rcp_f32_e32 v19, v17
	v_pk_mul_f32 v[8:9], v[8:9], v[16:17] op_sel_hi:[1,0]
	v_pk_mul_f32 v[10:11], v[10:11], v[16:17] op_sel_hi:[1,0]
	v_pk_mul_f32 v[4:5], v[4:5], v[16:17] op_sel_hi:[1,0]
	v_pk_mul_f32 v[14:15], v[14:15], v[18:19]
	v_pk_mul_f32 v[6:7], v[6:7], v[16:17] op_sel_hi:[1,0]
	v_cvt_pk_bf16_f32 v13, v14, v15
	v_mul_f32_e32 v14, 0x3d372713, v8
	v_mul_f32_e32 v15, 0x3d372713, v9
	v_mul_f32_e32 v14, v8, v14
	v_mul_f32_e32 v15, v9, v15
	v_fma_f32 v14, v8, v14, v8
	v_fma_f32 v15, v9, v15, v9
	v_mul_f32_e32 v14, 0x3f4c422a, v14
	v_mul_f32_e32 v15, 0x3f4c422a, v15
	v_mul_f32_e32 v14, 0xc038aa3b, v14
	v_mul_f32_e32 v15, 0xc038aa3b, v15
	v_exp_f32_e32 v14, v14
	v_exp_f32_e32 v15, v15
	v_pk_mul_f32 v[0:1], v[0:1], v[16:17] op_sel_hi:[1,0]
	v_pk_mul_f32 v[2:3], v[2:3], v[16:17] op_sel_hi:[1,0]
	v_add_f32_e32 v14, 1.0, v14
	v_add_f32_e32 v15, 1.0, v15
	v_rcp_f32_e32 v14, v14
	v_rcp_f32_e32 v15, v15
	s_nop 0
	v_pk_mul_f32 v[8:9], v[8:9], v[14:15]
	v_mul_f32_e32 v14, 0x3d372713, v10
	v_mul_f32_e32 v15, 0x3d372713, v11
	v_mul_f32_e32 v14, v10, v14
	v_mul_f32_e32 v15, v11, v15
	v_fma_f32 v14, v10, v14, v10
	v_fma_f32 v15, v11, v15, v11
	v_mul_f32_e32 v14, 0x3f4c422a, v14
	v_mul_f32_e32 v15, 0x3f4c422a, v15
	v_mul_f32_e32 v14, 0xc038aa3b, v14
	v_mul_f32_e32 v15, 0xc038aa3b, v15
	v_exp_f32_e32 v14, v14
	v_exp_f32_e32 v15, v15
	v_cvt_pk_bf16_f32 v8, v8, v9
	v_add_f32_e32 v14, 1.0, v14
	v_add_f32_e32 v15, 1.0, v15
	v_rcp_f32_e32 v14, v14
	v_rcp_f32_e32 v15, v15
	s_nop 0
	v_pk_mul_f32 v[10:11], v[10:11], v[14:15]
	s_nop 0
	v_cvt_pk_bf16_f32 v9, v10, v11
	v_add_u32_e32 v10, 0xe000, v126
	ds_write2_b64 v10, v[12:13], v[8:9] offset0:224 offset1:228
	v_mul_f32_e32 v8, 0x3d372713, v4
	v_mul_f32_e32 v9, 0x3d372713, v5
	v_mul_f32_e32 v8, v4, v8
	v_mul_f32_e32 v9, v5, v9
	v_fma_f32 v8, v4, v8, v4
	v_fma_f32 v9, v5, v9, v5
	v_mul_f32_e32 v8, 0x3f4c422a, v8
	v_mul_f32_e32 v9, 0x3f4c422a, v9
	v_mul_f32_e32 v8, 0xc038aa3b, v8
	v_mul_f32_e32 v9, 0xc038aa3b, v9
	v_exp_f32_e32 v8, v8
	v_exp_f32_e32 v9, v9
	v_add_f32_e32 v8, 1.0, v8
	v_add_f32_e32 v9, 1.0, v9
	v_rcp_f32_e32 v8, v8
	v_rcp_f32_e32 v9, v9
	s_nop 0
	v_pk_mul_f32 v[4:5], v[4:5], v[8:9]
	v_mul_f32_e32 v8, 0x3d372713, v6
	v_mul_f32_e32 v9, 0x3d372713, v7
	v_mul_f32_e32 v8, v6, v8
	v_mul_f32_e32 v9, v7, v9
	v_fma_f32 v8, v6, v8, v6
; DI unsigned pk2(float a, float b) { f32x2 v = {a, b}; bf16x2_t r = __builtin_convertvector(v, bf16x2_t); return __builtin_bit_cast(unsigned, r); }
; DI void store_tile_from_lds(const char* lds, bf16_t* dst, long ld, int tid) {
;     ...
;     for (int k = 0; k < 16; ++k) {
;         const int id = tid + NTH * k, row = id >> 5, ch = id & 31;
;         const u32x4 v = *(const u32x4*)(lds + row * 528 + ch * 16);
;         *(u32x4*)(dst + (long)row * ld + ch * 8) = v;
;     DI void operator()(gacc_t& acc, int pm, int pn, char* lds, int tid, int wr, int wc, int lane) const {
;     ...
;                 for (int j = 0; j < 4; ++j) {
;                     const float x = acc[m][n][j] * r;
;                     const float u = 0.7978845608028654f * (x + 0.044715f * x * x * x);
;                     const float e = __builtin_amdgcn_exp2f(-2.885390081777927f * u);
;                     g[j] = x * __builtin_amdgcn_rcpf(1.0f + e);
;                 }
;                 u32x2 w; w.x = pk2(g[0], g[1]); w.y = pk2(g[2], g[3]);
;                 *(u32x2*)(lbase + m * 16 * 528 + n * 32) = w;
;             }
;             __builtin_amdgcn_sched_barrier(0);
;         }
;         __syncthreads();
;         store_tile_from_lds(lds, z + (long)pm * 256 * 2048 + pn * 256, 2048, tid);
	v_fma_f32 v9, v7, v9, v7
	v_mul_f32_e32 v8, 0x3f4c422a, v8
	v_mul_f32_e32 v9, 0x3f4c422a, v9
	v_mul_f32_e32 v8, 0xc038aa3b, v8
	v_mul_f32_e32 v9, 0xc038aa3b, v9
	v_exp_f32_e32 v8, v8
	v_exp_f32_e32 v9, v9
	v_cvt_pk_bf16_f32 v4, v4, v5
	v_add_f32_e32 v8, 1.0, v8
	v_add_f32_e32 v9, 1.0, v9
	v_rcp_f32_e32 v8, v8
	v_rcp_f32_e32 v9, v9
	s_nop 0
	v_pk_mul_f32 v[6:7], v[6:7], v[8:9]
	s_nop 0
	v_cvt_pk_bf16_f32 v5, v6, v7
	v_mul_f32_e32 v6, 0x3d372713, v0
	v_mul_f32_e32 v7, 0x3d372713, v1
	v_mul_f32_e32 v6, v0, v6
	v_mul_f32_e32 v7, v1, v7
	v_fma_f32 v6, v0, v6, v0
	v_fma_f32 v7, v1, v7, v1
	v_mul_f32_e32 v6, 0x3f4c422a, v6
	v_mul_f32_e32 v7, 0x3f4c422a, v7
	v_mul_f32_e32 v6, 0xc038aa3b, v6
	v_mul_f32_e32 v7, 0xc038aa3b, v7
	v_exp_f32_e32 v6, v6
	v_exp_f32_e32 v7, v7
	v_add_f32_e32 v6, 1.0, v6
	v_add_f32_e32 v7, 1.0, v7
	v_rcp_f32_e32 v6, v6
	v_rcp_f32_e32 v7, v7
	s_nop 0
	v_pk_mul_f32 v[0:1], v[0:1], v[6:7]
	v_mul_f32_e32 v6, 0x3d372713, v2
	v_mul_f32_e32 v7, 0x3d372713, v3
	v_mul_f32_e32 v6, v2, v6
	v_mul_f32_e32 v7, v3, v7
	v_fma_f32 v6, v2, v6, v2
	v_fma_f32 v7, v3, v7, v3
	v_mul_f32_e32 v6, 0x3f4c422a, v6
	v_mul_f32_e32 v7, 0x3f4c422a, v7
	v_mul_f32_e32 v6, 0xc038aa3b, v6
	v_mul_f32_e32 v7, 0xc038aa3b, v7
	v_exp_f32_e32 v6, v6
	v_exp_f32_e32 v7, v7
	v_cvt_pk_bf16_f32 v0, v0, v1
	v_add_f32_e32 v6, 1.0, v6
	v_add_f32_e32 v7, 1.0, v7
	v_rcp_f32_e32 v6, v6
	v_rcp_f32_e32 v7, v7
	s_nop 0
	v_pk_mul_f32 v[2:3], v[2:3], v[6:7]
	s_nop 0
	v_cvt_pk_bf16_f32 v1, v2, v3
	ds_write2_b64 v10, v[4:5], v[0:1] offset0:232 offset1:236
	s_lshl_b64 s[8:9], s[8:9], 20
	s_add_u32 s8, s70, s8
	s_addc_u32 s9, s71, s9
	s_lshl_b32 s6, s6, 8
	s_ashr_i32 s7, s6, 31
	v_lshlrev_b32_e32 v0, 4, v125
	s_lshl_b64 s[6:7], s[6:7], 1
	v_and_b32_e32 v146, 0x1f0, v0
	s_add_u32 s6, s8, s6
	v_add_u32_e32 v4, 0, v146
	v_ashrrev_i32_e32 v6, 5, v125
	s_addc_u32 s7, s9, s7
	v_mad_u64_u32 v[0:1], s[8:9], v6, s3, v[4:5]
	s_waitcnt lgkmcnt(0)
	s_barrier
	ds_read_b128 v[0:3], v0
	v_ashrrev_i32_e32 v7, 31, v6
	v_lshl_add_u64 v[8:9], s[6:7], 0, v[146:147]
	v_lshlrev_b64 v[6:7], 12, v[6:7]
	v_lshl_add_u64 v[6:7], v[8:9], 0, v[6:7]
	s_waitcnt lgkmcnt(0)
	flat_store_dwordx4 v[6:7], v[0:3]
	s_add_i32 s17, s17, 1
	s_nop 0
	v_add_u32_e32 v0, 0x200, v125
	v_ashrrev_i32_e32 v6, 5, v0
	v_mad_u64_u32 v[0:1], s[6:7], v6, s3, v[4:5]
	ds_read_b128 v[0:3], v0
	v_ashrrev_i32_e32 v7, 31, v6
	v_lshlrev_b64 v[6:7], 12, v[6:7]
	v_lshl_add_u64 v[6:7], v[8:9], 0, v[6:7]
	s_waitcnt lgkmcnt(0)
	flat_store_dwordx4 v[6:7], v[0:3]
	s_nop 1
	v_add_u32_e32 v0, 0x400, v125
	v_ashrrev_i32_e32 v6, 5, v0
	v_mad_u64_u32 v[0:1], s[6:7], v6, s3, v[4:5]
	ds_read_b128 v[0:3], v0
	v_ashrrev_i32_e32 v7, 31, v6
	v_lshlrev_b64 v[6:7], 12, v[6:7]
	v_lshl_add_u64 v[6:7], v[8:9], 0, v[6:7]
	s_waitcnt lgkmcnt(0)
	flat_store_dwordx4 v[6:7], v[0:3]
	s_nop 1
	v_add_u32_e32 v0, 0x600, v125
	v_ashrrev_i32_e32 v6, 5, v0
	v_mad_u64_u32 v[0:1], s[6:7], v6, s3, v[4:5]
	ds_read_b128 v[0:3], v0
	v_ashrrev_i32_e32 v7, 31, v6
	v_lshlrev_b64 v[6:7], 12, v[6:7]
	v_lshl_add_u64 v[6:7], v[8:9], 0, v[6:7]
	s_waitcnt lgkmcnt(0)
	flat_store_dwordx4 v[6:7], v[0:3]
	s_nop 1
	v_add_u32_e32 v0, 0x800, v125
	v_ashrrev_i32_e32 v6, 5, v0
	v_mad_u64_u32 v[0:1], s[6:7], v6, s3, v[4:5]
	ds_read_b128 v[0:3], v0
	v_ashrrev_i32_e32 v7, 31, v6
	v_lshlrev_b64 v[6:7], 12, v[6:7]
	v_lshl_add_u64 v[6:7], v[8:9], 0, v[6:7]
	s_waitcnt lgkmcnt(0)
	flat_store_dwordx4 v[6:7], v[0:3]
	s_nop 1
	v_add_u32_e32 v0, 0xa00, v125
	v_ashrrev_i32_e32 v6, 5, v0
	v_mad_u64_u32 v[0:1], s[6:7], v6, s3, v[4:5]
	ds_read_b128 v[0:3], v0
	v_ashrrev_i32_e32 v7, 31, v6
	v_lshlrev_b64 v[6:7], 12, v[6:7]
	v_lshl_add_u64 v[6:7], v[8:9], 0, v[6:7]
	s_waitcnt lgkmcnt(0)
	flat_store_dwordx4 v[6:7], v[0:3]
	s_nop 1
	v_add_u32_e32 v0, 0xc00, v125
	v_ashrrev_i32_e32 v6, 5, v0
	v_mad_u64_u32 v[0:1], s[6:7], v6, s3, v[4:5]
	ds_read_b128 v[0:3], v0
	v_ashrrev_i32_e32 v7, 31, v6
	v_lshlrev_b64 v[6:7], 12, v[6:7]
	v_lshl_add_u64 v[6:7], v[8:9], 0, v[6:7]
	s_waitcnt lgkmcnt(0)
	flat_store_dwordx4 v[6:7], v[0:3]
	s_nop 1
	v_add_u32_e32 v0, 0xe00, v125
	v_ashrrev_i32_e32 v6, 5, v0
	v_mad_u64_u32 v[0:1], s[6:7], v6, s3, v[4:5]
	ds_read_b128 v[0:3], v0
	v_ashrrev_i32_e32 v7, 31, v6
	v_lshlrev_b64 v[6:7], 12, v[6:7]
	v_lshl_add_u64 v[6:7], v[8:9], 0, v[6:7]
	s_waitcnt lgkmcnt(0)
	flat_store_dwordx4 v[6:7], v[0:3]
	s_nop 1
	v_add_u32_e32 v0, 0x1000, v125
	v_ashrrev_i32_e32 v6, 5, v0
	v_mad_u64_u32 v[0:1], s[6:7], v6, s3, v[4:5]
	ds_read_b128 v[0:3], v0
	v_ashrrev_i32_e32 v7, 31, v6
	v_lshlrev_b64 v[6:7], 12, v[6:7]
	v_lshl_add_u64 v[6:7], v[8:9], 0, v[6:7]
	s_waitcnt lgkmcnt(0)
	flat_store_dwordx4 v[6:7], v[0:3]
	s_nop 1
	v_add_u32_e32 v0, 0x1200, v125
	v_ashrrev_i32_e32 v6, 5, v0
	v_mad_u64_u32 v[0:1], s[6:7], v6, s3, v[4:5]
	ds_read_b128 v[0:3], v0
	v_ashrrev_i32_e32 v7, 31, v6
	v_lshlrev_b64 v[6:7], 12, v[6:7]
	v_lshl_add_u64 v[6:7], v[8:9], 0, v[6:7]
	s_waitcnt lgkmcnt(0)
	flat_store_dwordx4 v[6:7], v[0:3]
	s_nop 1
	v_add_u32_e32 v0, 0x1400, v125
	v_ashrrev_i32_e32 v6, 5, v0
	v_mad_u64_u32 v[0:1], s[6:7], v6, s3, v[4:5]
	ds_read_b128 v[0:3], v0
	v_ashrrev_i32_e32 v7, 31, v6
	v_lshlrev_b64 v[6:7], 12, v[6:7]
	v_lshl_add_u64 v[6:7], v[8:9], 0, v[6:7]
	s_waitcnt lgkmcnt(0)
	flat_store_dwordx4 v[6:7], v[0:3]
	s_nop 1
	v_add_u32_e32 v0, 0x1600, v125
	v_ashrrev_i32_e32 v6, 5, v0
	v_mad_u64_u32 v[0:1], s[6:7], v6, s3, v[4:5]
	ds_read_b128 v[0:3], v0
	v_ashrrev_i32_e32 v7, 31, v6
	v_lshlrev_b64 v[6:7], 12, v[6:7]
	v_lshl_add_u64 v[6:7], v[8:9], 0, v[6:7]
	s_waitcnt lgkmcnt(0)
	flat_store_dwordx4 v[6:7], v[0:3]
	s_nop 1
	v_add_u32_e32 v0, 0x1800, v125
	v_ashrrev_i32_e32 v6, 5, v0
	v_mad_u64_u32 v[0:1], s[6:7], v6, s3, v[4:5]
	ds_read_b128 v[0:3], v0
	v_ashrrev_i32_e32 v7, 31, v6
	v_lshlrev_b64 v[6:7], 12, v[6:7]
	v_lshl_add_u64 v[6:7], v[8:9], 0, v[6:7]
	s_waitcnt lgkmcnt(0)
	flat_store_dwordx4 v[6:7], v[0:3]
	s_nop 1
	v_add_u32_e32 v0, 0x1a00, v125
	v_ashrrev_i32_e32 v6, 5, v0
	v_mad_u64_u32 v[0:1], s[6:7], v6, s3, v[4:5]
	ds_read_b128 v[0:3], v0
	v_ashrrev_i32_e32 v7, 31, v6
	v_lshlrev_b64 v[6:7], 12, v[6:7]
	v_lshl_add_u64 v[6:7], v[8:9], 0, v[6:7]
	s_waitcnt lgkmcnt(0)
	flat_store_dwordx4 v[6:7], v[0:3]
	s_nop 1
	v_add_u32_e32 v0, 0x1c00, v125
	v_ashrrev_i32_e32 v6, 5, v0
	v_mad_u64_u32 v[0:1], s[6:7], v6, s3, v[4:5]
	ds_read_b128 v[0:3], v0
	v_ashrrev_i32_e32 v7, 31, v6
	v_lshlrev_b64 v[6:7], 12, v[6:7]
	v_lshl_add_u64 v[6:7], v[8:9], 0, v[6:7]
	s_waitcnt lgkmcnt(0)
	flat_store_dwordx4 v[6:7], v[0:3]
	s_nop 1
	v_add_u32_e32 v0, 0x1e00, v125
	v_ashrrev_i32_e32 v6, 5, v0
	v_mad_u64_u32 v[0:1], s[6:7], v6, s3, v[4:5]
	ds_read_b128 v[0:3], v0
	v_ashrrev_i32_e32 v7, 31, v6
	s_mul_i32 s6, s17, s28
	v_lshlrev_b64 v[4:5], 12, v[6:7]
	s_add_i32 s6, s6, s2
	v_lshl_add_u64 v[4:5], v[8:9], 0, v[4:5]
	s_cmpk_lt_i32 s6, 0xa00
	s_waitcnt lgkmcnt(0)
	flat_store_dwordx4 v[4:5], v[0:3]
	s_waitcnt lgkmcnt(0)
	s_barrier
	s_cbranch_scc1 .LBB0_370

; #define MFMA16(a, b, c) __builtin_amdgcn_mfma_f32_16x16x32_bf16((a), (b), (c), 0, 0, 0)
; DI bf16x8 ldfrag(const char* lds, int row, int chunk) { return *(const bf16x8*)(lds + swz(row, chunk)); }
; template <bool RSTD, bool SWAP>
; DI void gemm_tile(gacc_t& acc, const bf16_t* __restrict__ A, int lda, const bf16_t* __restrict__ Bt, int ldb, int K,
;                   char* lds, int tid, int wr, int wc, int lane, const float* ssq_row) {
;     ...
;     for (int kt = 0; kt < nk; ++kt) {
;         const char* cur = lds + (kt & 1) * 65536;
;         if (kt + 1 < nk) GEMM_ISSUE(kt + 1, (kt + 1) & 1);
;         bf16x8 bfr[2][4], afr[3];
; #pragma unroll
;         for (int n = 0; n < 4; ++n) bfr[0][n] = ldfrag(cur + 32768, wc * 64 + n * 16 + fr, fq);
;         afr[0] = ldfrag(cur, wr * 128 + fr, fq);
;         afr[1] = ldfrag(cur, wr * 128 + 16 + fr, fq);
; #pragma unroll
;         for (int idx = 0; idx < 16; ++idx) {
;             const int ks = idx >> 3, m = idx & 7;
;             if (idx < 14) afr[(idx + 2) % 3] = ldfrag(cur, wr * 128 + ((idx + 2) & 7) * 16 + fr, ((idx + 2) >> 3) * 4 + fq);
;             if (ks == 0 && m >= 2 && m < 6) bfr[1][m - 2] = ldfrag(cur + 32768, wc * 64 + (m - 2) * 16 + fr, 4 + fq);
; #pragma unroll
;             for (int n = 0; n < 4; ++n) acc[m][n] = SWAP ? MFMA16(bfr[ks][n], afr[idx % 3], acc[m][n]) : MFMA16(afr[idx % 3], bfr[ks][n], acc[m][n]);
;         }
.LBB0_523:
	v_lshl_add_u64 v[158:159], v[136:137], 0, s[4:5]
	s_mov_b64 s[18:19], 0x800080
	v_lshl_add_u64 v[162:163], v[158:159], 0, s[18:19]
	s_mov_b64 s[18:19], 0x820080
	s_add_i32 s16, s13, 0xffff0000
	s_and_b32 s17, s13, 0x10000
	v_lshl_add_u64 v[166:167], v[158:159], 0, s[18:19]
	s_mov_b64 s[18:19], 0x840080
	s_and_b32 s21, s16, 0x10000
	s_add_i32 s16, s17, 0
	v_lshl_add_u64 v[174:175], v[158:159], 0, s[18:19]
	s_mov_b64 s[18:19], 0x860080
	v_lshl_add_u64 v[156:157], v[138:139], 0, s[4:5]
	v_lshl_add_u64 v[158:159], v[158:159], 0, s[18:19]
	s_add_i32 s18, s16, s12
	v_lshl_add_u64 v[160:161], v[156:157], 0, s[14:15]
	s_add_i32 s19, s18, 0x8000
	s_mov_b32 m0, s18
	v_lshl_add_u64 v[164:165], v[156:157], 0, s[72:73]
	global_load_lds_dwordx4 v[160:161], off
	v_mfma_f32_16x16x32_bf16 v[60:63], v[202:205], v[236:239], v[60:63]
	s_mov_b32 m0, s19
	v_lshl_add_u64 v[172:173], v[156:157], 0, s[76:77]
	global_load_lds_dwordx4 v[162:163], off
	v_mfma_f32_16x16x32_bf16 v[56:59], v[206:209], v[236:239], v[56:59]
	s_add_i32 m0, s18, 0x2000
	v_lshl_add_u64 v[156:157], v[156:157], 0, s[0:1]
	global_load_lds_dwordx4 v[164:165], off
	v_mfma_f32_16x16x32_bf16 v[52:55], v[210:213], v[236:239], v[52:55]
	s_add_i32 m0, s18, 0xa000
	s_add_i32 s17, s21, 0
	global_load_lds_dwordx4 v[166:167], off
	v_mfma_f32_16x16x32_bf16 v[48:51], v[214:217], v[236:239], v[48:51]
	s_add_i32 m0, s18, 0x4000
	v_add_u32_e32 v146, s17, v142
	global_load_lds_dwordx4 v[172:173], off
	v_mfma_f32_16x16x32_bf16 v[44:47], v[202:205], v[240:243], v[44:47]
	s_add_i32 m0, s18, 0xc000
	v_add3_u32 v155, v146, v148, v149
	global_load_lds_dwordx4 v[174:175], off
	v_mfma_f32_16x16x32_bf16 v[40:43], v[206:209], v[240:243], v[40:43]
	s_add_i32 m0, s18, 0x6000
	v_add_u32_e32 v176, v146, v144
	global_load_lds_dwordx4 v[156:157], off
	v_mfma_f32_16x16x32_bf16 v[36:39], v[210:213], v[240:243], v[36:39]
	s_add_i32 m0, s18, 0xe000
	s_nop 0
	global_load_lds_dwordx4 v[158:159], off
	v_mfma_f32_16x16x32_bf16 v[32:35], v[214:217], v[240:243], v[32:35]
	ds_read_b128 v[156:159], v155 offset:32768
	ds_read_b128 v[160:163], v155 offset:34816
	ds_read_b128 v[186:189], v155 offset:36864
	ds_read_b128 v[190:193], v155 offset:38912
	ds_read_b128 v[164:167], v176
	ds_read_b128 v[194:197], v176 offset:2048
	v_add_u32_e32 v155, v146, v150
	ds_read_b128 v[198:201], v176 offset:4096
	v_mfma_f32_16x16x32_bf16 v[28:31], v[202:205], v[244:247], v[28:31]
	v_mfma_f32_16x16x32_bf16 v[24:27], v[206:209], v[244:247], v[24:27]
	v_mfma_f32_16x16x32_bf16 v[20:23], v[210:213], v[244:247], v[20:23]
	v_mfma_f32_16x16x32_bf16 v[16:19], v[214:217], v[244:247], v[16:19]
	v_mfma_f32_16x16x32_bf16 v[12:15], v[202:205], v[248:251], v[12:15]
	v_mfma_f32_16x16x32_bf16 v[8:11], v[206:209], v[248:251], v[8:11]
	v_mfma_f32_16x16x32_bf16 v[4:7], v[210:213], v[248:251], v[4:7]
	v_mfma_f32_16x16x32_bf16 v[0:3], v[214:217], v[248:251], v[0:3]
	s_waitcnt lgkmcnt(2)
	v_mfma_f32_16x16x32_bf16 v[124:127], v[156:159], v[164:167], v[124:127]
	v_add_u32_e32 v146, v146, v152
	v_mfma_f32_16x16x32_bf16 v[120:123], v[160:163], v[164:167], v[120:123]
	v_mfma_f32_16x16x32_bf16 v[116:119], v[186:189], v[164:167], v[116:119]
	v_mfma_f32_16x16x32_bf16 v[112:115], v[190:193], v[164:167], v[112:115]
	ds_read_b128 v[164:167], v155
	v_add_u32_e32 v155, s17, v145
	v_add_u32_e32 v172, v155, v151
	s_waitcnt lgkmcnt(2)
	v_mfma_f32_16x16x32_bf16 v[108:111], v[156:159], v[194:197], v[108:111]
	v_mfma_f32_16x16x32_bf16 v[104:107], v[160:163], v[194:197], v[104:107]
	v_mfma_f32_16x16x32_bf16 v[100:103], v[186:189], v[194:197], v[100:103]
	v_mfma_f32_16x16x32_bf16 v[96:99], v[190:193], v[194:197], v[96:99]
	ds_read_b128 v[194:197], v176 offset:8192
	ds_read_b128 v[202:205], v172 offset:32768
	s_waitcnt lgkmcnt(3)
	v_mfma_f32_16x16x32_bf16 v[92:95], v[156:159], v[198:201], v[92:95]
	v_mfma_f32_16x16x32_bf16 v[88:91], v[160:163], v[198:201], v[88:91]
	v_mfma_f32_16x16x32_bf16 v[84:87], v[186:189], v[198:201], v[84:87]
	v_mfma_f32_16x16x32_bf16 v[80:83], v[190:193], v[198:201], v[80:83]
	ds_read_b128 v[198:201], v176 offset:10240
	ds_read_b128 v[206:209], v172 offset:34816
	s_waitcnt lgkmcnt(4)
	v_mfma_f32_16x16x32_bf16 v[76:79], v[156:159], v[164:167], v[76:79]
	v_mfma_f32_16x16x32_bf16 v[72:75], v[160:163], v[164:167], v[72:75]
	v_mfma_f32_16x16x32_bf16 v[68:71], v[186:189], v[164:167], v[68:71]
	v_mfma_f32_16x16x32_bf16 v[64:67], v[190:193], v[164:167], v[64:67]
	ds_read_b128 v[210:213], v172 offset:36864
	v_add_u32_e32 v172, v155, v153
	ds_read_b128 v[164:167], v176 offset:12288
	s_waitcnt lgkmcnt(5)
	v_mfma_f32_16x16x32_bf16 v[60:63], v[156:159], v[194:197], v[60:63]
	v_mfma_f32_16x16x32_bf16 v[56:59], v[160:163], v[194:197], v[56:59]
	v_mfma_f32_16x16x32_bf16 v[52:55], v[186:189], v[194:197], v[52:55]
	v_mfma_f32_16x16x32_bf16 v[48:51], v[190:193], v[194:197], v[48:51]
	ds_read_b128 v[214:217], v172 offset:38912
	ds_read_b128 v[194:197], v146
	v_add_u32_e32 v146, v155, v144
	s_waitcnt lgkmcnt(5)
	v_mfma_f32_16x16x32_bf16 v[44:47], v[156:159], v[198:201], v[44:47]
	v_mfma_f32_16x16x32_bf16 v[40:43], v[160:163], v[198:201], v[40:43]
	v_mfma_f32_16x16x32_bf16 v[36:39], v[186:189], v[198:201], v[36:39]
	v_mfma_f32_16x16x32_bf16 v[32:35], v[190:193], v[198:201], v[32:35]
	ds_read_b128 v[198:201], v146
	s_waitcnt lgkmcnt(3)
	v_mfma_f32_16x16x32_bf16 v[28:31], v[156:159], v[164:167], v[28:31]
	v_mfma_f32_16x16x32_bf16 v[24:27], v[160:163], v[164:167], v[24:27]
	v_mfma_f32_16x16x32_bf16 v[20:23], v[186:189], v[164:167], v[20:23]
	v_mfma_f32_16x16x32_bf16 v[16:19], v[190:193], v[164:167], v[16:19]
	ds_read_b128 v[164:167], v146 offset:2048
	s_waitcnt lgkmcnt(2)
; #define MFMA16(a, b, c) __builtin_amdgcn_mfma_f32_16x16x32_bf16((a), (b), (c), 0, 0, 0)
; DI bf16x8 ldfrag(const char* lds, int row, int chunk) { return *(const bf16x8*)(lds + swz(row, chunk)); }
; #define GEMM_SG1() do { __builtin_amdgcn_sched_group_barrier(0x100, 1, 0); __builtin_amdgcn_sched_group_barrier(0x008, 4, 0); } while (0)
; #define GEMM_SG2() do { __builtin_amdgcn_sched_group_barrier(0x100, 2, 0); __builtin_amdgcn_sched_group_barrier(0x008, 4, 0); } while (0)
; template <bool RSTD, bool SWAP>
; DI void gemm_tile(gacc_t& acc, const bf16_t* __restrict__ A, int lda, const bf16_t* __restrict__ Bt, int ldb, int K,
;                   char* lds, int tid, int wr, int wc, int lane, const float* ssq_row) {
;     ...
;     for (int kt = 0; kt < nk; ++kt) {
;         const char* cur = lds + (kt & 1) * 65536;
;         if (kt + 1 < nk) GEMM_ISSUE(kt + 1, (kt + 1) & 1);
;         bf16x8 bfr[2][4], afr[3];
; #pragma unroll
;         for (int n = 0; n < 4; ++n) bfr[0][n] = ldfrag(cur + 32768, wc * 64 + n * 16 + fr, fq);
;         afr[0] = ldfrag(cur, wr * 128 + fr, fq);
;         afr[1] = ldfrag(cur, wr * 128 + 16 + fr, fq);
; #pragma unroll
;         for (int idx = 0; idx < 16; ++idx) {
;             const int ks = idx >> 3, m = idx & 7;
;             if (idx < 14) afr[(idx + 2) % 3] = ldfrag(cur, wr * 128 + ((idx + 2) & 7) * 16 + fr, ((idx + 2) >> 3) * 4 + fq);
;             if (ks == 0 && m >= 2 && m < 6) bfr[1][m - 2] = ldfrag(cur + 32768, wc * 64 + (m - 2) * 16 + fr, 4 + fq);
; #pragma unroll
;             for (int n = 0; n < 4; ++n) acc[m][n] = SWAP ? MFMA16(bfr[ks][n], afr[idx % 3], acc[m][n]) : MFMA16(afr[idx % 3], bfr[ks][n], acc[m][n]);
;         }
;         __builtin_amdgcn_sched_group_barrier(0x100, 6, 0);
;     ...
;         GEMM_SG1(); GEMM_SG1(); GEMM_SG2(); GEMM_SG2(); GEMM_SG2(); GEMM_SG2(); GEMM_SG1(); GEMM_SG1();
;         GEMM_SG1(); GEMM_SG1(); GEMM_SG1(); GEMM_SG1(); GEMM_SG1(); GEMM_SG1();
;         __builtin_amdgcn_sched_group_barrier(0x008, 8, 0);
;         __builtin_amdgcn_sched_barrier(0);
;         asm volatile("s_waitcnt vmcnt(0)" ::: "memory");
;         __syncthreads();
	v_mfma_f32_16x16x32_bf16 v[8:11], v[160:163], v[194:197], v[8:11]
	v_add_u32_e32 v160, v155, v150
	v_mfma_f32_16x16x32_bf16 v[12:15], v[156:159], v[194:197], v[12:15]
	v_mfma_f32_16x16x32_bf16 v[4:7], v[186:189], v[194:197], v[4:7]
	v_mfma_f32_16x16x32_bf16 v[0:3], v[190:193], v[194:197], v[0:3]
	ds_read_b128 v[156:159], v146 offset:4096
	s_waitcnt lgkmcnt(2)
	v_mfma_f32_16x16x32_bf16 v[124:127], v[202:205], v[198:201], v[124:127]
	v_mfma_f32_16x16x32_bf16 v[120:123], v[206:209], v[198:201], v[120:123]
	v_mfma_f32_16x16x32_bf16 v[116:119], v[210:213], v[198:201], v[116:119]
	v_mfma_f32_16x16x32_bf16 v[112:115], v[214:217], v[198:201], v[112:115]
	ds_read_b128 v[160:163], v160
	s_waitcnt lgkmcnt(2)
	v_mfma_f32_16x16x32_bf16 v[108:111], v[202:205], v[164:167], v[108:111]
	v_mfma_f32_16x16x32_bf16 v[104:107], v[206:209], v[164:167], v[104:107]
	v_mfma_f32_16x16x32_bf16 v[100:103], v[210:213], v[164:167], v[100:103]
	v_mfma_f32_16x16x32_bf16 v[96:99], v[214:217], v[164:167], v[96:99]
	ds_read_b128 v[236:239], v146 offset:8192
	s_waitcnt lgkmcnt(2)
	v_mfma_f32_16x16x32_bf16 v[92:95], v[202:205], v[156:159], v[92:95]
	v_mfma_f32_16x16x32_bf16 v[88:91], v[206:209], v[156:159], v[88:91]
	v_mfma_f32_16x16x32_bf16 v[84:87], v[210:213], v[156:159], v[84:87]
	v_mfma_f32_16x16x32_bf16 v[80:83], v[214:217], v[156:159], v[80:83]
	ds_read_b128 v[240:243], v146 offset:10240
	ds_read_b128 v[244:247], v146 offset:12288
	v_add_u32_e32 v146, v155, v152
	ds_read_b128 v[248:251], v146
	s_waitcnt lgkmcnt(4)
	v_mfma_f32_16x16x32_bf16 v[76:79], v[202:205], v[160:163], v[76:79]
	v_mfma_f32_16x16x32_bf16 v[72:75], v[206:209], v[160:163], v[72:75]
	v_mfma_f32_16x16x32_bf16 v[68:71], v[210:213], v[160:163], v[68:71]
	v_mfma_f32_16x16x32_bf16 v[64:67], v[214:217], v[160:163], v[64:67]
	s_waitcnt lgkmcnt(0)
	s_waitcnt vmcnt(0)
	s_add_u32 s4, s4, 0x80
	s_addc_u32 s5, s5, 0
	s_add_i32 s13, s13, 0x10000
	s_cmpk_eq_i32 s4, 0x780
	s_waitcnt vmcnt(0)
	s_barrier
	s_cbranch_scc0 .LBB0_523
	v_mfma_f32_16x16x32_bf16 v[60:63], v[202:205], v[236:239], v[60:63]
	v_mfma_f32_16x16x32_bf16 v[56:59], v[206:209], v[236:239], v[56:59]
	v_mfma_f32_16x16x32_bf16 v[52:55], v[210:213], v[236:239], v[52:55]
	v_mfma_f32_16x16x32_bf16 v[48:51], v[214:217], v[236:239], v[48:51]
	v_mfma_f32_16x16x32_bf16 v[44:47], v[202:205], v[240:243], v[44:47]
	v_mfma_f32_16x16x32_bf16 v[40:43], v[206:209], v[240:243], v[40:43]
	v_mfma_f32_16x16x32_bf16 v[36:39], v[210:213], v[240:243], v[36:39]
	v_mfma_f32_16x16x32_bf16 v[32:35], v[214:217], v[240:243], v[32:35]
	v_mfma_f32_16x16x32_bf16 v[28:31], v[202:205], v[244:247], v[28:31]
	v_mfma_f32_16x16x32_bf16 v[24:27], v[206:209], v[244:247], v[24:27]
	v_mfma_f32_16x16x32_bf16 v[20:23], v[210:213], v[244:247], v[20:23]
	v_mfma_f32_16x16x32_bf16 v[16:19], v[214:217], v[244:247], v[16:19]
	v_mfma_f32_16x16x32_bf16 v[12:15], v[202:205], v[248:251], v[12:15]
	v_mfma_f32_16x16x32_bf16 v[8:11], v[206:209], v[248:251], v[8:11]
	v_mfma_f32_16x16x32_bf16 v[4:7], v[210:213], v[248:251], v[4:7]
	v_mfma_f32_16x16x32_bf16 v[0:3], v[214:217], v[248:251], v[0:3]
	v_add_u32_e32 v146, s16, v142
	v_add3_u32 v155, v146, v148, v149
	ds_read_b128 v[136:139], v155 offset:32768
	ds_read_b128 v[156:159], v155 offset:34816
	ds_read_b128 v[164:167], v155 offset:36864
	ds_read_b128 v[186:189], v155 offset:38912
	v_add_u32_e32 v172, v146, v144
	ds_read_b128 v[160:163], v172
	ds_read_b128 v[190:193], v172 offset:2048
	v_add_u32_e32 v155, v146, v150
	ds_read_b128 v[194:197], v172 offset:4096
	s_waitcnt lgkmcnt(2)
	v_mfma_f32_16x16x32_bf16 v[124:127], v[136:139], v[160:163], v[124:127]
	v_add_u32_e32 v146, v146, v152
	s_lshl_b64 s[12:13], s[8:9], 8
	v_mfma_f32_16x16x32_bf16 v[120:123], v[156:159], v[160:163], v[120:123]
	v_mfma_f32_16x16x32_bf16 v[116:119], v[164:167], v[160:163], v[116:119]
	v_mfma_f32_16x16x32_bf16 v[112:115], v[186:189], v[160:163], v[112:115]
	ds_read_b128 v[160:163], v155
	v_add_u32_e32 v155, s16, v145
	v_add_u32_e32 v173, v155, v151
	s_waitcnt lgkmcnt(2)
	v_mfma_f32_16x16x32_bf16 v[108:111], v[136:139], v[190:193], v[108:111]
	v_mfma_f32_16x16x32_bf16 v[104:107], v[156:159], v[190:193], v[104:107]
	v_mfma_f32_16x16x32_bf16 v[100:103], v[164:167], v[190:193], v[100:103]
	v_mfma_f32_16x16x32_bf16 v[96:99], v[186:189], v[190:193], v[96:99]
	ds_read_b128 v[190:193], v172 offset:8192
	ds_read_b128 v[198:201], v173 offset:32768
	s_waitcnt lgkmcnt(3)
	v_mfma_f32_16x16x32_bf16 v[92:95], v[136:139], v[194:197], v[92:95]
	v_mfma_f32_16x16x32_bf16 v[88:91], v[156:159], v[194:197], v[88:91]
	v_mfma_f32_16x16x32_bf16 v[84:87], v[164:167], v[194:197], v[84:87]
	v_mfma_f32_16x16x32_bf16 v[80:83], v[186:189], v[194:197], v[80:83]
	ds_read_b128 v[194:197], v172 offset:10240
	ds_read_b128 v[202:205], v173 offset:34816
	s_waitcnt lgkmcnt(4)
	v_mfma_f32_16x16x32_bf16 v[76:79], v[136:139], v[160:163], v[76:79]
	v_mfma_f32_16x16x32_bf16 v[72:75], v[156:159], v[160:163], v[72:75]
	v_mfma_f32_16x16x32_bf16 v[68:71], v[164:167], v[160:163], v[68:71]
	v_mfma_f32_16x16x32_bf16 v[64:67], v[186:189], v[160:163], v[64:67]
	ds_read_b128 v[160:163], v172 offset:12288
	ds_read_b128 v[206:209], v173 offset:36864
	s_waitcnt lgkmcnt(5)
	v_mfma_f32_16x16x32_bf16 v[60:63], v[136:139], v[190:193], v[60:63]
	v_mfma_f32_16x16x32_bf16 v[56:59], v[156:159], v[190:193], v[56:59]
	v_mfma_f32_16x16x32_bf16 v[52:55], v[164:167], v[190:193], v[52:55]
	v_mfma_f32_16x16x32_bf16 v[48:51], v[186:189], v[190:193], v[48:51]
	ds_read_b128 v[190:193], v146
	v_add_u32_e32 v146, v155, v153
	ds_read_b128 v[210:213], v146 offset:38912
	v_add_u32_e32 v146, v155, v144
	s_waitcnt lgkmcnt(5)
; #define MFMA16(a, b, c) __builtin_amdgcn_mfma_f32_16x16x32_bf16((a), (b), (c), 0, 0, 0)
; DI unsigned pk2(float a, float b) { f32x2 v = {a, b}; bf16x2_t r = __builtin_convertvector(v, bf16x2_t); return __builtin_bit_cast(unsigned, r); }
; DI bf16x8 ldfrag(const char* lds, int row, int chunk) { return *(const bf16x8*)(lds + swz(row, chunk)); }
; template <bool RSTD, bool SWAP>
; DI void gemm_tile(gacc_t& acc, const bf16_t* __restrict__ A, int lda, const bf16_t* __restrict__ Bt, int ldb, int K,
;                   char* lds, int tid, int wr, int wc, int lane, const float* ssq_row) {
;     ...
;         for (int idx = 0; idx < 16; ++idx) {
;             const int ks = idx >> 3, m = idx & 7;
;             if (idx < 14) afr[(idx + 2) % 3] = ldfrag(cur, wr * 128 + ((idx + 2) & 7) * 16 + fr, ((idx + 2) >> 3) * 4 + fq);
;             if (ks == 0 && m >= 2 && m < 6) bfr[1][m - 2] = ldfrag(cur + 32768, wc * 64 + (m - 2) * 16 + fr, 4 + fq);
; #pragma unroll
;             for (int n = 0; n < 4; ++n) acc[m][n] = SWAP ? MFMA16(bfr[ks][n], afr[idx % 3], acc[m][n]) : MFMA16(afr[idx % 3], bfr[ks][n], acc[m][n]);
;         }
;     DI void operator()(gacc_t& acc, int pm, int pn, char* lds, int tid, int wr, int wc, int lane) const {
;     ...
;         for (int m = 0; m < 8; ++m)
; #pragma unroll
;             for (int n = 0; n < 4; ++n) { u32x2 w; w.x = pk2(acc[m][n][0], acc[m][n][1]); w.y = pk2(acc[m][n][2], acc[m][n][3]); *(u32x2*)(lbase + m * 16 * 528 + n * 32) = w; }
	v_mfma_f32_16x16x32_bf16 v[44:47], v[136:139], v[194:197], v[44:47]
	v_mfma_f32_16x16x32_bf16 v[40:43], v[156:159], v[194:197], v[40:43]
	v_mfma_f32_16x16x32_bf16 v[36:39], v[164:167], v[194:197], v[36:39]
	v_mfma_f32_16x16x32_bf16 v[32:35], v[186:189], v[194:197], v[32:35]
	ds_read_b128 v[194:197], v146
	s_waitcnt lgkmcnt(4)
	v_mfma_f32_16x16x32_bf16 v[28:31], v[136:139], v[160:163], v[28:31]
	v_mfma_f32_16x16x32_bf16 v[24:27], v[156:159], v[160:163], v[24:27]
	v_mfma_f32_16x16x32_bf16 v[20:23], v[164:167], v[160:163], v[20:23]
	v_mfma_f32_16x16x32_bf16 v[16:19], v[186:189], v[160:163], v[16:19]
	ds_read_b128 v[160:163], v146 offset:2048
	s_waitcnt lgkmcnt(3)
	v_mfma_f32_16x16x32_bf16 v[8:11], v[156:159], v[190:193], v[8:11]
	v_add_u32_e32 v156, v155, v150
	v_mfma_f32_16x16x32_bf16 v[12:15], v[136:139], v[190:193], v[12:15]
	v_mfma_f32_16x16x32_bf16 v[4:7], v[164:167], v[190:193], v[4:7]
	v_mfma_f32_16x16x32_bf16 v[0:3], v[186:189], v[190:193], v[0:3]
	ds_read_b128 v[136:139], v146 offset:4096
	s_waitcnt lgkmcnt(2)
	v_mfma_f32_16x16x32_bf16 v[124:127], v[198:201], v[194:197], v[124:127]
	v_mfma_f32_16x16x32_bf16 v[120:123], v[202:205], v[194:197], v[120:123]
	v_mfma_f32_16x16x32_bf16 v[116:119], v[206:209], v[194:197], v[116:119]
	v_mfma_f32_16x16x32_bf16 v[112:115], v[210:213], v[194:197], v[112:115]
	ds_read_b128 v[156:159], v156
	s_waitcnt lgkmcnt(2)
	v_mfma_f32_16x16x32_bf16 v[108:111], v[198:201], v[160:163], v[108:111]
	v_mfma_f32_16x16x32_bf16 v[104:107], v[202:205], v[160:163], v[104:107]
	v_mfma_f32_16x16x32_bf16 v[100:103], v[206:209], v[160:163], v[100:103]
	v_mfma_f32_16x16x32_bf16 v[96:99], v[210:213], v[160:163], v[96:99]
	ds_read_b128 v[160:163], v146 offset:8192
	s_waitcnt lgkmcnt(2)
	v_mfma_f32_16x16x32_bf16 v[92:95], v[198:201], v[136:139], v[92:95]
	v_mfma_f32_16x16x32_bf16 v[88:91], v[202:205], v[136:139], v[88:91]
	v_mfma_f32_16x16x32_bf16 v[84:87], v[206:209], v[136:139], v[84:87]
	v_mfma_f32_16x16x32_bf16 v[80:83], v[210:213], v[136:139], v[80:83]
	ds_read_b128 v[136:139], v146 offset:10240
	s_waitcnt lgkmcnt(2)
	v_mfma_f32_16x16x32_bf16 v[76:79], v[198:201], v[156:159], v[76:79]
	v_mfma_f32_16x16x32_bf16 v[72:75], v[202:205], v[156:159], v[72:75]
	v_mfma_f32_16x16x32_bf16 v[68:71], v[206:209], v[156:159], v[68:71]
	v_mfma_f32_16x16x32_bf16 v[64:67], v[210:213], v[156:159], v[64:67]
	ds_read_b128 v[156:159], v146 offset:12288
	v_add_u32_e32 v146, v155, v152
	s_waitcnt lgkmcnt(2)
	v_mfma_f32_16x16x32_bf16 v[60:63], v[198:201], v[160:163], v[60:63]
	v_mfma_f32_16x16x32_bf16 v[56:59], v[202:205], v[160:163], v[56:59]
	v_mfma_f32_16x16x32_bf16 v[52:55], v[206:209], v[160:163], v[52:55]
	v_mfma_f32_16x16x32_bf16 v[48:51], v[210:213], v[160:163], v[48:51]
	ds_read_b128 v[160:163], v146
	s_waitcnt lgkmcnt(2)
	v_mfma_f32_16x16x32_bf16 v[44:47], v[198:201], v[136:139], v[44:47]
	v_mfma_f32_16x16x32_bf16 v[40:43], v[202:205], v[136:139], v[40:43]
	v_mfma_f32_16x16x32_bf16 v[36:39], v[206:209], v[136:139], v[36:39]
	v_mfma_f32_16x16x32_bf16 v[32:35], v[210:213], v[136:139], v[32:35]
	s_waitcnt lgkmcnt(1)
	v_mfma_f32_16x16x32_bf16 v[24:27], v[202:205], v[156:159], v[24:27]
	v_mfma_f32_16x16x32_bf16 v[20:23], v[206:209], v[156:159], v[20:23]
	v_mfma_f32_16x16x32_bf16 v[16:19], v[210:213], v[156:159], v[16:19]
	s_waitcnt lgkmcnt(0)
	v_mfma_f32_16x16x32_bf16 v[12:15], v[198:201], v[160:163], v[12:15]
	v_mfma_f32_16x16x32_bf16 v[8:11], v[202:205], v[160:163], v[8:11]
	v_mfma_f32_16x16x32_bf16 v[4:7], v[206:209], v[160:163], v[4:7]
	v_mfma_f32_16x16x32_bf16 v[0:3], v[210:213], v[160:163], v[0:3]
	v_mfma_f32_16x16x32_bf16 v[28:31], v[198:201], v[156:159], v[28:31]
	v_mov_b32_e32 v136, v141
	v_mov_b32_e32 v137, v140
	s_waitcnt vmcnt(0)
	s_barrier
	v_cvt_pk_bf16_f32 v124, v124, v125
	v_and_or_b32 v138, v136, 15, v143
	v_ashrrev_i32_e32 v139, 1, v136
	v_mul_lo_u32 v138, v138, s3
	v_and_b32_e32 v139, -8, v139
	v_add3_u32 v138, v154, v138, v139
	v_cvt_pk_bf16_f32 v125, v126, v127
	v_cvt_pk_bf16_f32 v120, v120, v121
	v_cvt_pk_bf16_f32 v121, v122, v123
	v_cvt_pk_bf16_f32 v116, v116, v117
	v_cvt_pk_bf16_f32 v117, v118, v119
	v_cvt_pk_bf16_f32 v112, v112, v113
	v_cvt_pk_bf16_f32 v113, v114, v115
	v_cvt_pk_bf16_f32 v108, v108, v109
	v_cvt_pk_bf16_f32 v109, v110, v111
	v_cvt_pk_bf16_f32 v104, v104, v105
	v_cvt_pk_bf16_f32 v105, v106, v107
	v_add_u32_e32 v106, 0x2000, v138
	v_cvt_pk_bf16_f32 v100, v100, v101
	v_cvt_pk_bf16_f32 v101, v102, v103
	v_cvt_pk_bf16_f32 v96, v96, v97
	v_cvt_pk_bf16_f32 v97, v98, v99
	v_cvt_pk_bf16_f32 v92, v92, v93
	v_cvt_pk_bf16_f32 v93, v94, v95
	v_cvt_pk_bf16_f32 v88, v88, v89
	v_cvt_pk_bf16_f32 v89, v90, v91
	v_add_u32_e32 v90, 0x4000, v138
	v_cvt_pk_bf16_f32 v84, v84, v85
	v_cvt_pk_bf16_f32 v85, v86, v87
	v_cvt_pk_bf16_f32 v80, v80, v81
	v_cvt_pk_bf16_f32 v81, v82, v83
	v_cvt_pk_bf16_f32 v76, v76, v77
	v_cvt_pk_bf16_f32 v77, v78, v79
	v_cvt_pk_bf16_f32 v72, v72, v73
	v_cvt_pk_bf16_f32 v73, v74, v75
	v_add_u32_e32 v74, 0x6000, v138
	v_cvt_pk_bf16_f32 v68, v68, v69
	v_cvt_pk_bf16_f32 v69, v70, v71
	v_cvt_pk_bf16_f32 v64, v64, v65
	v_cvt_pk_bf16_f32 v65, v66, v67
	v_cvt_pk_bf16_f32 v60, v60, v61
	v_cvt_pk_bf16_f32 v61, v62, v63
	v_cvt_pk_bf16_f32 v56, v56, v57
	v_cvt_pk_bf16_f32 v57, v58, v59
	v_add_u32_e32 v58, 0x8000, v138
	v_cvt_pk_bf16_f32 v52, v52, v53
	v_cvt_pk_bf16_f32 v53, v54, v55
	v_cvt_pk_bf16_f32 v48, v48, v49
	v_cvt_pk_bf16_f32 v49, v50, v51
	v_cvt_pk_bf16_f32 v44, v44, v45
	v_cvt_pk_bf16_f32 v45, v46, v47
	v_cvt_pk_bf16_f32 v40, v40, v41
	v_cvt_pk_bf16_f32 v41, v42, v43
	v_add_u32_e32 v42, 0xa000, v138
	v_cvt_pk_bf16_f32 v36, v36, v37
	v_cvt_pk_bf16_f32 v37, v38, v39
	v_cvt_pk_bf16_f32 v32, v32, v33
; DI unsigned pk2(float a, float b) { f32x2 v = {a, b}; bf16x2_t r = __builtin_convertvector(v, bf16x2_t); return __builtin_bit_cast(unsigned, r); }
; DI float bflo(unsigned w) { return __uint_as_float(w << 16); }
; DI float bfhi(unsigned w) { return __uint_as_float(w & 0xffff0000u); }
;     DI void operator()(gacc_t& acc, int pm, int pn, char* lds, int tid, int wr, int wc, int lane) const {
;     ...
;             for (int n = 0; n < 4; ++n) { u32x2 w; w.x = pk2(acc[m][n][0], acc[m][n][1]); w.y = pk2(acc[m][n][2], acc[m][n][3]); *(u32x2*)(lbase + m * 16 * 528 + n * 32) = w; }
;         __builtin_amdgcn_sched_barrier(0);
;         __syncthreads();
;         __builtin_amdgcn_sched_barrier(0);
;         const int g = lane >> 5, j32 = lane & 31;
; #pragma unroll
;         for (int ib = 0; ib < 4; ++ib) {
;             __builtin_amdgcn_sched_barrier(0);
;             u32x4 xv[4];
; #pragma unroll
;             for (int u = 0; u < 4; ++u) {
;                 const long row = (long)pm * 256 + (ib * 4 + u) * 16 + wid * 2 + g;
;                 xv[u] = *(const u32x4*)(xold + row * 1024 + pn * 256 + j32 * 8);
;             }
; #pragma unroll
;             for (int u = 0; u < 4; ++u) {
;                 const int rloc = (ib * 4 + u) * 16 + wid * 2 + g;
;                 const long row = (long)pm * 256 + rloc;
;                 const u32x4 a = *(const u32x4*)(lds + rloc * 528 + j32 * 16);
;                 u32x4 w; float ss = 0.f;
; #pragma unroll
;                 for (int e = 0; e < 4; ++e) {
;                     w[e] = pk2(bflo(xv[u][e]) + bflo(a[e]), bfhi(xv[u][e]) + bfhi(a[e]));
;                     const float b0 = bflo(w[e]), b1 = bfhi(w[e]);
;                     ss += b0 * b0 + b1 * b1;
;                 }
;                 *(u32x4*)(xnew + row * 1024 + pn * 256 + j32 * 8) = w;
; #pragma unroll
;                 for (int o = 1; o < 32; o <<= 1) ss += __shfl_xor(ss, o);
;                 if (j32 == 0) ssq[row * 4 + pn] = ss;
	v_cvt_pk_bf16_f32 v33, v34, v35
	v_cvt_pk_bf16_f32 v28, v28, v29
	v_cvt_pk_bf16_f32 v29, v30, v31
	v_cvt_pk_bf16_f32 v24, v24, v25
	v_cvt_pk_bf16_f32 v25, v26, v27
	v_add_u32_e32 v26, 0xc000, v138
	v_cvt_pk_bf16_f32 v20, v20, v21
	v_cvt_pk_bf16_f32 v21, v22, v23
	v_cvt_pk_bf16_f32 v16, v16, v17
	v_cvt_pk_bf16_f32 v17, v18, v19
	v_cvt_pk_bf16_f32 v12, v12, v13
	v_cvt_pk_bf16_f32 v13, v14, v15
	v_cvt_pk_bf16_f32 v8, v8, v9
	v_cvt_pk_bf16_f32 v9, v10, v11
	v_add_u32_e32 v10, 0xe000, v138
	v_cvt_pk_bf16_f32 v4, v4, v5
	v_cvt_pk_bf16_f32 v5, v6, v7
	v_cvt_pk_bf16_f32 v0, v0, v1
	v_cvt_pk_bf16_f32 v1, v2, v3
	ds_write2_b64 v138, v[124:125], v[120:121] offset1:4
	ds_write2_b64 v138, v[116:117], v[112:113] offset0:8 offset1:12
	ds_write2_b64 v106, v[108:109], v[104:105] offset0:32 offset1:36
	ds_write2_b64 v106, v[100:101], v[96:97] offset0:40 offset1:44
	ds_write2_b64 v90, v[92:93], v[88:89] offset0:64 offset1:68
	ds_write2_b64 v90, v[84:85], v[80:81] offset0:72 offset1:76
	ds_write2_b64 v74, v[76:77], v[72:73] offset0:96 offset1:100
	ds_write2_b64 v74, v[68:69], v[64:65] offset0:104 offset1:108
	ds_write2_b64 v58, v[60:61], v[56:57] offset0:128 offset1:132
	ds_write2_b64 v58, v[52:53], v[48:49] offset0:136 offset1:140
	ds_write2_b64 v42, v[44:45], v[40:41] offset0:160 offset1:164
	ds_write2_b64 v42, v[36:37], v[32:33] offset0:168 offset1:172
	ds_write2_b64 v26, v[28:29], v[24:25] offset0:192 offset1:196
	ds_write2_b64 v26, v[20:21], v[16:17] offset0:200 offset1:204
	ds_write2_b64 v10, v[12:13], v[8:9] offset0:224 offset1:228
	ds_write2_b64 v10, v[4:5], v[0:1] offset0:232 offset1:236
	s_waitcnt lgkmcnt(0)
	s_barrier
	v_ashrrev_i32_e32 v0, 5, v136
	v_ashrrev_i32_e32 v1, 5, v137
	v_and_b32_e32 v14, 31, v136
	v_and_b32_e32 v2, -2, v1
	v_ashrrev_i32_e32 v1, 31, v0
	v_ashrrev_i32_e32 v3, 31, v2
	v_lshl_add_u64 v[4:5], s[12:13], 0, v[0:1]
	s_lshl_b32 s16, s6, 8
	v_add_u32_e32 v16, v2, v0
	v_lshlrev_b32_e32 v146, 4, v14
	v_and_b32_e32 v0, 64, v169
	v_lshl_add_u64 v[4:5], v[4:5], 0, v[2:3]
	s_ashr_i32 s17, s16, 31
	v_add_u32_e32 v26, 0, v146
	v_add_u32_e32 v15, 64, v0
	v_cmp_eq_u32_e64 s[4:5], 0, v14
	v_cmp_eq_u32_e64 s[98:99], 16, v14
	s_lshl_b64 s[18:19], s[16:17], 1
	s_add_u32 s22, s10, s18
	s_addc_u32 s23, s11, s19
	v_lshl_add_u64 v[0:1], s[22:23], 0, v[146:147]
	v_lshlrev_b64 v[2:3], 11, v[4:5]
	v_lshl_add_u64 v[18:19], v[0:1], 0, v[2:3]
	flat_load_dwordx4 v[22:25], v[18:19]
	v_add_co_u32_e32 v0, vcc, s49, v18
	v_mul_lo_u32 v20, v16, s3
	s_nop 0
	v_addc_co_u32_e32 v1, vcc, 0, v19, vcc
	flat_load_dwordx4 v[8:11], v[0:1]
	v_add_co_u32_e32 v0, vcc, s48, v18
	v_add_u32_e32 v12, v26, v20
	s_nop 0
	v_addc_co_u32_e32 v1, vcc, 0, v19, vcc
	flat_load_dwordx4 v[4:7], v[0:1]
	v_add_co_u32_e32 v0, vcc, s47, v18
	ds_read_b128 v[28:31], v12
	s_nop 0
	v_addc_co_u32_e32 v1, vcc, 0, v19, vcc
	flat_load_dwordx4 v[0:3], v[0:1]
	v_ashrrev_i32_e32 v17, 31, v16
	s_waitcnt lgkmcnt(0)
	v_lshlrev_b32_e32 v32, 16, v28
	v_and_b32_e32 v33, 0xffff0000, v28
	v_lshlrev_b32_e32 v28, 16, v29
	v_and_b32_e32 v29, 0xffff0000, v29
	s_waitcnt vmcnt(0)
	v_lshlrev_b32_e32 v12, 16, v22
	v_and_b32_e32 v13, 0xffff0000, v22
	v_pk_add_f32 v[12:13], v[12:13], v[32:33]
	s_nop 0
	v_cvt_pk_bf16_f32 v22, v12, v13
	v_and_b32_e32 v13, 0xffff0000, v22
	v_lshlrev_b32_e32 v12, 16, v22
	v_mul_f32_e32 v21, v13, v13
	v_fmac_f32_e32 v21, v12, v12
	v_lshlrev_b32_e32 v12, 16, v23
	v_and_b32_e32 v13, 0xffff0000, v23
	v_pk_add_f32 v[12:13], v[12:13], v[28:29]
	v_lshlrev_b32_e32 v28, 16, v30
	v_cvt_pk_bf16_f32 v23, v12, v13
	v_and_b32_e32 v13, 0xffff0000, v23
	v_lshlrev_b32_e32 v12, 16, v23
	v_mul_f32_e32 v13, v13, v13
	v_fmac_f32_e32 v13, v12, v12
	v_add_f32_e32 v21, v21, v13
	v_lshlrev_b32_e32 v12, 16, v24
	v_and_b32_e32 v13, 0xffff0000, v24
	v_and_b32_e32 v29, 0xffff0000, v30
	v_pk_add_f32 v[12:13], v[12:13], v[28:29]
	v_lshlrev_b32_e32 v28, 16, v31
	v_cvt_pk_bf16_f32 v24, v12, v13
	v_and_b32_e32 v13, 0xffff0000, v24
	v_lshlrev_b32_e32 v12, 16, v24
	v_mul_f32_e32 v13, v13, v13
	v_fmac_f32_e32 v13, v12, v12
	v_add_f32_e32 v21, v13, v21
	v_lshlrev_b32_e32 v12, 16, v25
	v_and_b32_e32 v13, 0xffff0000, v25
	v_and_b32_e32 v29, 0xffff0000, v31
	v_pk_add_f32 v[12:13], v[12:13], v[28:29]
	s_nop 0
	v_cvt_pk_bf16_f32 v25, v12, v13
	v_and_b32_e32 v13, 0xffff0000, v25
	v_lshlrev_b32_e32 v12, 16, v25
	v_mul_f32_e32 v13, v13, v13
	v_fmac_f32_e32 v13, v12, v12
	v_add_f32_e32 v21, v13, v21
	v_lshl_add_u64 v[12:13], s[12:13], 0, v[16:17]
	v_lshlrev_b64 v[28:29], 11, v[12:13]
	v_xor_b32_e32 v17, 1, v169
	v_lshl_add_u64 v[28:29], s[68:69], 0, v[28:29]
	v_cmp_lt_i32_e32 vcc, v17, v15
	v_lshl_add_u64 v[28:29], v[28:29], 0, s[18:19]
	v_lshl_add_u64 v[28:29], v[28:29], 0, v[146:147]
	v_cndmask_b32_e32 v17, v169, v17, vcc
	v_lshlrev_b32_e32 v17, 2, v17
	flat_store_dwordx4 v[28:29], v[22:25]
	s_nop 1
	v_add_f32_dpp v86, v21, v21 quad_perm:[1,0,3,2] row_mask:0xf bank_mask:0xf
	s_nop 1
	v_add_f32_dpp v86, v86, v86 quad_perm:[2,3,0,1] row_mask:0xf bank_mask:0xf
	s_nop 1
	v_add_f32_dpp v86, v86, v86 row_half_mirror row_mask:0xf bank_mask:0xf
	s_nop 1
	v_add_f32_dpp v86, v86, v86 row_mirror row_mask:0xf bank_mask:0xf
	s_nop 1
	v_add_f32_dpp v86, v86, v86 row_bcast:15 row_mask:0xa bank_mask:0xf
	s_waitcnt lgkmcnt(0)
	v_xor_b32_e32 v22, 2, v169
	v_cmp_lt_i32_e32 vcc, v22, v15
	s_nop 1
	v_cndmask_b32_e32 v22, v169, v22, vcc
	v_lshlrev_b32_e32 v22, 2, v22
	s_waitcnt lgkmcnt(0)
	v_xor_b32_e32 v23, 4, v169
	v_cmp_lt_i32_e32 vcc, v23, v15
	s_nop 1
	v_cndmask_b32_e32 v23, v169, v23, vcc
	v_lshlrev_b32_e32 v23, 2, v23
	s_waitcnt lgkmcnt(0)
	v_xor_b32_e32 v24, 8, v169
	v_cmp_lt_i32_e32 vcc, v24, v15
	s_nop 1
	v_cndmask_b32_e32 v24, v169, v24, vcc
	v_lshlrev_b32_e32 v24, 2, v24
	s_waitcnt lgkmcnt(0)
	v_xor_b32_e32 v25, 16, v169
	v_cmp_lt_i32_e32 vcc, v25, v15
	s_nop 1
	v_cndmask_b32_e32 v15, v169, v25, vcc
	v_lshlrev_b32_e32 v25, 2, v15
	s_and_saveexec_b64 s[18:19], s[98:99]
	s_cbranch_execz .LBB0_526
	v_lshl_add_u64 v[12:13], v[12:13], 4, s[78:79]
	v_lshl_add_u64 v[12:13], s[6:7], 2, v[12:13]
	s_waitcnt lgkmcnt(0)
	v_mov_b32_e32 v15, v86
	flat_store_dword v[12:13], v15

; #define MFMA16(a, b, c) __builtin_amdgcn_mfma_f32_16x16x32_bf16((a), (b), (c), 0, 0, 0)
; DI bf16x8 ldfrag(const char* lds, int row, int chunk) { return *(const bf16x8*)(lds + swz(row, chunk)); }
; template <bool RSTD, bool SWAP>
; DI void gemm_tile(gacc_t& acc, const bf16_t* __restrict__ A, int lda, const bf16_t* __restrict__ Bt, int ldb, int K,
;                   char* lds, int tid, int wr, int wc, int lane, const float* ssq_row) {
;     ...
;     for (int kt = 0; kt < nk; ++kt) {
;         const char* cur = lds + (kt & 1) * 65536;
;         if (kt + 1 < nk) GEMM_ISSUE(kt + 1, (kt + 1) & 1);
;         bf16x8 bfr[2][4], afr[3];
; #pragma unroll
;         for (int n = 0; n < 4; ++n) bfr[0][n] = ldfrag(cur + 32768, wc * 64 + n * 16 + fr, fq);
;         afr[0] = ldfrag(cur, wr * 128 + fr, fq);
;         afr[1] = ldfrag(cur, wr * 128 + 16 + fr, fq);
; #pragma unroll
;         for (int idx = 0; idx < 16; ++idx) {
;             const int ks = idx >> 3, m = idx & 7;
;             if (idx < 14) afr[(idx + 2) % 3] = ldfrag(cur, wr * 128 + ((idx + 2) & 7) * 16 + fr, ((idx + 2) >> 3) * 4 + fq);
;             if (ks == 0 && m >= 2 && m < 6) bfr[1][m - 2] = ldfrag(cur + 32768, wc * 64 + (m - 2) * 16 + fr, 4 + fq);
; #pragma unroll
;             for (int n = 0; n < 4; ++n) acc[m][n] = SWAP ? MFMA16(bfr[ks][n], afr[idx % 3], acc[m][n]) : MFMA16(afr[idx % 3], bfr[ks][n], acc[m][n]);
;         }
.LBB0_618:
	s_add_i32 s45, s44, 0xffff0000
	s_and_b32 s45, s45, 0x10000
	s_add_i32 s45, s45, 0
	v_add_u32_e32 v146, s45, v144
	v_add3_u32 v161, v146, v150, v151
	v_add_u32_e32 v166, v146, v148
	ds_read_b128 v[162:165], v161 offset:32768
	ds_read_b128 v[172:175], v161 offset:34816
	ds_read_b128 v[180:183], v161 offset:36864
	ds_read_b128 v[186:189], v161 offset:38912
	ds_read_b128 v[176:179], v166
	ds_read_b128 v[190:193], v166 offset:2048
	v_add_u32_e32 v161, v146, v152
	ds_read_b128 v[194:197], v166 offset:4096
	v_lshl_add_u64 v[240:241], v[140:141], 0, s[12:13]
	v_lshl_add_u64 v[242:243], v[138:139], 0, s[12:13]
	s_and_b32 s48, s44, 0x10000
	s_add_i32 s48, s43, s48
	s_mov_b64 s[46:47], 0x2ee40080
	v_lshl_add_u64 v[232:233], v[240:241], 0, s[46:47]
	s_mov_b32 m0, s48
	v_mfma_f32_16x16x32_bf16 v[60:63], v[198:201], v[214:217], v[60:63]
	global_load_lds_dwordx4 v[232:233], off
	v_mfma_f32_16x16x32_bf16 v[56:59], v[202:205], v[214:217], v[56:59]
	s_mov_b64 s[46:47], 0x1c80080
	v_lshl_add_u64 v[234:235], v[242:243], 0, s[46:47]
	s_add_i32 m0, s48, 0x8000
	v_mfma_f32_16x16x32_bf16 v[52:55], v[206:209], v[214:217], v[52:55]
	global_load_lds_dwordx4 v[234:235], off
	v_mfma_f32_16x16x32_bf16 v[48:51], v[210:213], v[214:217], v[48:51]
	s_mov_b64 s[46:47], 0x2ee60080
	v_lshl_add_u64 v[232:233], v[240:241], 0, s[46:47]
	s_add_i32 m0, s48, 0x2000
	v_mfma_f32_16x16x32_bf16 v[44:47], v[198:201], v[218:221], v[44:47]
	global_load_lds_dwordx4 v[232:233], off
	v_mfma_f32_16x16x32_bf16 v[40:43], v[202:205], v[218:221], v[40:43]
	s_mov_b64 s[46:47], 0x1ca0080
	v_lshl_add_u64 v[234:235], v[242:243], 0, s[46:47]
	s_add_i32 m0, s48, 0xa000
	v_mfma_f32_16x16x32_bf16 v[36:39], v[206:209], v[218:221], v[36:39]
	global_load_lds_dwordx4 v[234:235], off
	v_mfma_f32_16x16x32_bf16 v[32:35], v[210:213], v[218:221], v[32:35]
	s_mov_b64 s[46:47], 0x2ee80080
	v_lshl_add_u64 v[232:233], v[240:241], 0, s[46:47]
	s_add_i32 m0, s48, 0x4000
	v_mfma_f32_16x16x32_bf16 v[28:31], v[198:201], v[222:225], v[28:31]
	global_load_lds_dwordx4 v[232:233], off
	v_mfma_f32_16x16x32_bf16 v[24:27], v[202:205], v[222:225], v[24:27]
	s_mov_b64 s[46:47], 0x1cc0080
	v_lshl_add_u64 v[234:235], v[242:243], 0, s[46:47]
	s_add_i32 m0, s48, 0xc000
	v_mfma_f32_16x16x32_bf16 v[20:23], v[206:209], v[222:225], v[20:23]
	global_load_lds_dwordx4 v[234:235], off
	v_mfma_f32_16x16x32_bf16 v[16:19], v[210:213], v[222:225], v[16:19]
	s_mov_b64 s[46:47], 0x2eea0080
	v_lshl_add_u64 v[232:233], v[240:241], 0, s[46:47]
	s_add_i32 m0, s48, 0x6000
	v_mfma_f32_16x16x32_bf16 v[12:15], v[198:201], v[236:239], v[12:15]
	global_load_lds_dwordx4 v[232:233], off
	v_mfma_f32_16x16x32_bf16 v[8:11], v[202:205], v[236:239], v[8:11]
	s_mov_b64 s[46:47], 0x1ce0080
	v_lshl_add_u64 v[234:235], v[242:243], 0, s[46:47]
	s_add_i32 m0, s48, 0xe000
	v_mfma_f32_16x16x32_bf16 v[4:7], v[206:209], v[236:239], v[4:7]
	global_load_lds_dwordx4 v[234:235], off
	v_mfma_f32_16x16x32_bf16 v[0:3], v[210:213], v[236:239], v[0:3]
	s_waitcnt lgkmcnt(2)
	v_mfma_f32_16x16x32_bf16 v[124:127], v[162:165], v[176:179], v[124:127]
	v_add_u32_e32 v146, v146, v154
	v_mfma_f32_16x16x32_bf16 v[120:123], v[172:175], v[176:179], v[120:123]
	v_mfma_f32_16x16x32_bf16 v[116:119], v[180:183], v[176:179], v[116:119]
	v_mfma_f32_16x16x32_bf16 v[112:115], v[186:189], v[176:179], v[112:115]
	ds_read_b128 v[176:179], v161
	v_add_u32_e32 v161, s45, v149
	v_add_u32_e32 v167, v161, v153
	s_waitcnt lgkmcnt(2)
	v_mfma_f32_16x16x32_bf16 v[108:111], v[162:165], v[190:193], v[108:111]
	v_mfma_f32_16x16x32_bf16 v[104:107], v[172:175], v[190:193], v[104:107]
	v_mfma_f32_16x16x32_bf16 v[100:103], v[180:183], v[190:193], v[100:103]
	v_mfma_f32_16x16x32_bf16 v[96:99], v[186:189], v[190:193], v[96:99]
	ds_read_b128 v[190:193], v166 offset:8192
	ds_read_b128 v[198:201], v167 offset:32768
	s_waitcnt lgkmcnt(3)
	v_mfma_f32_16x16x32_bf16 v[92:95], v[162:165], v[194:197], v[92:95]
	v_mfma_f32_16x16x32_bf16 v[88:91], v[172:175], v[194:197], v[88:91]
	v_mfma_f32_16x16x32_bf16 v[84:87], v[180:183], v[194:197], v[84:87]
	v_mfma_f32_16x16x32_bf16 v[80:83], v[186:189], v[194:197], v[80:83]
	ds_read_b128 v[194:197], v166 offset:10240
	ds_read_b128 v[202:205], v167 offset:34816
	s_waitcnt lgkmcnt(4)
	v_mfma_f32_16x16x32_bf16 v[76:79], v[162:165], v[176:179], v[76:79]
	v_mfma_f32_16x16x32_bf16 v[72:75], v[172:175], v[176:179], v[72:75]
	v_mfma_f32_16x16x32_bf16 v[68:71], v[180:183], v[176:179], v[68:71]
	v_mfma_f32_16x16x32_bf16 v[64:67], v[186:189], v[176:179], v[64:67]
	ds_read_b128 v[176:179], v166 offset:12288
	v_add_u32_e32 v166, v161, v155
	ds_read_b128 v[206:209], v167 offset:36864
	s_waitcnt lgkmcnt(5)
	v_mfma_f32_16x16x32_bf16 v[60:63], v[162:165], v[190:193], v[60:63]
	v_mfma_f32_16x16x32_bf16 v[56:59], v[172:175], v[190:193], v[56:59]
	v_mfma_f32_16x16x32_bf16 v[52:55], v[180:183], v[190:193], v[52:55]
	v_mfma_f32_16x16x32_bf16 v[48:51], v[186:189], v[190:193], v[48:51]
	ds_read_b128 v[210:213], v166 offset:38912
	ds_read_b128 v[190:193], v146
	v_add_u32_e32 v146, v161, v148
	s_waitcnt lgkmcnt(5)
	v_mfma_f32_16x16x32_bf16 v[44:47], v[162:165], v[194:197], v[44:47]
	v_add_u32_e32 v166, v161, v152
	v_mfma_f32_16x16x32_bf16 v[40:43], v[172:175], v[194:197], v[40:43]
	v_mfma_f32_16x16x32_bf16 v[36:39], v[180:183], v[194:197], v[36:39]
	v_mfma_f32_16x16x32_bf16 v[32:35], v[186:189], v[194:197], v[32:35]
	ds_read_b128 v[194:197], v146
	v_add_u32_e32 v230, v161, v154
	s_waitcnt lgkmcnt(4)
	v_mfma_f32_16x16x32_bf16 v[28:31], v[162:165], v[176:179], v[28:31]
	v_mfma_f32_16x16x32_bf16 v[24:27], v[172:175], v[176:179], v[24:27]
	v_mfma_f32_16x16x32_bf16 v[20:23], v[180:183], v[176:179], v[20:23]
	v_mfma_f32_16x16x32_bf16 v[16:19], v[186:189], v[176:179], v[16:19]
	ds_read_b128 v[176:179], v146 offset:2048
	s_waitcnt lgkmcnt(2)
; #define MFMA16(a, b, c) __builtin_amdgcn_mfma_f32_16x16x32_bf16((a), (b), (c), 0, 0, 0)
; DI bf16x8 ldfrag(const char* lds, int row, int chunk) { return *(const bf16x8*)(lds + swz(row, chunk)); }
; #define GEMM_SG1() do { __builtin_amdgcn_sched_group_barrier(0x100, 1, 0); __builtin_amdgcn_sched_group_barrier(0x008, 4, 0); } while (0)
; #define GEMM_SG2() do { __builtin_amdgcn_sched_group_barrier(0x100, 2, 0); __builtin_amdgcn_sched_group_barrier(0x008, 4, 0); } while (0)
; template <bool RSTD, bool SWAP>
; DI void gemm_tile(gacc_t& acc, const bf16_t* __restrict__ A, int lda, const bf16_t* __restrict__ Bt, int ldb, int K,
;                   char* lds, int tid, int wr, int wc, int lane, const float* ssq_row) {
;     ...
;     for (int kt = 0; kt < nk; ++kt) {
;         const char* cur = lds + (kt & 1) * 65536;
;         if (kt + 1 < nk) GEMM_ISSUE(kt + 1, (kt + 1) & 1);
;         bf16x8 bfr[2][4], afr[3];
; #pragma unroll
;         for (int n = 0; n < 4; ++n) bfr[0][n] = ldfrag(cur + 32768, wc * 64 + n * 16 + fr, fq);
;         afr[0] = ldfrag(cur, wr * 128 + fr, fq);
;         afr[1] = ldfrag(cur, wr * 128 + 16 + fr, fq);
; #pragma unroll
;         for (int idx = 0; idx < 16; ++idx) {
;             const int ks = idx >> 3, m = idx & 7;
;             if (idx < 14) afr[(idx + 2) % 3] = ldfrag(cur, wr * 128 + ((idx + 2) & 7) * 16 + fr, ((idx + 2) >> 3) * 4 + fq);
;             if (ks == 0 && m >= 2 && m < 6) bfr[1][m - 2] = ldfrag(cur + 32768, wc * 64 + (m - 2) * 16 + fr, 4 + fq);
; #pragma unroll
;             for (int n = 0; n < 4; ++n) acc[m][n] = SWAP ? MFMA16(bfr[ks][n], afr[idx % 3], acc[m][n]) : MFMA16(afr[idx % 3], bfr[ks][n], acc[m][n]);
;         }
;         __builtin_amdgcn_sched_group_barrier(0x100, 6, 0);
;     ...
;         GEMM_SG1(); GEMM_SG1(); GEMM_SG2(); GEMM_SG2(); GEMM_SG2(); GEMM_SG2(); GEMM_SG1(); GEMM_SG1();
;         GEMM_SG1(); GEMM_SG1(); GEMM_SG1(); GEMM_SG1(); GEMM_SG1(); GEMM_SG1();
;         __builtin_amdgcn_sched_group_barrier(0x008, 8, 0);
;         __builtin_amdgcn_sched_barrier(0);
;         asm volatile("s_waitcnt vmcnt(0)" ::: "memory");
;         __syncthreads();
	v_mfma_f32_16x16x32_bf16 v[12:15], v[162:165], v[190:193], v[12:15]
	v_mfma_f32_16x16x32_bf16 v[8:11], v[172:175], v[190:193], v[8:11]
	v_mfma_f32_16x16x32_bf16 v[4:7], v[180:183], v[190:193], v[4:7]
	v_mfma_f32_16x16x32_bf16 v[0:3], v[186:189], v[190:193], v[0:3]
	ds_read_b128 v[162:165], v146 offset:4096
	s_waitcnt lgkmcnt(2)
	v_mfma_f32_16x16x32_bf16 v[124:127], v[198:201], v[194:197], v[124:127]
	v_mfma_f32_16x16x32_bf16 v[120:123], v[202:205], v[194:197], v[120:123]
	v_mfma_f32_16x16x32_bf16 v[116:119], v[206:209], v[194:197], v[116:119]
	v_mfma_f32_16x16x32_bf16 v[112:115], v[210:213], v[194:197], v[112:115]
	ds_read_b128 v[172:175], v166
	ds_read_b128 v[214:217], v146 offset:8192
	s_waitcnt lgkmcnt(3)
	v_mfma_f32_16x16x32_bf16 v[108:111], v[198:201], v[176:179], v[108:111]
	v_mfma_f32_16x16x32_bf16 v[104:107], v[202:205], v[176:179], v[104:107]
	v_mfma_f32_16x16x32_bf16 v[100:103], v[206:209], v[176:179], v[100:103]
	v_mfma_f32_16x16x32_bf16 v[96:99], v[210:213], v[176:179], v[96:99]
	ds_read_b128 v[218:221], v146 offset:10240
	s_waitcnt lgkmcnt(3)
	v_mfma_f32_16x16x32_bf16 v[92:95], v[198:201], v[162:165], v[92:95]
	v_mfma_f32_16x16x32_bf16 v[88:91], v[202:205], v[162:165], v[88:91]
	v_mfma_f32_16x16x32_bf16 v[84:87], v[206:209], v[162:165], v[84:87]
	v_mfma_f32_16x16x32_bf16 v[80:83], v[210:213], v[162:165], v[80:83]
	ds_read_b128 v[222:225], v146 offset:12288
	ds_read_b128 v[236:239], v230
	s_waitcnt lgkmcnt(4)
	v_mfma_f32_16x16x32_bf16 v[76:79], v[198:201], v[172:175], v[76:79]
	v_mfma_f32_16x16x32_bf16 v[72:75], v[202:205], v[172:175], v[72:75]
	v_mfma_f32_16x16x32_bf16 v[68:71], v[206:209], v[172:175], v[68:71]
	v_mfma_f32_16x16x32_bf16 v[64:67], v[210:213], v[172:175], v[64:67]
	s_waitcnt lgkmcnt(0)
	s_waitcnt vmcnt(0)
	s_add_u32 s12, s12, 0x80
	s_addc_u32 s13, s13, 0
	s_add_i32 s44, s44, 0x10000
	s_cmpk_lg_i32 s12, 0x780
	s_waitcnt vmcnt(0)
	s_barrier
	s_cbranch_scc1 .LBB0_618
	v_mfma_f32_16x16x32_bf16 v[60:63], v[198:201], v[214:217], v[60:63]
	v_mfma_f32_16x16x32_bf16 v[56:59], v[202:205], v[214:217], v[56:59]
	v_mfma_f32_16x16x32_bf16 v[52:55], v[206:209], v[214:217], v[52:55]
	v_mfma_f32_16x16x32_bf16 v[48:51], v[210:213], v[214:217], v[48:51]
	v_mfma_f32_16x16x32_bf16 v[44:47], v[198:201], v[218:221], v[44:47]
	v_mfma_f32_16x16x32_bf16 v[40:43], v[202:205], v[218:221], v[40:43]
	v_mfma_f32_16x16x32_bf16 v[36:39], v[206:209], v[218:221], v[36:39]
	v_mfma_f32_16x16x32_bf16 v[32:35], v[210:213], v[218:221], v[32:35]
	v_mfma_f32_16x16x32_bf16 v[28:31], v[198:201], v[222:225], v[28:31]
	v_mfma_f32_16x16x32_bf16 v[24:27], v[202:205], v[222:225], v[24:27]
	v_mfma_f32_16x16x32_bf16 v[20:23], v[206:209], v[222:225], v[20:23]
	v_mfma_f32_16x16x32_bf16 v[16:19], v[210:213], v[222:225], v[16:19]
	v_mfma_f32_16x16x32_bf16 v[12:15], v[198:201], v[236:239], v[12:15]
	v_mfma_f32_16x16x32_bf16 v[8:11], v[202:205], v[236:239], v[8:11]
	v_mfma_f32_16x16x32_bf16 v[4:7], v[206:209], v[236:239], v[4:7]
	v_mfma_f32_16x16x32_bf16 v[0:3], v[210:213], v[236:239], v[0:3]
	ds_read_b128 v[138:141], v160
	ds_read_b128 v[162:165], v160 offset:2048
	ds_read_b128 v[176:179], v160 offset:4096
	ds_read_b128 v[180:183], v160 offset:6144
	v_add_u32_e32 v146, v156, v148
	ds_read_b128 v[172:175], v146
	ds_read_b128 v[186:189], v146 offset:2048
	v_add_u32_e32 v161, v156, v152
	ds_read_b128 v[190:193], v146 offset:4096
	s_waitcnt lgkmcnt(2)
	v_mfma_f32_16x16x32_bf16 v[124:127], v[138:141], v[172:175], v[124:127]
	v_mfma_f32_16x16x32_bf16 v[120:123], v[162:165], v[172:175], v[120:123]
	v_mfma_f32_16x16x32_bf16 v[116:119], v[176:179], v[172:175], v[116:119]
	v_mfma_f32_16x16x32_bf16 v[112:115], v[180:183], v[172:175], v[112:115]
	ds_read_b128 v[172:175], v161
	v_add_u32_e32 v161, v157, v153
	s_waitcnt lgkmcnt(2)
	v_mfma_f32_16x16x32_bf16 v[108:111], v[138:141], v[186:189], v[108:111]
	v_mfma_f32_16x16x32_bf16 v[104:107], v[162:165], v[186:189], v[104:107]
	v_mfma_f32_16x16x32_bf16 v[100:103], v[176:179], v[186:189], v[100:103]
	v_mfma_f32_16x16x32_bf16 v[96:99], v[180:183], v[186:189], v[96:99]
	ds_read_b128 v[186:189], v146 offset:8192
	ds_read_b128 v[194:197], v161
	s_waitcnt lgkmcnt(3)
	v_mfma_f32_16x16x32_bf16 v[92:95], v[138:141], v[190:193], v[92:95]
	v_mfma_f32_16x16x32_bf16 v[88:91], v[162:165], v[190:193], v[88:91]
	v_mfma_f32_16x16x32_bf16 v[84:87], v[176:179], v[190:193], v[84:87]
	v_mfma_f32_16x16x32_bf16 v[80:83], v[180:183], v[190:193], v[80:83]
	ds_read_b128 v[190:193], v146 offset:10240
	ds_read_b128 v[198:201], v161 offset:2048
	s_waitcnt lgkmcnt(4)
	v_mfma_f32_16x16x32_bf16 v[76:79], v[138:141], v[172:175], v[76:79]
	v_mfma_f32_16x16x32_bf16 v[72:75], v[162:165], v[172:175], v[72:75]
	v_mfma_f32_16x16x32_bf16 v[68:71], v[176:179], v[172:175], v[68:71]
	v_mfma_f32_16x16x32_bf16 v[64:67], v[180:183], v[172:175], v[64:67]
	ds_read_b128 v[172:175], v146 offset:12288
	v_add_u32_e32 v146, v156, v154
	ds_read_b128 v[202:205], v161 offset:4096
	s_waitcnt lgkmcnt(5)
	v_mfma_f32_16x16x32_bf16 v[60:63], v[138:141], v[186:189], v[60:63]
	v_mfma_f32_16x16x32_bf16 v[56:59], v[162:165], v[186:189], v[56:59]
	v_mfma_f32_16x16x32_bf16 v[52:55], v[176:179], v[186:189], v[52:55]
	v_mfma_f32_16x16x32_bf16 v[48:51], v[180:183], v[186:189], v[48:51]
	ds_read_b128 v[186:189], v146
	v_add_u32_e32 v146, v157, v155
	ds_read_b128 v[206:209], v146 offset:6144
	v_add_u32_e32 v146, v158, v148
	s_waitcnt lgkmcnt(5)
; #define MFMA16(a, b, c) __builtin_amdgcn_mfma_f32_16x16x32_bf16((a), (b), (c), 0, 0, 0)
; DI unsigned pk2(float a, float b) { f32x2 v = {a, b}; bf16x2_t r = __builtin_convertvector(v, bf16x2_t); return __builtin_bit_cast(unsigned, r); }
; DI bf16x8 ldfrag(const char* lds, int row, int chunk) { return *(const bf16x8*)(lds + swz(row, chunk)); }
; template <bool RSTD, bool SWAP>
; DI void gemm_tile(gacc_t& acc, const bf16_t* __restrict__ A, int lda, const bf16_t* __restrict__ Bt, int ldb, int K,
;                   char* lds, int tid, int wr, int wc, int lane, const float* ssq_row) {
;     ...
;         for (int idx = 0; idx < 16; ++idx) {
;             const int ks = idx >> 3, m = idx & 7;
;             if (idx < 14) afr[(idx + 2) % 3] = ldfrag(cur, wr * 128 + ((idx + 2) & 7) * 16 + fr, ((idx + 2) >> 3) * 4 + fq);
;             if (ks == 0 && m >= 2 && m < 6) bfr[1][m - 2] = ldfrag(cur + 32768, wc * 64 + (m - 2) * 16 + fr, 4 + fq);
; #pragma unroll
;             for (int n = 0; n < 4; ++n) acc[m][n] = SWAP ? MFMA16(bfr[ks][n], afr[idx % 3], acc[m][n]) : MFMA16(afr[idx % 3], bfr[ks][n], acc[m][n]);
;     DI void operator()(gacc_t& acc, int pm, int pn, char* lds, int tid, int wr, int wc, int lane) const {
;     ...
;             char* lbase = lds + (wr * 128 + fr) * RS + (wc * 64 + 4 * fq) * 2;
;             bf16_t* hrow = halo + (long)(pm * 4) * 5632 + pn * 256 + wc * 64 + 4 * fq;
; #pragma unroll
;             for (int m = 0; m < 8; ++m) {
;                 const float r = rl[m * 16];
; #pragma unroll
;                 for (int n = 0; n < 4; ++n) {
;                     u32x2 w; w.x = pk2(acc[m][n][0] * r, acc[m][n][1] * r); w.y = pk2(acc[m][n][2] * r, acc[m][n][3] * r);
;                     *(u32x2*)(lbase + m * 16 * RS + n * 32) = w;
;                     if (m == 0 && wr == 0 && fr < 2) *(u32x2*)(hrow + fr * 5632 + n * 16) = w;
	v_mfma_f32_16x16x32_bf16 v[44:47], v[138:141], v[190:193], v[44:47]
	v_mfma_f32_16x16x32_bf16 v[40:43], v[162:165], v[190:193], v[40:43]
	v_mfma_f32_16x16x32_bf16 v[36:39], v[176:179], v[190:193], v[36:39]
	v_mfma_f32_16x16x32_bf16 v[32:35], v[180:183], v[190:193], v[32:35]
	ds_read_b128 v[190:193], v146
	s_waitcnt lgkmcnt(4)
	v_mfma_f32_16x16x32_bf16 v[28:31], v[138:141], v[172:175], v[28:31]
	v_mfma_f32_16x16x32_bf16 v[24:27], v[162:165], v[172:175], v[24:27]
	v_mfma_f32_16x16x32_bf16 v[20:23], v[176:179], v[172:175], v[20:23]
	v_mfma_f32_16x16x32_bf16 v[16:19], v[180:183], v[172:175], v[16:19]
	ds_read_b128 v[172:175], v146 offset:2048
	s_waitcnt lgkmcnt(3)
	v_mfma_f32_16x16x32_bf16 v[12:15], v[138:141], v[186:189], v[12:15]
	v_mfma_f32_16x16x32_bf16 v[8:11], v[162:165], v[186:189], v[8:11]
	v_mfma_f32_16x16x32_bf16 v[4:7], v[176:179], v[186:189], v[4:7]
	v_mfma_f32_16x16x32_bf16 v[138:141], v[180:183], v[186:189], v[0:3]
	s_nop 2
	ds_read_b128 v[0:3], v146 offset:4096
	s_waitcnt lgkmcnt(2)
	v_mfma_f32_16x16x32_bf16 v[164:167], v[194:197], v[190:193], v[124:127]
	v_mfma_f32_16x16x32_bf16 v[120:123], v[198:201], v[190:193], v[120:123]
	s_nop 1
	v_add_u32_e32 v124, v158, v152
	v_mfma_f32_16x16x32_bf16 v[116:119], v[202:205], v[190:193], v[116:119]
	v_mfma_f32_16x16x32_bf16 v[112:115], v[206:209], v[190:193], v[112:115]
	ds_read_b128 v[124:127], v124
	s_waitcnt lgkmcnt(2)
	v_mfma_f32_16x16x32_bf16 v[108:111], v[194:197], v[172:175], v[108:111]
	v_mfma_f32_16x16x32_bf16 v[104:107], v[198:201], v[172:175], v[104:107]
	v_mfma_f32_16x16x32_bf16 v[100:103], v[202:205], v[172:175], v[100:103]
	v_mfma_f32_16x16x32_bf16 v[96:99], v[206:209], v[172:175], v[96:99]
	ds_read_b128 v[172:175], v146 offset:8192
	s_waitcnt lgkmcnt(2)
	v_mfma_f32_16x16x32_bf16 v[92:95], v[194:197], v[0:3], v[92:95]
	v_mfma_f32_16x16x32_bf16 v[88:91], v[198:201], v[0:3], v[88:91]
	v_mfma_f32_16x16x32_bf16 v[84:87], v[202:205], v[0:3], v[84:87]
	v_mfma_f32_16x16x32_bf16 v[80:83], v[206:209], v[0:3], v[80:83]
	ds_read_b128 v[0:3], v146 offset:10240
	s_waitcnt lgkmcnt(2)
	v_mfma_f32_16x16x32_bf16 v[76:79], v[194:197], v[124:127], v[76:79]
	v_mfma_f32_16x16x32_bf16 v[72:75], v[198:201], v[124:127], v[72:75]
	v_mfma_f32_16x16x32_bf16 v[68:71], v[202:205], v[124:127], v[68:71]
	v_mfma_f32_16x16x32_bf16 v[64:67], v[206:209], v[124:127], v[64:67]
	ds_read_b128 v[124:127], v146 offset:12288
	v_add_u32_e32 v146, v158, v154
	s_waitcnt lgkmcnt(2)
	v_mfma_f32_16x16x32_bf16 v[60:63], v[194:197], v[172:175], v[60:63]
	v_mfma_f32_16x16x32_bf16 v[56:59], v[198:201], v[172:175], v[56:59]
	v_mfma_f32_16x16x32_bf16 v[52:55], v[202:205], v[172:175], v[52:55]
	v_mfma_f32_16x16x32_bf16 v[48:51], v[206:209], v[172:175], v[48:51]
	ds_read_b128 v[172:175], v146
	s_waitcnt lgkmcnt(2)
	v_mfma_f32_16x16x32_bf16 v[44:47], v[194:197], v[0:3], v[44:47]
	v_mfma_f32_16x16x32_bf16 v[40:43], v[198:201], v[0:3], v[40:43]
	v_mfma_f32_16x16x32_bf16 v[36:39], v[202:205], v[0:3], v[36:39]
	v_mfma_f32_16x16x32_bf16 v[32:35], v[206:209], v[0:3], v[32:35]
	s_waitcnt lgkmcnt(1)
	v_mfma_f32_16x16x32_bf16 v[28:31], v[194:197], v[124:127], v[28:31]
	v_mfma_f32_16x16x32_bf16 v[24:27], v[198:201], v[124:127], v[24:27]
	v_mfma_f32_16x16x32_bf16 v[20:23], v[202:205], v[124:127], v[20:23]
	v_mfma_f32_16x16x32_bf16 v[16:19], v[206:209], v[124:127], v[16:19]
	s_waitcnt lgkmcnt(0)
	v_mfma_f32_16x16x32_bf16 v[12:15], v[194:197], v[172:175], v[12:15]
	v_mfma_f32_16x16x32_bf16 v[8:11], v[198:201], v[172:175], v[8:11]
	v_mfma_f32_16x16x32_bf16 v[0:3], v[202:205], v[172:175], v[4:7]
	v_mfma_f32_16x16x32_bf16 v[4:7], v[206:209], v[172:175], v[138:141]
	s_lshl_b32 s12, s42, 2
	s_mul_i32 s13, s42, 0xb000
	s_mul_hi_i32 s12, s12, 0x2c00
	s_add_u32 s43, s22, s13
	v_mov_b32_e32 v124, v142
	v_mov_b32_e32 v140, v133
	s_addc_u32 s44, s23, s12
	s_lshl_b32 s12, s40, 8
	s_waitcnt vmcnt(0)
	s_barrier
	s_ashr_i32 s13, s12, 31
	v_and_b32_e32 v162, 15, v124
	v_or_b32_e32 v125, v162, v145
	v_ashrrev_i32_e32 v124, 2, v124
	s_lshl_b64 s[12:13], s[12:13], 1
	v_mul_lo_u32 v125, v125, s3
	v_and_b32_e32 v124, -4, v124
	s_add_u32 s12, s43, s12
	v_add_u32_e32 v125, 0, v125
	v_add_lshl_u32 v126, v124, v132, 1
	s_addc_u32 s13, s44, s13
	v_lshlrev_b32_e32 v146, 1, v132
	v_lshl_add_u32 v161, v162, 2, v159
	v_add_u32_e32 v141, v125, v126
	v_lshl_add_u64 v[126:127], s[12:13], 0, v[146:147]
	v_ashrrev_i32_e32 v125, 31, v124
	v_lshl_add_u64 v[124:125], v[124:125], 1, v[126:127]
	ds_read_b32 v126, v161
	v_mul_u32_u24_e32 v127, 0x1600, v162
	v_cmp_gt_u32_e32 vcc, 2, v162
	v_lshlrev_b32_e32 v146, 1, v127
	v_lshl_add_u64 v[124:125], v[124:125], 0, v[146:147]
	s_waitcnt lgkmcnt(0)
	v_pk_mul_f32 v[138:139], v[164:165], v[126:127] op_sel_hi:[1,0]
	v_pk_mul_f32 v[164:165], v[166:167], v[126:127] op_sel_hi:[1,0]
	s_and_b64 s[12:13], s[8:9], vcc
	v_cvt_pk_bf16_f32 v138, v138, v139
	v_cvt_pk_bf16_f32 v139, v164, v165
	ds_write_b64 v141, v[138:139]
	s_and_saveexec_b64 s[44:45], s[12:13]
	s_cbranch_execz .LBB0_621
	flat_store_dwordx2 v[124:125], v[138:139]

; #define MFMA16(a, b, c) __builtin_amdgcn_mfma_f32_16x16x32_bf16((a), (b), (c), 0, 0, 0)
; DI bf16x8 ldfrag(const char* lds, int row, int chunk) { return *(const bf16x8*)(lds + swz(row, chunk)); }
; template <bool RSTD, bool SWAP>
; DI void gemm_tile(gacc_t& acc, const bf16_t* __restrict__ A, int lda, const bf16_t* __restrict__ Bt, int ldb, int K,
;                   char* lds, int tid, int wr, int wc, int lane, const float* ssq_row) {
;     ...
;     for (int kt = 0; kt < nk; ++kt) {
;         const char* cur = lds + (kt & 1) * 65536;
;         if (kt + 1 < nk) GEMM_ISSUE(kt + 1, (kt + 1) & 1);
;         bf16x8 bfr[2][4], afr[3];
; #pragma unroll
;         for (int n = 0; n < 4; ++n) bfr[0][n] = ldfrag(cur + 32768, wc * 64 + n * 16 + fr, fq);
;         afr[0] = ldfrag(cur, wr * 128 + fr, fq);
;         afr[1] = ldfrag(cur, wr * 128 + 16 + fr, fq);
; #pragma unroll
;         for (int idx = 0; idx < 16; ++idx) {
;             const int ks = idx >> 3, m = idx & 7;
;             if (idx < 14) afr[(idx + 2) % 3] = ldfrag(cur, wr * 128 + ((idx + 2) & 7) * 16 + fr, ((idx + 2) >> 3) * 4 + fq);
;             if (ks == 0 && m >= 2 && m < 6) bfr[1][m - 2] = ldfrag(cur + 32768, wc * 64 + (m - 2) * 16 + fr, 4 + fq);
; #pragma unroll
;             for (int n = 0; n < 4; ++n) acc[m][n] = SWAP ? MFMA16(bfr[ks][n], afr[idx % 3], acc[m][n]) : MFMA16(afr[idx % 3], bfr[ks][n], acc[m][n]);
.LBB0_775:
	s_add_i32 s16, s13, 0xffff0000
	v_lshl_add_u64 v[156:157], v[138:139], 0, s[4:5]
	s_and_b32 s18, s13, 0x10000
	s_and_b32 s21, s16, 0x10000
	s_mov_b64 s[16:17], 0x10080080
	v_lshl_add_u64 v[158:159], v[136:137], 0, s[4:5]
	v_lshl_add_u64 v[160:161], v[156:157], 0, s[16:17]
	s_add_i32 s16, s18, 0
	s_mov_b64 s[18:19], 0x4880080
	v_lshl_add_u64 v[162:163], v[158:159], 0, s[18:19]
	s_mov_b64 s[18:19], 0x100d8080
	v_lshl_add_u64 v[164:165], v[156:157], 0, s[18:19]
	s_mov_b64 s[18:19], 0x48d8080
	v_lshl_add_u64 v[166:167], v[158:159], 0, s[18:19]
	s_mov_b64 s[18:19], 0x10130080
	v_lshl_add_u64 v[172:173], v[156:157], 0, s[18:19]
	s_mov_b64 s[18:19], 0x4930080
	v_lshl_add_u64 v[174:175], v[158:159], 0, s[18:19]
	s_mov_b64 s[18:19], 0x10188080
	v_lshl_add_u64 v[156:157], v[156:157], 0, s[18:19]
	s_mov_b64 s[18:19], 0x4988080
	v_lshl_add_u64 v[158:159], v[158:159], 0, s[18:19]
	s_add_i32 s18, s16, s12
	s_add_i32 s19, s18, 0x8000
	s_mov_b32 m0, s18
	s_add_i32 s17, s21, 0
	global_load_lds_dwordx4 v[160:161], off
	v_mfma_f32_16x16x32_bf16 v[60:63], v[190:193], v[236:239], v[60:63]
	s_mov_b32 m0, s19
	v_add_u32_e32 v146, s17, v142
	global_load_lds_dwordx4 v[162:163], off
	v_mfma_f32_16x16x32_bf16 v[56:59], v[194:197], v[236:239], v[56:59]
	s_add_i32 m0, s18, 0x2000
	v_add3_u32 v155, v146, v148, v149
	global_load_lds_dwordx4 v[164:165], off
	v_mfma_f32_16x16x32_bf16 v[52:55], v[198:201], v[236:239], v[52:55]
	s_add_i32 m0, s18, 0xa000
	v_add_u32_e32 v185, v146, v144
	global_load_lds_dwordx4 v[166:167], off
	v_mfma_f32_16x16x32_bf16 v[48:51], v[202:205], v[236:239], v[48:51]
	s_add_i32 m0, s18, 0x4000
	s_nop 0
	global_load_lds_dwordx4 v[172:173], off
	v_mfma_f32_16x16x32_bf16 v[44:47], v[190:193], v[240:243], v[44:47]
	s_add_i32 m0, s18, 0xc000
	s_nop 0
	global_load_lds_dwordx4 v[174:175], off
	v_mfma_f32_16x16x32_bf16 v[40:43], v[194:197], v[240:243], v[40:43]
	s_add_i32 m0, s18, 0x6000
	s_nop 0
	global_load_lds_dwordx4 v[156:157], off
	v_mfma_f32_16x16x32_bf16 v[36:39], v[198:201], v[240:243], v[36:39]
	s_add_i32 m0, s18, 0xe000
	s_nop 0
	global_load_lds_dwordx4 v[158:159], off
	v_mfma_f32_16x16x32_bf16 v[32:35], v[202:205], v[240:243], v[32:35]
	ds_read_b128 v[156:159], v155 offset:32768
	ds_read_b128 v[160:163], v155 offset:34816
	ds_read_b128 v[172:175], v155 offset:36864
	ds_read_b128 v[176:179], v155 offset:38912
	ds_read_b128 v[164:167], v185
	ds_read_b128 v[180:183], v185 offset:2048
	v_add_u32_e32 v155, v146, v150
	ds_read_b128 v[186:189], v185 offset:4096
	v_mfma_f32_16x16x32_bf16 v[28:31], v[190:193], v[244:247], v[28:31]
	v_mfma_f32_16x16x32_bf16 v[24:27], v[194:197], v[244:247], v[24:27]
	v_mfma_f32_16x16x32_bf16 v[20:23], v[198:201], v[244:247], v[20:23]
	v_mfma_f32_16x16x32_bf16 v[16:19], v[202:205], v[244:247], v[16:19]
	v_mfma_f32_16x16x32_bf16 v[12:15], v[190:193], v[248:251], v[12:15]
	v_mfma_f32_16x16x32_bf16 v[8:11], v[194:197], v[248:251], v[8:11]
	v_mfma_f32_16x16x32_bf16 v[4:7], v[198:201], v[248:251], v[4:7]
	v_mfma_f32_16x16x32_bf16 v[0:3], v[202:205], v[248:251], v[0:3]
	s_waitcnt lgkmcnt(2)
	v_mfma_f32_16x16x32_bf16 v[124:127], v[156:159], v[164:167], v[124:127]
	v_add_u32_e32 v146, v146, v152
	v_mfma_f32_16x16x32_bf16 v[120:123], v[160:163], v[164:167], v[120:123]
	v_mfma_f32_16x16x32_bf16 v[116:119], v[172:175], v[164:167], v[116:119]
	v_mfma_f32_16x16x32_bf16 v[112:115], v[176:179], v[164:167], v[112:115]
	ds_read_b128 v[164:167], v155
	v_add_u32_e32 v155, s17, v145
	v_add_u32_e32 v198, v155, v151
	s_waitcnt lgkmcnt(2)
	v_mfma_f32_16x16x32_bf16 v[108:111], v[156:159], v[180:183], v[108:111]
	v_mfma_f32_16x16x32_bf16 v[104:107], v[160:163], v[180:183], v[104:107]
	v_mfma_f32_16x16x32_bf16 v[100:103], v[172:175], v[180:183], v[100:103]
	v_mfma_f32_16x16x32_bf16 v[96:99], v[176:179], v[180:183], v[96:99]
	ds_read_b128 v[180:183], v185 offset:8192
	ds_read_b128 v[190:193], v198 offset:32768
	s_waitcnt lgkmcnt(3)
	v_mfma_f32_16x16x32_bf16 v[92:95], v[156:159], v[186:189], v[92:95]
	v_mfma_f32_16x16x32_bf16 v[88:91], v[160:163], v[186:189], v[88:91]
	v_mfma_f32_16x16x32_bf16 v[84:87], v[172:175], v[186:189], v[84:87]
	v_mfma_f32_16x16x32_bf16 v[80:83], v[176:179], v[186:189], v[80:83]
	ds_read_b128 v[186:189], v185 offset:10240
	ds_read_b128 v[194:197], v198 offset:34816
	s_waitcnt lgkmcnt(4)
	v_mfma_f32_16x16x32_bf16 v[76:79], v[156:159], v[164:167], v[76:79]
	v_mfma_f32_16x16x32_bf16 v[72:75], v[160:163], v[164:167], v[72:75]
	v_mfma_f32_16x16x32_bf16 v[68:71], v[172:175], v[164:167], v[68:71]
	v_mfma_f32_16x16x32_bf16 v[64:67], v[176:179], v[164:167], v[64:67]
	ds_read_b128 v[164:167], v185 offset:12288
	v_add_u32_e32 v185, v155, v153
	ds_read_b128 v[198:201], v198 offset:36864
	s_waitcnt lgkmcnt(5)
	v_mfma_f32_16x16x32_bf16 v[60:63], v[156:159], v[180:183], v[60:63]
	v_mfma_f32_16x16x32_bf16 v[56:59], v[160:163], v[180:183], v[56:59]
	v_mfma_f32_16x16x32_bf16 v[52:55], v[172:175], v[180:183], v[52:55]
	v_mfma_f32_16x16x32_bf16 v[48:51], v[176:179], v[180:183], v[48:51]
	ds_read_b128 v[202:205], v185 offset:38912
	ds_read_b128 v[180:183], v146
	v_add_u32_e32 v146, v155, v144
	s_waitcnt lgkmcnt(5)
	v_mfma_f32_16x16x32_bf16 v[44:47], v[156:159], v[186:189], v[44:47]
	v_mfma_f32_16x16x32_bf16 v[40:43], v[160:163], v[186:189], v[40:43]
	v_mfma_f32_16x16x32_bf16 v[36:39], v[172:175], v[186:189], v[36:39]
	v_mfma_f32_16x16x32_bf16 v[32:35], v[176:179], v[186:189], v[32:35]
	ds_read_b128 v[186:189], v146
	s_waitcnt lgkmcnt(4)
	v_mfma_f32_16x16x32_bf16 v[28:31], v[156:159], v[164:167], v[28:31]
	v_mfma_f32_16x16x32_bf16 v[24:27], v[160:163], v[164:167], v[24:27]
	v_mfma_f32_16x16x32_bf16 v[20:23], v[172:175], v[164:167], v[20:23]
	v_mfma_f32_16x16x32_bf16 v[16:19], v[176:179], v[164:167], v[16:19]
	ds_read_b128 v[164:167], v146 offset:2048
	s_waitcnt lgkmcnt(2)
; #define MFMA16(a, b, c) __builtin_amdgcn_mfma_f32_16x16x32_bf16((a), (b), (c), 0, 0, 0)
; DI bf16x8 ldfrag(const char* lds, int row, int chunk) { return *(const bf16x8*)(lds + swz(row, chunk)); }
; #define GEMM_SG1() do { __builtin_amdgcn_sched_group_barrier(0x100, 1, 0); __builtin_amdgcn_sched_group_barrier(0x008, 4, 0); } while (0)
; #define GEMM_SG2() do { __builtin_amdgcn_sched_group_barrier(0x100, 2, 0); __builtin_amdgcn_sched_group_barrier(0x008, 4, 0); } while (0)
; template <bool RSTD, bool SWAP>
; DI void gemm_tile(gacc_t& acc, const bf16_t* __restrict__ A, int lda, const bf16_t* __restrict__ Bt, int ldb, int K,
;                   char* lds, int tid, int wr, int wc, int lane, const float* ssq_row) {
;     ...
;         for (int idx = 0; idx < 16; ++idx) {
;             const int ks = idx >> 3, m = idx & 7;
;             if (idx < 14) afr[(idx + 2) % 3] = ldfrag(cur, wr * 128 + ((idx + 2) & 7) * 16 + fr, ((idx + 2) >> 3) * 4 + fq);
;             if (ks == 0 && m >= 2 && m < 6) bfr[1][m - 2] = ldfrag(cur + 32768, wc * 64 + (m - 2) * 16 + fr, 4 + fq);
; #pragma unroll
;             for (int n = 0; n < 4; ++n) acc[m][n] = SWAP ? MFMA16(bfr[ks][n], afr[idx % 3], acc[m][n]) : MFMA16(afr[idx % 3], bfr[ks][n], acc[m][n]);
;         }
;         __builtin_amdgcn_sched_group_barrier(0x100, 6, 0);
;     ...
;         GEMM_SG1(); GEMM_SG1(); GEMM_SG2(); GEMM_SG2(); GEMM_SG2(); GEMM_SG2(); GEMM_SG1(); GEMM_SG1();
;         GEMM_SG1(); GEMM_SG1(); GEMM_SG1(); GEMM_SG1(); GEMM_SG1(); GEMM_SG1();
;         __builtin_amdgcn_sched_group_barrier(0x008, 8, 0);
;         __builtin_amdgcn_sched_barrier(0);
;         asm volatile("s_waitcnt vmcnt(0)" ::: "memory");
;         __syncthreads();
;     }
	v_mfma_f32_16x16x32_bf16 v[8:11], v[160:163], v[180:183], v[8:11]
	v_add_u32_e32 v160, v155, v150
	v_mfma_f32_16x16x32_bf16 v[12:15], v[156:159], v[180:183], v[12:15]
	v_mfma_f32_16x16x32_bf16 v[4:7], v[172:175], v[180:183], v[4:7]
	v_mfma_f32_16x16x32_bf16 v[0:3], v[176:179], v[180:183], v[0:3]
	ds_read_b128 v[156:159], v146 offset:4096
	s_waitcnt lgkmcnt(2)
	v_mfma_f32_16x16x32_bf16 v[124:127], v[190:193], v[186:189], v[124:127]
	v_mfma_f32_16x16x32_bf16 v[120:123], v[194:197], v[186:189], v[120:123]
	v_mfma_f32_16x16x32_bf16 v[116:119], v[198:201], v[186:189], v[116:119]
	v_mfma_f32_16x16x32_bf16 v[112:115], v[202:205], v[186:189], v[112:115]
	ds_read_b128 v[160:163], v160
	s_waitcnt lgkmcnt(2)
	v_mfma_f32_16x16x32_bf16 v[108:111], v[190:193], v[164:167], v[108:111]
	v_mfma_f32_16x16x32_bf16 v[104:107], v[194:197], v[164:167], v[104:107]
	v_mfma_f32_16x16x32_bf16 v[100:103], v[198:201], v[164:167], v[100:103]
	v_mfma_f32_16x16x32_bf16 v[96:99], v[202:205], v[164:167], v[96:99]
	ds_read_b128 v[236:239], v146 offset:8192
	s_waitcnt lgkmcnt(2)
	v_mfma_f32_16x16x32_bf16 v[92:95], v[190:193], v[156:159], v[92:95]
	v_mfma_f32_16x16x32_bf16 v[88:91], v[194:197], v[156:159], v[88:91]
	v_mfma_f32_16x16x32_bf16 v[84:87], v[198:201], v[156:159], v[84:87]
	v_mfma_f32_16x16x32_bf16 v[80:83], v[202:205], v[156:159], v[80:83]
	ds_read_b128 v[240:243], v146 offset:10240
	ds_read_b128 v[244:247], v146 offset:12288
	v_add_u32_e32 v146, v155, v152
	ds_read_b128 v[248:251], v146
	s_waitcnt lgkmcnt(4)
	v_mfma_f32_16x16x32_bf16 v[76:79], v[190:193], v[160:163], v[76:79]
	v_mfma_f32_16x16x32_bf16 v[72:75], v[194:197], v[160:163], v[72:75]
	v_mfma_f32_16x16x32_bf16 v[68:71], v[198:201], v[160:163], v[68:71]
	v_mfma_f32_16x16x32_bf16 v[64:67], v[202:205], v[160:163], v[64:67]
	s_waitcnt lgkmcnt(0)
	s_waitcnt vmcnt(0)
	s_add_u32 s4, s4, 0x80
	s_addc_u32 s5, s5, 0
	s_add_i32 s13, s13, 0x10000
	s_cmpk_eq_i32 s4, 0x1580
	s_waitcnt vmcnt(0)
	s_barrier
	s_cbranch_scc0 .LBB0_775
	v_mfma_f32_16x16x32_bf16 v[60:63], v[190:193], v[236:239], v[60:63]
	v_mfma_f32_16x16x32_bf16 v[56:59], v[194:197], v[236:239], v[56:59]
	v_mfma_f32_16x16x32_bf16 v[52:55], v[198:201], v[236:239], v[52:55]
	v_mfma_f32_16x16x32_bf16 v[48:51], v[202:205], v[236:239], v[48:51]
	v_mfma_f32_16x16x32_bf16 v[44:47], v[190:193], v[240:243], v[44:47]
	v_mfma_f32_16x16x32_bf16 v[40:43], v[194:197], v[240:243], v[40:43]
	v_mfma_f32_16x16x32_bf16 v[36:39], v[198:201], v[240:243], v[36:39]
	v_mfma_f32_16x16x32_bf16 v[32:35], v[202:205], v[240:243], v[32:35]
	v_mfma_f32_16x16x32_bf16 v[28:31], v[190:193], v[244:247], v[28:31]
	v_mfma_f32_16x16x32_bf16 v[24:27], v[194:197], v[244:247], v[24:27]
	v_mfma_f32_16x16x32_bf16 v[20:23], v[198:201], v[244:247], v[20:23]
	v_mfma_f32_16x16x32_bf16 v[16:19], v[202:205], v[244:247], v[16:19]
	v_mfma_f32_16x16x32_bf16 v[12:15], v[190:193], v[248:251], v[12:15]
	v_mfma_f32_16x16x32_bf16 v[8:11], v[194:197], v[248:251], v[8:11]
	v_mfma_f32_16x16x32_bf16 v[4:7], v[198:201], v[248:251], v[4:7]
	v_mfma_f32_16x16x32_bf16 v[0:3], v[202:205], v[248:251], v[0:3]
	v_add_u32_e32 v146, s16, v142
	v_add3_u32 v155, v146, v148, v149
	ds_read_b128 v[136:139], v155 offset:32768
	ds_read_b128 v[156:159], v155 offset:34816
	ds_read_b128 v[164:167], v155 offset:36864
	ds_read_b128 v[172:175], v155 offset:38912
	v_add_u32_e32 v185, v146, v144
	ds_read_b128 v[160:163], v185
	ds_read_b128 v[176:179], v185 offset:2048
	v_add_u32_e32 v155, v146, v150
	ds_read_b128 v[180:183], v185 offset:4096
	s_waitcnt lgkmcnt(2)
	v_mfma_f32_16x16x32_bf16 v[124:127], v[136:139], v[160:163], v[124:127]
	v_add_u32_e32 v146, v146, v152
	s_lshl_b64 s[12:13], s[8:9], 8
	v_mfma_f32_16x16x32_bf16 v[120:123], v[156:159], v[160:163], v[120:123]
	v_mfma_f32_16x16x32_bf16 v[116:119], v[164:167], v[160:163], v[116:119]
	v_mfma_f32_16x16x32_bf16 v[112:115], v[172:175], v[160:163], v[112:115]
	ds_read_b128 v[160:163], v155
	v_add_u32_e32 v155, s16, v145
	v_add_u32_e32 v194, v155, v151
	s_waitcnt lgkmcnt(2)
	v_mfma_f32_16x16x32_bf16 v[108:111], v[136:139], v[176:179], v[108:111]
	v_mfma_f32_16x16x32_bf16 v[104:107], v[156:159], v[176:179], v[104:107]
	v_mfma_f32_16x16x32_bf16 v[100:103], v[164:167], v[176:179], v[100:103]
	v_mfma_f32_16x16x32_bf16 v[96:99], v[172:175], v[176:179], v[96:99]
	ds_read_b128 v[176:179], v185 offset:8192
	ds_read_b128 v[186:189], v194 offset:32768
	s_waitcnt lgkmcnt(3)
	v_mfma_f32_16x16x32_bf16 v[92:95], v[136:139], v[180:183], v[92:95]
	v_mfma_f32_16x16x32_bf16 v[88:91], v[156:159], v[180:183], v[88:91]
	v_mfma_f32_16x16x32_bf16 v[84:87], v[164:167], v[180:183], v[84:87]
	v_mfma_f32_16x16x32_bf16 v[80:83], v[172:175], v[180:183], v[80:83]
	ds_read_b128 v[180:183], v185 offset:10240
	ds_read_b128 v[190:193], v194 offset:34816
	s_waitcnt lgkmcnt(4)
	v_mfma_f32_16x16x32_bf16 v[76:79], v[136:139], v[160:163], v[76:79]
	v_mfma_f32_16x16x32_bf16 v[72:75], v[156:159], v[160:163], v[72:75]
	v_mfma_f32_16x16x32_bf16 v[68:71], v[164:167], v[160:163], v[68:71]
	v_mfma_f32_16x16x32_bf16 v[64:67], v[172:175], v[160:163], v[64:67]
	ds_read_b128 v[160:163], v185 offset:12288
	ds_read_b128 v[194:197], v194 offset:36864
	s_waitcnt lgkmcnt(5)
	v_mfma_f32_16x16x32_bf16 v[60:63], v[136:139], v[176:179], v[60:63]
	v_mfma_f32_16x16x32_bf16 v[56:59], v[156:159], v[176:179], v[56:59]
	v_mfma_f32_16x16x32_bf16 v[52:55], v[164:167], v[176:179], v[52:55]
	v_mfma_f32_16x16x32_bf16 v[48:51], v[172:175], v[176:179], v[48:51]
	ds_read_b128 v[176:179], v146
	v_add_u32_e32 v146, v155, v153
	ds_read_b128 v[198:201], v146 offset:38912
	v_add_u32_e32 v146, v155, v144
	s_waitcnt lgkmcnt(5)
; #define MFMA16(a, b, c) __builtin_amdgcn_mfma_f32_16x16x32_bf16((a), (b), (c), 0, 0, 0)
; DI unsigned pk2(float a, float b) { f32x2 v = {a, b}; bf16x2_t r = __builtin_convertvector(v, bf16x2_t); return __builtin_bit_cast(unsigned, r); }
; DI bf16x8 ldfrag(const char* lds, int row, int chunk) { return *(const bf16x8*)(lds + swz(row, chunk)); }
; template <bool RSTD, bool SWAP>
; DI void gemm_tile(gacc_t& acc, const bf16_t* __restrict__ A, int lda, const bf16_t* __restrict__ Bt, int ldb, int K,
;                   char* lds, int tid, int wr, int wc, int lane, const float* ssq_row) {
;     ...
;         for (int idx = 0; idx < 16; ++idx) {
;             const int ks = idx >> 3, m = idx & 7;
;             if (idx < 14) afr[(idx + 2) % 3] = ldfrag(cur, wr * 128 + ((idx + 2) & 7) * 16 + fr, ((idx + 2) >> 3) * 4 + fq);
;             if (ks == 0 && m >= 2 && m < 6) bfr[1][m - 2] = ldfrag(cur + 32768, wc * 64 + (m - 2) * 16 + fr, 4 + fq);
; #pragma unroll
;             for (int n = 0; n < 4; ++n) acc[m][n] = SWAP ? MFMA16(bfr[ks][n], afr[idx % 3], acc[m][n]) : MFMA16(afr[idx % 3], bfr[ks][n], acc[m][n]);
;     DI void operator()(gacc_t& acc, int pm, int pn, char* lds, int tid, int wr, int wc, int lane) const {
;     ...
;         char* lbase = lds + (wr * 128 + fr) * 528 + (wc * 64 + 4 * fq) * 2;
; #pragma unroll
;         for (int m = 0; m < 8; ++m)
; #pragma unroll
;             for (int n = 0; n < 4; ++n) { u32x2 w; w.x = pk2(acc[m][n][0], acc[m][n][1]); w.y = pk2(acc[m][n][2], acc[m][n][3]); *(u32x2*)(lbase + m * 16 * 528 + n * 32) = w; }
	v_mfma_f32_16x16x32_bf16 v[44:47], v[136:139], v[180:183], v[44:47]
	v_mfma_f32_16x16x32_bf16 v[40:43], v[156:159], v[180:183], v[40:43]
	v_mfma_f32_16x16x32_bf16 v[36:39], v[164:167], v[180:183], v[36:39]
	v_mfma_f32_16x16x32_bf16 v[32:35], v[172:175], v[180:183], v[32:35]
	ds_read_b128 v[180:183], v146
	s_waitcnt lgkmcnt(4)
	v_mfma_f32_16x16x32_bf16 v[28:31], v[136:139], v[160:163], v[28:31]
	v_mfma_f32_16x16x32_bf16 v[24:27], v[156:159], v[160:163], v[24:27]
	v_mfma_f32_16x16x32_bf16 v[20:23], v[164:167], v[160:163], v[20:23]
	v_mfma_f32_16x16x32_bf16 v[16:19], v[172:175], v[160:163], v[16:19]
	ds_read_b128 v[160:163], v146 offset:2048
	s_waitcnt lgkmcnt(3)
	v_mfma_f32_16x16x32_bf16 v[8:11], v[156:159], v[176:179], v[8:11]
	v_add_u32_e32 v156, v155, v150
	v_mfma_f32_16x16x32_bf16 v[12:15], v[136:139], v[176:179], v[12:15]
	v_mfma_f32_16x16x32_bf16 v[4:7], v[164:167], v[176:179], v[4:7]
	v_mfma_f32_16x16x32_bf16 v[0:3], v[172:175], v[176:179], v[0:3]
	ds_read_b128 v[136:139], v146 offset:4096
	s_waitcnt lgkmcnt(2)
	v_mfma_f32_16x16x32_bf16 v[124:127], v[186:189], v[180:183], v[124:127]
	v_mfma_f32_16x16x32_bf16 v[120:123], v[190:193], v[180:183], v[120:123]
	v_mfma_f32_16x16x32_bf16 v[116:119], v[194:197], v[180:183], v[116:119]
	v_mfma_f32_16x16x32_bf16 v[112:115], v[198:201], v[180:183], v[112:115]
	ds_read_b128 v[156:159], v156
	s_waitcnt lgkmcnt(2)
	v_mfma_f32_16x16x32_bf16 v[108:111], v[186:189], v[160:163], v[108:111]
	v_mfma_f32_16x16x32_bf16 v[104:107], v[190:193], v[160:163], v[104:107]
	v_mfma_f32_16x16x32_bf16 v[100:103], v[194:197], v[160:163], v[100:103]
	v_mfma_f32_16x16x32_bf16 v[96:99], v[198:201], v[160:163], v[96:99]
	ds_read_b128 v[160:163], v146 offset:8192
	s_waitcnt lgkmcnt(2)
	v_mfma_f32_16x16x32_bf16 v[92:95], v[186:189], v[136:139], v[92:95]
	v_mfma_f32_16x16x32_bf16 v[88:91], v[190:193], v[136:139], v[88:91]
	v_mfma_f32_16x16x32_bf16 v[84:87], v[194:197], v[136:139], v[84:87]
	v_mfma_f32_16x16x32_bf16 v[80:83], v[198:201], v[136:139], v[80:83]
	ds_read_b128 v[136:139], v146 offset:10240
	s_waitcnt lgkmcnt(2)
	v_mfma_f32_16x16x32_bf16 v[76:79], v[186:189], v[156:159], v[76:79]
	v_mfma_f32_16x16x32_bf16 v[72:75], v[190:193], v[156:159], v[72:75]
	v_mfma_f32_16x16x32_bf16 v[68:71], v[194:197], v[156:159], v[68:71]
	v_mfma_f32_16x16x32_bf16 v[64:67], v[198:201], v[156:159], v[64:67]
	ds_read_b128 v[156:159], v146 offset:12288
	v_add_u32_e32 v146, v155, v152
	s_waitcnt lgkmcnt(2)
	v_mfma_f32_16x16x32_bf16 v[60:63], v[186:189], v[160:163], v[60:63]
	v_mfma_f32_16x16x32_bf16 v[56:59], v[190:193], v[160:163], v[56:59]
	v_mfma_f32_16x16x32_bf16 v[52:55], v[194:197], v[160:163], v[52:55]
	v_mfma_f32_16x16x32_bf16 v[48:51], v[198:201], v[160:163], v[48:51]
	ds_read_b128 v[160:163], v146
	s_waitcnt lgkmcnt(2)
	v_mfma_f32_16x16x32_bf16 v[44:47], v[186:189], v[136:139], v[44:47]
	v_mfma_f32_16x16x32_bf16 v[40:43], v[190:193], v[136:139], v[40:43]
	v_mfma_f32_16x16x32_bf16 v[36:39], v[194:197], v[136:139], v[36:39]
	v_mfma_f32_16x16x32_bf16 v[32:35], v[198:201], v[136:139], v[32:35]
	s_waitcnt lgkmcnt(1)
	v_mfma_f32_16x16x32_bf16 v[24:27], v[190:193], v[156:159], v[24:27]
	v_mfma_f32_16x16x32_bf16 v[20:23], v[194:197], v[156:159], v[20:23]
	v_mfma_f32_16x16x32_bf16 v[16:19], v[198:201], v[156:159], v[16:19]
	s_waitcnt lgkmcnt(0)
	v_mfma_f32_16x16x32_bf16 v[12:15], v[186:189], v[160:163], v[12:15]
	v_mfma_f32_16x16x32_bf16 v[8:11], v[190:193], v[160:163], v[8:11]
	v_mfma_f32_16x16x32_bf16 v[4:7], v[194:197], v[160:163], v[4:7]
	v_mfma_f32_16x16x32_bf16 v[0:3], v[198:201], v[160:163], v[0:3]
	v_mfma_f32_16x16x32_bf16 v[28:31], v[186:189], v[156:159], v[28:31]
	v_mov_b32_e32 v136, v140
	v_mov_b32_e32 v137, v141
	s_waitcnt vmcnt(0)
	s_barrier
	v_cvt_pk_bf16_f32 v124, v124, v125
	v_and_or_b32 v138, v137, 15, v143
	v_ashrrev_i32_e32 v139, 1, v137
	v_mul_lo_u32 v138, v138, s3
	v_and_b32_e32 v139, -8, v139
	v_add3_u32 v138, v154, v138, v139
	v_cvt_pk_bf16_f32 v125, v126, v127
	v_cvt_pk_bf16_f32 v120, v120, v121
	v_cvt_pk_bf16_f32 v121, v122, v123
	v_cvt_pk_bf16_f32 v116, v116, v117
	v_cvt_pk_bf16_f32 v117, v118, v119
	v_cvt_pk_bf16_f32 v112, v112, v113
	v_cvt_pk_bf16_f32 v113, v114, v115
	v_cvt_pk_bf16_f32 v108, v108, v109
	v_cvt_pk_bf16_f32 v109, v110, v111
	v_cvt_pk_bf16_f32 v104, v104, v105
	v_cvt_pk_bf16_f32 v105, v106, v107
	v_add_u32_e32 v106, 0x2000, v138
	v_cvt_pk_bf16_f32 v100, v100, v101
	v_cvt_pk_bf16_f32 v101, v102, v103
	v_cvt_pk_bf16_f32 v96, v96, v97
	v_cvt_pk_bf16_f32 v97, v98, v99
	v_cvt_pk_bf16_f32 v92, v92, v93
	v_cvt_pk_bf16_f32 v93, v94, v95
	v_cvt_pk_bf16_f32 v88, v88, v89
	v_cvt_pk_bf16_f32 v89, v90, v91
	v_add_u32_e32 v90, 0x4000, v138
	v_cvt_pk_bf16_f32 v84, v84, v85
	v_cvt_pk_bf16_f32 v85, v86, v87
	v_cvt_pk_bf16_f32 v80, v80, v81
	v_cvt_pk_bf16_f32 v81, v82, v83
	v_cvt_pk_bf16_f32 v76, v76, v77
	v_cvt_pk_bf16_f32 v77, v78, v79
	v_cvt_pk_bf16_f32 v72, v72, v73
	v_cvt_pk_bf16_f32 v73, v74, v75
	v_add_u32_e32 v74, 0x6000, v138
	v_cvt_pk_bf16_f32 v68, v68, v69
	v_cvt_pk_bf16_f32 v69, v70, v71
	v_cvt_pk_bf16_f32 v64, v64, v65
	v_cvt_pk_bf16_f32 v65, v66, v67
	v_cvt_pk_bf16_f32 v60, v60, v61
	v_cvt_pk_bf16_f32 v61, v62, v63
	v_cvt_pk_bf16_f32 v56, v56, v57
	v_cvt_pk_bf16_f32 v57, v58, v59
	v_add_u32_e32 v58, 0x8000, v138
	v_cvt_pk_bf16_f32 v52, v52, v53
	v_cvt_pk_bf16_f32 v53, v54, v55
	v_cvt_pk_bf16_f32 v48, v48, v49
	v_cvt_pk_bf16_f32 v49, v50, v51
	v_cvt_pk_bf16_f32 v44, v44, v45
	v_cvt_pk_bf16_f32 v45, v46, v47
	v_cvt_pk_bf16_f32 v40, v40, v41
	v_cvt_pk_bf16_f32 v41, v42, v43
	v_add_u32_e32 v42, 0xa000, v138
	v_cvt_pk_bf16_f32 v36, v36, v37
	v_cvt_pk_bf16_f32 v37, v38, v39
	v_cvt_pk_bf16_f32 v32, v32, v33
; DI unsigned pk2(float a, float b) { f32x2 v = {a, b}; bf16x2_t r = __builtin_convertvector(v, bf16x2_t); return __builtin_bit_cast(unsigned, r); }
; DI float bflo(unsigned w) { return __uint_as_float(w << 16); }
; DI float bfhi(unsigned w) { return __uint_as_float(w & 0xffff0000u); }
;     DI void operator()(gacc_t& acc, int pm, int pn, char* lds, int tid, int wr, int wc, int lane) const {
;     ...
;             for (int n = 0; n < 4; ++n) { u32x2 w; w.x = pk2(acc[m][n][0], acc[m][n][1]); w.y = pk2(acc[m][n][2], acc[m][n][3]); *(u32x2*)(lbase + m * 16 * 528 + n * 32) = w; }
;         __builtin_amdgcn_sched_barrier(0);
;         __syncthreads();
;         __builtin_amdgcn_sched_barrier(0);
;         const int g = lane >> 5, j32 = lane & 31;
; #pragma unroll
;         for (int ib = 0; ib < 4; ++ib) {
;             __builtin_amdgcn_sched_barrier(0);
;             u32x4 xv[4];
; #pragma unroll
;             for (int u = 0; u < 4; ++u) {
;                 const long row = (long)pm * 256 + (ib * 4 + u) * 16 + wid * 2 + g;
;                 xv[u] = *(const u32x4*)(xold + row * 1024 + pn * 256 + j32 * 8);
;             }
; #pragma unroll
;             for (int u = 0; u < 4; ++u) {
;                 const int rloc = (ib * 4 + u) * 16 + wid * 2 + g;
;                 const long row = (long)pm * 256 + rloc;
;                 const u32x4 a = *(const u32x4*)(lds + rloc * 528 + j32 * 16);
;                 u32x4 w; float ss = 0.f;
; #pragma unroll
;                 for (int e = 0; e < 4; ++e) {
;                     w[e] = pk2(bflo(xv[u][e]) + bflo(a[e]), bfhi(xv[u][e]) + bfhi(a[e]));
;                     const float b0 = bflo(w[e]), b1 = bfhi(w[e]);
;                     ss += b0 * b0 + b1 * b1;
;                 }
;                 *(u32x4*)(xnew + row * 1024 + pn * 256 + j32 * 8) = w;
; #pragma unroll
;                 for (int o = 1; o < 32; o <<= 1) ss += __shfl_xor(ss, o);
;                 if (j32 == 0) ssq[row * 4 + pn] = ss;
	v_cvt_pk_bf16_f32 v33, v34, v35
	v_cvt_pk_bf16_f32 v28, v28, v29
	v_cvt_pk_bf16_f32 v29, v30, v31
	v_cvt_pk_bf16_f32 v24, v24, v25
	v_cvt_pk_bf16_f32 v25, v26, v27
	v_add_u32_e32 v26, 0xc000, v138
	v_cvt_pk_bf16_f32 v20, v20, v21
	v_cvt_pk_bf16_f32 v21, v22, v23
	v_cvt_pk_bf16_f32 v16, v16, v17
	v_cvt_pk_bf16_f32 v17, v18, v19
	v_cvt_pk_bf16_f32 v12, v12, v13
	v_cvt_pk_bf16_f32 v13, v14, v15
	v_cvt_pk_bf16_f32 v8, v8, v9
	v_cvt_pk_bf16_f32 v9, v10, v11
	v_add_u32_e32 v10, 0xe000, v138
	v_cvt_pk_bf16_f32 v4, v4, v5
	v_cvt_pk_bf16_f32 v5, v6, v7
	v_cvt_pk_bf16_f32 v0, v0, v1
	v_cvt_pk_bf16_f32 v1, v2, v3
	ds_write2_b64 v138, v[124:125], v[120:121] offset1:4
	ds_write2_b64 v138, v[116:117], v[112:113] offset0:8 offset1:12
	ds_write2_b64 v106, v[108:109], v[104:105] offset0:32 offset1:36
	ds_write2_b64 v106, v[100:101], v[96:97] offset0:40 offset1:44
	ds_write2_b64 v90, v[92:93], v[88:89] offset0:64 offset1:68
	ds_write2_b64 v90, v[84:85], v[80:81] offset0:72 offset1:76
	ds_write2_b64 v74, v[76:77], v[72:73] offset0:96 offset1:100
	ds_write2_b64 v74, v[68:69], v[64:65] offset0:104 offset1:108
	ds_write2_b64 v58, v[60:61], v[56:57] offset0:128 offset1:132
	ds_write2_b64 v58, v[52:53], v[48:49] offset0:136 offset1:140
	ds_write2_b64 v42, v[44:45], v[40:41] offset0:160 offset1:164
	ds_write2_b64 v42, v[36:37], v[32:33] offset0:168 offset1:172
	ds_write2_b64 v26, v[28:29], v[24:25] offset0:192 offset1:196
	ds_write2_b64 v26, v[20:21], v[16:17] offset0:200 offset1:204
	ds_write2_b64 v10, v[12:13], v[8:9] offset0:224 offset1:228
	ds_write2_b64 v10, v[4:5], v[0:1] offset0:232 offset1:236
	s_waitcnt lgkmcnt(0)
	s_barrier
	v_ashrrev_i32_e32 v0, 5, v137
	v_ashrrev_i32_e32 v1, 5, v136
	v_and_b32_e32 v14, 31, v137
	v_and_b32_e32 v2, -2, v1
	v_ashrrev_i32_e32 v1, 31, v0
	v_ashrrev_i32_e32 v3, 31, v2
	v_lshl_add_u64 v[4:5], s[12:13], 0, v[0:1]
	s_lshl_b32 s16, s6, 8
	v_add_u32_e32 v16, v2, v0
	v_lshlrev_b32_e32 v146, 4, v14
	v_and_b32_e32 v0, 64, v169
	v_lshl_add_u64 v[4:5], v[4:5], 0, v[2:3]
	s_ashr_i32 s17, s16, 31
	v_add_u32_e32 v26, 0, v146
	v_add_u32_e32 v15, 64, v0
	v_cmp_eq_u32_e64 s[4:5], 0, v14
	v_cmp_eq_u32_e64 s[98:99], 16, v14
	s_lshl_b64 s[18:19], s[16:17], 1
	s_add_u32 s22, s68, s18
	s_addc_u32 s23, s69, s19
	v_lshl_add_u64 v[0:1], s[22:23], 0, v[146:147]
	v_lshlrev_b64 v[2:3], 11, v[4:5]
	v_lshl_add_u64 v[18:19], v[0:1], 0, v[2:3]
	flat_load_dwordx4 v[22:25], v[18:19]
	v_add_co_u32_e32 v0, vcc, s49, v18
	v_mul_lo_u32 v20, v16, s3
	s_nop 0
	v_addc_co_u32_e32 v1, vcc, 0, v19, vcc
	flat_load_dwordx4 v[8:11], v[0:1]
	v_add_co_u32_e32 v0, vcc, s48, v18
	v_add_u32_e32 v12, v26, v20
	s_nop 0
	v_addc_co_u32_e32 v1, vcc, 0, v19, vcc
	flat_load_dwordx4 v[4:7], v[0:1]
	v_add_co_u32_e32 v0, vcc, s47, v18
	ds_read_b128 v[28:31], v12
	s_nop 0
	v_addc_co_u32_e32 v1, vcc, 0, v19, vcc
	flat_load_dwordx4 v[0:3], v[0:1]
	v_ashrrev_i32_e32 v17, 31, v16
	s_waitcnt lgkmcnt(0)
	v_lshlrev_b32_e32 v32, 16, v28
	v_and_b32_e32 v33, 0xffff0000, v28
	v_lshlrev_b32_e32 v28, 16, v29
	v_and_b32_e32 v29, 0xffff0000, v29
	s_waitcnt vmcnt(0)
	v_lshlrev_b32_e32 v12, 16, v22
	v_and_b32_e32 v13, 0xffff0000, v22
	v_pk_add_f32 v[12:13], v[12:13], v[32:33]
	s_nop 0
	v_cvt_pk_bf16_f32 v22, v12, v13
	v_and_b32_e32 v13, 0xffff0000, v22
	v_lshlrev_b32_e32 v12, 16, v22
	v_mul_f32_e32 v21, v13, v13
	v_fmac_f32_e32 v21, v12, v12
	v_lshlrev_b32_e32 v12, 16, v23
	v_and_b32_e32 v13, 0xffff0000, v23
	v_pk_add_f32 v[12:13], v[12:13], v[28:29]
	v_lshlrev_b32_e32 v28, 16, v30
	v_cvt_pk_bf16_f32 v23, v12, v13
	v_and_b32_e32 v13, 0xffff0000, v23
	v_lshlrev_b32_e32 v12, 16, v23
	v_mul_f32_e32 v13, v13, v13
	v_fmac_f32_e32 v13, v12, v12
	v_add_f32_e32 v21, v21, v13
	v_lshlrev_b32_e32 v12, 16, v24
	v_and_b32_e32 v13, 0xffff0000, v24
	v_and_b32_e32 v29, 0xffff0000, v30
	v_pk_add_f32 v[12:13], v[12:13], v[28:29]
	v_lshlrev_b32_e32 v28, 16, v31
	v_cvt_pk_bf16_f32 v24, v12, v13
	v_and_b32_e32 v13, 0xffff0000, v24
	v_lshlrev_b32_e32 v12, 16, v24
	v_mul_f32_e32 v13, v13, v13
	v_fmac_f32_e32 v13, v12, v12
	v_add_f32_e32 v21, v13, v21
	v_lshlrev_b32_e32 v12, 16, v25
	v_and_b32_e32 v13, 0xffff0000, v25
	v_and_b32_e32 v29, 0xffff0000, v31
	v_pk_add_f32 v[12:13], v[12:13], v[28:29]
	s_nop 0
	v_cvt_pk_bf16_f32 v25, v12, v13
	v_and_b32_e32 v13, 0xffff0000, v25
	v_lshlrev_b32_e32 v12, 16, v25
	v_mul_f32_e32 v13, v13, v13
	v_fmac_f32_e32 v13, v12, v12
	v_add_f32_e32 v21, v13, v21
	v_lshl_add_u64 v[12:13], s[12:13], 0, v[16:17]
	v_lshlrev_b64 v[28:29], 11, v[12:13]
	v_xor_b32_e32 v17, 1, v169
	v_lshl_add_u64 v[28:29], s[10:11], 0, v[28:29]
	v_cmp_lt_i32_e32 vcc, v17, v15
	v_lshl_add_u64 v[28:29], v[28:29], 0, s[18:19]
	v_lshl_add_u64 v[28:29], v[28:29], 0, v[146:147]
	v_cndmask_b32_e32 v17, v169, v17, vcc
	v_lshlrev_b32_e32 v17, 2, v17
	flat_store_dwordx4 v[28:29], v[22:25]
	s_nop 1
	v_add_f32_dpp v86, v21, v21 quad_perm:[1,0,3,2] row_mask:0xf bank_mask:0xf
	s_nop 1
	v_add_f32_dpp v86, v86, v86 quad_perm:[2,3,0,1] row_mask:0xf bank_mask:0xf
	s_nop 1
	v_add_f32_dpp v86, v86, v86 row_half_mirror row_mask:0xf bank_mask:0xf
	s_nop 1
	v_add_f32_dpp v86, v86, v86 row_mirror row_mask:0xf bank_mask:0xf
	s_nop 1
	v_add_f32_dpp v86, v86, v86 row_bcast:15 row_mask:0xa bank_mask:0xf
	s_waitcnt lgkmcnt(0)
	v_xor_b32_e32 v22, 2, v169
	v_cmp_lt_i32_e32 vcc, v22, v15
	s_nop 1
	v_cndmask_b32_e32 v22, v169, v22, vcc
	v_lshlrev_b32_e32 v22, 2, v22
	s_waitcnt lgkmcnt(0)
	v_xor_b32_e32 v23, 4, v169
	v_cmp_lt_i32_e32 vcc, v23, v15
	s_nop 1
	v_cndmask_b32_e32 v23, v169, v23, vcc
	v_lshlrev_b32_e32 v23, 2, v23
	s_waitcnt lgkmcnt(0)
	v_xor_b32_e32 v24, 8, v169
	v_cmp_lt_i32_e32 vcc, v24, v15
	s_nop 1
	v_cndmask_b32_e32 v24, v169, v24, vcc
	v_lshlrev_b32_e32 v24, 2, v24
	s_waitcnt lgkmcnt(0)
	v_xor_b32_e32 v25, 16, v169
	v_cmp_lt_i32_e32 vcc, v25, v15
	s_nop 1
	v_cndmask_b32_e32 v15, v169, v25, vcc
	v_lshlrev_b32_e32 v25, 2, v15
	s_and_saveexec_b64 s[18:19], s[98:99]
	s_cbranch_execz .LBB0_778
	v_lshl_add_u64 v[12:13], v[12:13], 4, s[78:79]
	v_lshl_add_u64 v[12:13], s[6:7], 2, v[12:13]
	s_waitcnt lgkmcnt(0)
	v_mov_b32_e32 v15, v86
	flat_store_dword v[12:13], v15
